# K-loop critical path: s_setprio 0 moved from before to after the barrier that closes each MFMA segment (on top of the redundant-wait deletion)
# speedup vs baseline: 1.0079x; 1.0031x over previous
.LBB0_143:
	ds_read_b128 v[168:171], v163
	ds_read_b128 v[172:175], v163 offset:1024
	ds_read_b128 v[176:179], v163 offset:2048
	ds_read_b128 v[180:183], v163 offset:3072
	ds_read_b128 v[184:187], v164
	ds_read_b128 v[188:191], v164 offset:1024
	ds_read_b128 v[192:195], v164 offset:2048
	ds_read_b128 v[196:199], v164 offset:3072
	s_add_u32 s26, s24, 0xfff80080
	s_addc_u32 s27, s25, -1
	s_cmp_eq_u32 s62, 28
	s_cselect_b32 s31, s15, s27
	s_cselect_b32 s30, s23, s26
	s_cselect_b32 s27, s13, s61
	s_cselect_b32 s26, s59, s60
	v_lshl_add_u64 v[154:155], s[24:25], 0, v[144:145]
	s_add_i32 m0, s43, 0xc000
	ds_read_b128 v[200:203], v165
	ds_read_b128 v[204:207], v165 offset:1024
	ds_read_b128 v[208:211], v165 offset:2048
	ds_read_b128 v[212:215], v165 offset:3072
	ds_read_b128 v[216:219], v165 offset:4096
	ds_read_b128 v[220:223], v165 offset:5120
	ds_read_b128 v[224:227], v165 offset:6144
	ds_read_b128 v[228:231], v165 offset:7168
	global_load_lds_dwordx4 v[154:155], off
	v_lshl_add_u64 v[154:155], s[24:25], 0, v[142:143]
	s_add_i32 m0, s43, 0xe000
	s_nop 0
	global_load_lds_dwordx4 v[154:155], off
	s_waitcnt vmcnt(8)
	s_waitcnt lgkmcnt(0)
	s_barrier
	s_setprio 1
	v_mfma_f32_16x16x32_bf16 v[126:129], v[168:171], v[200:203], v[126:129]
	v_mfma_f32_16x16x32_bf16 v[122:125], v[176:179], v[200:203], v[122:125]
	v_mfma_f32_16x16x32_bf16 v[114:117], v[168:171], v[208:211], v[114:117]
	v_mfma_f32_16x16x32_bf16 v[106:109], v[176:179], v[208:211], v[106:109]
	v_mfma_f32_16x16x32_bf16 v[98:101], v[168:171], v[216:219], v[98:101]
	v_mfma_f32_16x16x32_bf16 v[90:93], v[176:179], v[216:219], v[90:93]
	v_mfma_f32_16x16x32_bf16 v[82:85], v[168:171], v[224:227], v[82:85]
	v_mfma_f32_16x16x32_bf16 v[74:77], v[176:179], v[224:227], v[74:77]
	v_mfma_f32_16x16x32_bf16 v[126:129], v[172:175], v[204:207], v[126:129]
	v_mfma_f32_16x16x32_bf16 v[122:125], v[180:183], v[204:207], v[122:125]
	v_mfma_f32_16x16x32_bf16 v[114:117], v[172:175], v[212:215], v[114:117]
	v_mfma_f32_16x16x32_bf16 v[106:109], v[180:183], v[212:215], v[106:109]
	v_mfma_f32_16x16x32_bf16 v[98:101], v[172:175], v[220:223], v[98:101]
	v_mfma_f32_16x16x32_bf16 v[90:93], v[180:183], v[220:223], v[90:93]
	v_mfma_f32_16x16x32_bf16 v[82:85], v[172:175], v[228:231], v[82:85]
	v_mfma_f32_16x16x32_bf16 v[74:77], v[180:183], v[228:231], v[74:77]
	s_setprio 0
	s_setprio 1
	v_mfma_f32_16x16x32_bf16 v[118:121], v[184:187], v[200:203], v[118:121]
	v_mfma_f32_16x16x32_bf16 v[110:113], v[192:195], v[200:203], v[110:113]
	v_mfma_f32_16x16x32_bf16 v[102:105], v[184:187], v[208:211], v[102:105]
	v_mfma_f32_16x16x32_bf16 v[94:97], v[192:195], v[208:211], v[94:97]
	v_mfma_f32_16x16x32_bf16 v[86:89], v[184:187], v[216:219], v[86:89]
	v_mfma_f32_16x16x32_bf16 v[78:81], v[192:195], v[216:219], v[78:81]
	v_mfma_f32_16x16x32_bf16 v[70:73], v[184:187], v[224:227], v[70:73]
	v_mfma_f32_16x16x32_bf16 v[66:69], v[192:195], v[224:227], v[66:69]
	v_mfma_f32_16x16x32_bf16 v[118:121], v[188:191], v[204:207], v[118:121]
	v_mfma_f32_16x16x32_bf16 v[110:113], v[196:199], v[204:207], v[110:113]
	v_mfma_f32_16x16x32_bf16 v[102:105], v[188:191], v[212:215], v[102:105]
	v_mfma_f32_16x16x32_bf16 v[94:97], v[196:199], v[212:215], v[94:97]
	v_mfma_f32_16x16x32_bf16 v[86:89], v[188:191], v[220:223], v[86:89]
	v_mfma_f32_16x16x32_bf16 v[78:81], v[196:199], v[220:223], v[78:81]
	v_mfma_f32_16x16x32_bf16 v[70:73], v[188:191], v[228:231], v[70:73]
	v_mfma_f32_16x16x32_bf16 v[66:69], v[196:199], v[228:231], v[66:69]
	s_barrier
	s_setprio 0
	s_add_i32 s63, s55, s42
	v_lshl_add_u64 v[154:155], s[26:27], 0, v[132:133]
	s_mov_b32 m0, s63
	ds_read_b128 v[200:203], v165 offset:16384
	ds_read_b128 v[204:207], v165 offset:17408
	ds_read_b128 v[208:211], v165 offset:18432
	ds_read_b128 v[212:215], v165 offset:19456
	ds_read_b128 v[216:219], v165 offset:20480
	ds_read_b128 v[220:223], v165 offset:21504
	ds_read_b128 v[224:227], v165 offset:22528
	ds_read_b128 v[228:231], v165 offset:23552
	global_load_lds_dwordx4 v[154:155], off
	s_add_i32 m0, s63, 0x2000
	s_add_u32 s64, s26, 0x80000
	v_lshl_add_u64 v[232:233], s[26:27], 0, v[136:137]
	s_addc_u32 s65, s27, 0
	s_add_i32 s63, s56, s42
	global_load_lds_dwordx4 v[232:233], off
	v_lshl_add_u64 v[234:235], s[64:65], 0, v[132:133]
	s_mov_b32 m0, s63
	v_lshl_add_u64 v[236:237], s[30:31], 0, v[134:135]
	global_load_lds_dwordx4 v[234:235], off
	v_lshl_add_u64 v[234:235], s[64:65], 0, v[136:137]
	s_add_i32 m0, s63, 0x2000
	s_nop 0
	global_load_lds_dwordx4 v[234:235], off
	v_lshl_add_u64 v[234:235], s[30:31], 0, v[130:131]
	s_mov_b32 m0, s43
	s_nop 0
	global_load_lds_dwordx4 v[234:235], off
	s_mov_b32 m0, s44
	s_nop 0
	global_load_lds_dwordx4 v[236:237], off
	s_waitcnt vmcnt(8)
	s_waitcnt lgkmcnt(0)
	s_barrier
	s_setprio 1
	v_mfma_f32_16x16x32_bf16 v[62:65], v[168:171], v[200:203], v[62:65]
	v_mfma_f32_16x16x32_bf16 v[58:61], v[176:179], v[200:203], v[58:61]
	v_mfma_f32_16x16x32_bf16 v[50:53], v[168:171], v[208:211], v[50:53]
	v_mfma_f32_16x16x32_bf16 v[42:45], v[176:179], v[208:211], v[42:45]
	v_mfma_f32_16x16x32_bf16 v[34:37], v[168:171], v[216:219], v[34:37]
	v_mfma_f32_16x16x32_bf16 v[26:29], v[176:179], v[216:219], v[26:29]
	v_mfma_f32_16x16x32_bf16 v[18:21], v[168:171], v[224:227], v[18:21]
	v_mfma_f32_16x16x32_bf16 v[10:13], v[176:179], v[224:227], v[10:13]
	v_mfma_f32_16x16x32_bf16 v[62:65], v[172:175], v[204:207], v[62:65]
	v_mfma_f32_16x16x32_bf16 v[58:61], v[180:183], v[204:207], v[58:61]
	v_mfma_f32_16x16x32_bf16 v[50:53], v[172:175], v[212:215], v[50:53]
	v_mfma_f32_16x16x32_bf16 v[42:45], v[180:183], v[212:215], v[42:45]
	v_mfma_f32_16x16x32_bf16 v[34:37], v[172:175], v[220:223], v[34:37]
	v_mfma_f32_16x16x32_bf16 v[26:29], v[180:183], v[220:223], v[26:29]
	v_mfma_f32_16x16x32_bf16 v[18:21], v[172:175], v[228:231], v[18:21]
	v_mfma_f32_16x16x32_bf16 v[10:13], v[180:183], v[228:231], v[10:13]
	s_setprio 0
	s_setprio 1
	v_mfma_f32_16x16x32_bf16 v[54:57], v[184:187], v[200:203], v[54:57]
	v_mfma_f32_16x16x32_bf16 v[46:49], v[192:195], v[200:203], v[46:49]
	v_mfma_f32_16x16x32_bf16 v[38:41], v[184:187], v[208:211], v[38:41]
	v_mfma_f32_16x16x32_bf16 v[30:33], v[192:195], v[208:211], v[30:33]
	v_mfma_f32_16x16x32_bf16 v[22:25], v[184:187], v[216:219], v[22:25]
	v_mfma_f32_16x16x32_bf16 v[14:17], v[192:195], v[216:219], v[14:17]
	v_mfma_f32_16x16x32_bf16 v[6:9], v[184:187], v[224:227], v[6:9]
	v_mfma_f32_16x16x32_bf16 v[2:5], v[192:195], v[224:227], v[2:5]
	v_mfma_f32_16x16x32_bf16 v[54:57], v[188:191], v[204:207], v[54:57]
	v_mfma_f32_16x16x32_bf16 v[46:49], v[196:199], v[204:207], v[46:49]
	v_mfma_f32_16x16x32_bf16 v[38:41], v[188:191], v[212:215], v[38:41]
	v_mfma_f32_16x16x32_bf16 v[30:33], v[196:199], v[212:215], v[30:33]
	v_mfma_f32_16x16x32_bf16 v[22:25], v[188:191], v[220:223], v[22:25]
	v_mfma_f32_16x16x32_bf16 v[14:17], v[196:199], v[220:223], v[14:17]
	v_mfma_f32_16x16x32_bf16 v[6:9], v[188:191], v[228:231], v[6:9]
	v_mfma_f32_16x16x32_bf16 v[2:5], v[196:199], v[228:231], v[2:5]
	s_barrier
	s_setprio 0
	s_add_i32 s63, 0, 0x18000
	v_add_u32_e32 v138, s63, v159
	s_add_i32 s64, 0, 0x1c000
	ds_read_b128 v[168:171], v138
	ds_read_b128 v[172:175], v138 offset:1024
	ds_read_b128 v[176:179], v138 offset:2048
	ds_read_b128 v[180:183], v138 offset:3072
	v_add_u32_e32 v138, s64, v159
	ds_read_b128 v[184:187], v138
	ds_read_b128 v[188:191], v138 offset:1024
	ds_read_b128 v[192:195], v138 offset:2048
	ds_read_b128 v[196:199], v138 offset:3072
	s_add_u32 s30, s30, 0x80000
	s_addc_u32 s31, s31, 0
	s_mov_b32 m0, s45
	v_lshl_add_u64 v[238:239], s[30:31], 0, v[130:131]
	ds_read_b128 v[200:203], v165 offset:32768
	ds_read_b128 v[204:207], v165 offset:33792
	ds_read_b128 v[208:211], v165 offset:34816
	ds_read_b128 v[212:215], v165 offset:35840
	ds_read_b128 v[216:219], v165 offset:36864
	ds_read_b128 v[220:223], v165 offset:37888
	ds_read_b128 v[224:227], v165 offset:38912
	ds_read_b128 v[228:231], v165 offset:39936
	global_load_lds_dwordx4 v[238:239], off
	v_lshl_add_u64 v[238:239], s[30:31], 0, v[134:135]
	s_mov_b32 m0, s46
	s_nop 0
	global_load_lds_dwordx4 v[238:239], off
	s_waitcnt vmcnt(8)
	s_waitcnt lgkmcnt(0)
	s_barrier
	s_setprio 1
	v_mfma_f32_16x16x32_bf16 v[126:129], v[168:171], v[200:203], v[126:129]
	v_mfma_f32_16x16x32_bf16 v[122:125], v[176:179], v[200:203], v[122:125]
	v_mfma_f32_16x16x32_bf16 v[114:117], v[168:171], v[208:211], v[114:117]
	v_mfma_f32_16x16x32_bf16 v[106:109], v[176:179], v[208:211], v[106:109]
	v_mfma_f32_16x16x32_bf16 v[98:101], v[168:171], v[216:219], v[98:101]
	v_mfma_f32_16x16x32_bf16 v[90:93], v[176:179], v[216:219], v[90:93]
	v_mfma_f32_16x16x32_bf16 v[82:85], v[168:171], v[224:227], v[82:85]
	v_mfma_f32_16x16x32_bf16 v[74:77], v[176:179], v[224:227], v[74:77]
	v_mfma_f32_16x16x32_bf16 v[126:129], v[172:175], v[204:207], v[126:129]
	v_mfma_f32_16x16x32_bf16 v[122:125], v[180:183], v[204:207], v[122:125]
	v_mfma_f32_16x16x32_bf16 v[114:117], v[172:175], v[212:215], v[114:117]
	v_mfma_f32_16x16x32_bf16 v[106:109], v[180:183], v[212:215], v[106:109]
	v_mfma_f32_16x16x32_bf16 v[98:101], v[172:175], v[220:223], v[98:101]
	v_mfma_f32_16x16x32_bf16 v[90:93], v[180:183], v[220:223], v[90:93]
	v_mfma_f32_16x16x32_bf16 v[82:85], v[172:175], v[228:231], v[82:85]
	v_mfma_f32_16x16x32_bf16 v[74:77], v[180:183], v[228:231], v[74:77]
	s_setprio 0
	s_setprio 1
	v_mfma_f32_16x16x32_bf16 v[118:121], v[184:187], v[200:203], v[118:121]
	v_mfma_f32_16x16x32_bf16 v[110:113], v[192:195], v[200:203], v[110:113]
	v_mfma_f32_16x16x32_bf16 v[102:105], v[184:187], v[208:211], v[102:105]
	v_mfma_f32_16x16x32_bf16 v[94:97], v[192:195], v[208:211], v[94:97]
	v_mfma_f32_16x16x32_bf16 v[86:89], v[184:187], v[216:219], v[86:89]
	v_mfma_f32_16x16x32_bf16 v[78:81], v[192:195], v[216:219], v[78:81]
	v_mfma_f32_16x16x32_bf16 v[70:73], v[184:187], v[224:227], v[70:73]
	v_mfma_f32_16x16x32_bf16 v[66:69], v[192:195], v[224:227], v[66:69]
	v_mfma_f32_16x16x32_bf16 v[118:121], v[188:191], v[204:207], v[118:121]
	v_mfma_f32_16x16x32_bf16 v[110:113], v[196:199], v[204:207], v[110:113]
	v_mfma_f32_16x16x32_bf16 v[102:105], v[188:191], v[212:215], v[102:105]
	v_mfma_f32_16x16x32_bf16 v[94:97], v[196:199], v[212:215], v[94:97]
	v_mfma_f32_16x16x32_bf16 v[86:89], v[188:191], v[220:223], v[86:89]
	v_mfma_f32_16x16x32_bf16 v[78:81], v[196:199], v[220:223], v[78:81]
	v_mfma_f32_16x16x32_bf16 v[70:73], v[188:191], v[228:231], v[70:73]
	v_mfma_f32_16x16x32_bf16 v[66:69], v[196:199], v[228:231], v[66:69]
	s_barrier
	s_setprio 0
	s_add_i32 s30, s63, s42
	v_lshl_add_u64 v[154:155], v[154:155], 0, s[8:9]
	s_mov_b32 m0, s30
	ds_read_b128 v[200:203], v165 offset:49152
	ds_read_b128 v[204:207], v165 offset:50176
	ds_read_b128 v[208:211], v165 offset:51200
	ds_read_b128 v[212:215], v165 offset:52224
	ds_read_b128 v[216:219], v165 offset:53248
	ds_read_b128 v[220:223], v165 offset:54272
	ds_read_b128 v[224:227], v165 offset:55296
	ds_read_b128 v[228:231], v165 offset:56320
	global_load_lds_dwordx4 v[154:155], off
	s_add_i32 m0, s30, 0x2000
	s_add_u32 s26, s26, 0x80080
	v_lshl_add_u64 v[154:155], v[232:233], 0, s[8:9]
	s_addc_u32 s27, s27, 0
	s_add_i32 s30, s64, s42
	global_load_lds_dwordx4 v[154:155], off
	v_lshl_add_u64 v[154:155], s[26:27], 0, v[132:133]
	s_mov_b32 m0, s30
	s_nop 0
	global_load_lds_dwordx4 v[154:155], off
	v_lshl_add_u64 v[154:155], s[26:27], 0, v[136:137]
	s_add_i32 m0, s30, 0x2000
	s_nop 0
	global_load_lds_dwordx4 v[154:155], off
	v_lshl_add_u64 v[154:155], v[234:235], 0, s[8:9]
	s_mov_b32 m0, s51
	s_nop 0
	global_load_lds_dwordx4 v[154:155], off
	v_lshl_add_u64 v[154:155], v[236:237], 0, s[8:9]
	s_mov_b32 m0, s53
	s_nop 0
	global_load_lds_dwordx4 v[154:155], off
	s_waitcnt vmcnt(8)
	s_waitcnt lgkmcnt(0)
	s_barrier
	s_setprio 1
	v_mfma_f32_16x16x32_bf16 v[62:65], v[168:171], v[200:203], v[62:65]
	v_mfma_f32_16x16x32_bf16 v[58:61], v[176:179], v[200:203], v[58:61]
	v_mfma_f32_16x16x32_bf16 v[50:53], v[168:171], v[208:211], v[50:53]
	v_mfma_f32_16x16x32_bf16 v[42:45], v[176:179], v[208:211], v[42:45]
	v_mfma_f32_16x16x32_bf16 v[34:37], v[168:171], v[216:219], v[34:37]
	v_mfma_f32_16x16x32_bf16 v[26:29], v[176:179], v[216:219], v[26:29]
	v_mfma_f32_16x16x32_bf16 v[18:21], v[168:171], v[224:227], v[18:21]
	v_mfma_f32_16x16x32_bf16 v[10:13], v[176:179], v[224:227], v[10:13]
	v_mfma_f32_16x16x32_bf16 v[62:65], v[172:175], v[204:207], v[62:65]
	v_mfma_f32_16x16x32_bf16 v[58:61], v[180:183], v[204:207], v[58:61]
	v_mfma_f32_16x16x32_bf16 v[50:53], v[172:175], v[212:215], v[50:53]
	v_mfma_f32_16x16x32_bf16 v[42:45], v[180:183], v[212:215], v[42:45]
	v_mfma_f32_16x16x32_bf16 v[34:37], v[172:175], v[220:223], v[34:37]
	v_mfma_f32_16x16x32_bf16 v[26:29], v[180:183], v[220:223], v[26:29]
	v_mfma_f32_16x16x32_bf16 v[18:21], v[172:175], v[228:231], v[18:21]
	v_mfma_f32_16x16x32_bf16 v[10:13], v[180:183], v[228:231], v[10:13]
	s_setprio 0
	s_setprio 1
	v_mfma_f32_16x16x32_bf16 v[54:57], v[184:187], v[200:203], v[54:57]
	v_mfma_f32_16x16x32_bf16 v[46:49], v[192:195], v[200:203], v[46:49]
	v_mfma_f32_16x16x32_bf16 v[38:41], v[184:187], v[208:211], v[38:41]
	v_mfma_f32_16x16x32_bf16 v[30:33], v[192:195], v[208:211], v[30:33]
	v_mfma_f32_16x16x32_bf16 v[22:25], v[184:187], v[216:219], v[22:25]
	v_mfma_f32_16x16x32_bf16 v[14:17], v[192:195], v[216:219], v[14:17]
	v_mfma_f32_16x16x32_bf16 v[6:9], v[184:187], v[224:227], v[6:9]
	v_mfma_f32_16x16x32_bf16 v[2:5], v[192:195], v[224:227], v[2:5]
	v_mfma_f32_16x16x32_bf16 v[54:57], v[188:191], v[204:207], v[54:57]
	v_mfma_f32_16x16x32_bf16 v[46:49], v[196:199], v[204:207], v[46:49]
	v_mfma_f32_16x16x32_bf16 v[38:41], v[188:191], v[212:215], v[38:41]
	v_mfma_f32_16x16x32_bf16 v[30:33], v[196:199], v[212:215], v[30:33]
	v_mfma_f32_16x16x32_bf16 v[22:25], v[188:191], v[220:223], v[22:25]
	v_mfma_f32_16x16x32_bf16 v[14:17], v[196:199], v[220:223], v[14:17]
	v_mfma_f32_16x16x32_bf16 v[6:9], v[188:191], v[228:231], v[6:9]
	v_mfma_f32_16x16x32_bf16 v[2:5], v[196:199], v[228:231], v[2:5]
	s_barrier
	s_setprio 0
	s_add_i32 s62, s62, 2
	s_add_u32 s60, s60, 0x100
	s_addc_u32 s61, s61, 0
	s_add_u32 s24, s24, 0x100
	s_addc_u32 s25, s25, 0
	s_cmp_gt_u32 s62, 29
	s_cbranch_scc0 .LBB0_143
	s_and_b64 vcc, exec, s[10:11]
	s_cbranch_vccz .LBB0_146
	s_barrier

.LBB0_268:
	ds_read_b128 v[150:153], v139
	ds_read_b128 v[154:157], v139 offset:1024
	ds_read_b128 v[158:161], v139 offset:2048
	ds_read_b128 v[162:165], v139 offset:3072
	ds_read_b128 v[166:169], v146
	ds_read_b128 v[170:173], v146 offset:1024
	ds_read_b128 v[174:177], v146 offset:2048
	ds_read_b128 v[178:181], v146 offset:3072
	s_add_u32 s18, s14, s16
	s_addc_u32 s19, s15, s17
	s_add_u32 s18, s18, 0x28300100
	s_addc_u32 s19, s19, 0
	s_add_u32 s55, s41, s16
	s_addc_u32 s56, s42, s17
	s_cmpk_eq_i32 s16, 0x300
	s_cselect_b32 s23, s11, s19
	s_cselect_b32 s22, s10, s18
	s_cselect_b32 s19, s9, s56
	s_cselect_b32 s18, s8, s55
	s_mov_b32 m0, s44
	v_lshl_add_u64 v[214:215], v[142:143], 0, s[16:17]
	ds_read_b128 v[182:185], v147
	ds_read_b128 v[186:189], v147 offset:1024
	ds_read_b128 v[190:193], v147 offset:2048
	ds_read_b128 v[194:197], v147 offset:3072
	ds_read_b128 v[198:201], v147 offset:4096
	ds_read_b128 v[202:205], v147 offset:5120
	ds_read_b128 v[206:209], v147 offset:6144
	ds_read_b128 v[210:213], v147 offset:7168
	global_load_lds_dwordx4 v[214:215], off
	v_lshl_add_u64 v[214:215], v[140:141], 0, s[16:17]
	s_mov_b32 m0, s45
	s_nop 0
	global_load_lds_dwordx4 v[214:215], off
	s_waitcnt vmcnt(8)
	s_waitcnt lgkmcnt(0)
	s_barrier
	s_setprio 1
	v_mfma_f32_16x16x32_bf16 v[126:129], v[150:153], v[182:185], v[126:129]
	v_mfma_f32_16x16x32_bf16 v[122:125], v[158:161], v[182:185], v[122:125]
	v_mfma_f32_16x16x32_bf16 v[118:121], v[150:153], v[190:193], v[118:121]
	v_mfma_f32_16x16x32_bf16 v[110:113], v[158:161], v[190:193], v[110:113]
	v_mfma_f32_16x16x32_bf16 v[102:105], v[150:153], v[198:201], v[102:105]
	v_mfma_f32_16x16x32_bf16 v[94:97], v[158:161], v[198:201], v[94:97]
	v_mfma_f32_16x16x32_bf16 v[86:89], v[150:153], v[206:209], v[86:89]
	v_mfma_f32_16x16x32_bf16 v[78:81], v[158:161], v[206:209], v[78:81]
	v_mfma_f32_16x16x32_bf16 v[126:129], v[154:157], v[186:189], v[126:129]
	v_mfma_f32_16x16x32_bf16 v[122:125], v[162:165], v[186:189], v[122:125]
	v_mfma_f32_16x16x32_bf16 v[118:121], v[154:157], v[194:197], v[118:121]
	v_mfma_f32_16x16x32_bf16 v[110:113], v[162:165], v[194:197], v[110:113]
	v_mfma_f32_16x16x32_bf16 v[102:105], v[154:157], v[202:205], v[102:105]
	v_mfma_f32_16x16x32_bf16 v[94:97], v[162:165], v[202:205], v[94:97]
	v_mfma_f32_16x16x32_bf16 v[86:89], v[154:157], v[210:213], v[86:89]
	v_mfma_f32_16x16x32_bf16 v[78:81], v[162:165], v[210:213], v[78:81]
	s_setprio 0
	s_setprio 1
	v_mfma_f32_16x16x32_bf16 v[114:117], v[166:169], v[182:185], v[114:117]
	v_mfma_f32_16x16x32_bf16 v[106:109], v[174:177], v[182:185], v[106:109]
	v_mfma_f32_16x16x32_bf16 v[98:101], v[166:169], v[190:193], v[98:101]
	v_mfma_f32_16x16x32_bf16 v[90:93], v[174:177], v[190:193], v[90:93]
	v_mfma_f32_16x16x32_bf16 v[82:85], v[166:169], v[198:201], v[82:85]
	v_mfma_f32_16x16x32_bf16 v[74:77], v[174:177], v[198:201], v[74:77]
	v_mfma_f32_16x16x32_bf16 v[70:73], v[166:169], v[206:209], v[70:73]
	v_mfma_f32_16x16x32_bf16 v[66:69], v[174:177], v[206:209], v[66:69]
	v_mfma_f32_16x16x32_bf16 v[114:117], v[170:173], v[186:189], v[114:117]
	v_mfma_f32_16x16x32_bf16 v[106:109], v[178:181], v[186:189], v[106:109]
	v_mfma_f32_16x16x32_bf16 v[98:101], v[170:173], v[194:197], v[98:101]
	v_mfma_f32_16x16x32_bf16 v[90:93], v[178:181], v[194:197], v[90:93]
	v_mfma_f32_16x16x32_bf16 v[82:85], v[170:173], v[202:205], v[82:85]
	v_mfma_f32_16x16x32_bf16 v[74:77], v[178:181], v[202:205], v[74:77]
	v_mfma_f32_16x16x32_bf16 v[70:73], v[170:173], v[210:213], v[70:73]
	v_mfma_f32_16x16x32_bf16 v[66:69], v[178:181], v[210:213], v[66:69]
	s_barrier
	s_setprio 0
	s_mov_b32 m0, s46
	v_lshl_add_u64 v[214:215], s[18:19], 0, v[132:133]
	s_add_u32 s56, s18, 0x20000
	ds_read_b128 v[182:185], v147 offset:16384
	ds_read_b128 v[186:189], v147 offset:17408
	ds_read_b128 v[190:193], v147 offset:18432
	ds_read_b128 v[194:197], v147 offset:19456
	ds_read_b128 v[198:201], v147 offset:20480
	ds_read_b128 v[202:205], v147 offset:21504
	ds_read_b128 v[206:209], v147 offset:22528
	ds_read_b128 v[210:213], v147 offset:23552
	global_load_lds_dwordx4 v[214:215], off
	v_lshl_add_u64 v[216:217], s[18:19], 0, v[136:137]
	s_mov_b32 m0, s47
	s_addc_u32 s57, s19, 0
	global_load_lds_dwordx4 v[216:217], off
	v_lshl_add_u64 v[218:219], s[56:57], 0, v[132:133]
	s_mov_b32 m0, s48
	v_lshl_add_u64 v[220:221], s[22:23], 0, v[134:135]
	global_load_lds_dwordx4 v[218:219], off
	v_lshl_add_u64 v[218:219], s[56:57], 0, v[136:137]
	s_mov_b32 m0, s49
	s_nop 0
	global_load_lds_dwordx4 v[218:219], off
	v_lshl_add_u64 v[218:219], s[22:23], 0, v[130:131]
	s_mov_b32 m0, s7
	s_nop 0
	global_load_lds_dwordx4 v[218:219], off
	s_mov_b32 m0, s36
	s_nop 0
	global_load_lds_dwordx4 v[220:221], off
	s_waitcnt vmcnt(8)
	s_waitcnt lgkmcnt(0)
	s_barrier
	s_setprio 1
	v_mfma_f32_16x16x32_bf16 v[62:65], v[150:153], v[182:185], v[62:65]
	v_mfma_f32_16x16x32_bf16 v[58:61], v[158:161], v[182:185], v[58:61]
	v_mfma_f32_16x16x32_bf16 v[54:57], v[150:153], v[190:193], v[54:57]
	v_mfma_f32_16x16x32_bf16 v[46:49], v[158:161], v[190:193], v[46:49]
	v_mfma_f32_16x16x32_bf16 v[38:41], v[150:153], v[198:201], v[38:41]
	v_mfma_f32_16x16x32_bf16 v[30:33], v[158:161], v[198:201], v[30:33]
	v_mfma_f32_16x16x32_bf16 v[22:25], v[150:153], v[206:209], v[22:25]
	v_mfma_f32_16x16x32_bf16 v[14:17], v[158:161], v[206:209], v[14:17]
	v_mfma_f32_16x16x32_bf16 v[62:65], v[154:157], v[186:189], v[62:65]
	v_mfma_f32_16x16x32_bf16 v[58:61], v[162:165], v[186:189], v[58:61]
	v_mfma_f32_16x16x32_bf16 v[54:57], v[154:157], v[194:197], v[54:57]
	v_mfma_f32_16x16x32_bf16 v[46:49], v[162:165], v[194:197], v[46:49]
	v_mfma_f32_16x16x32_bf16 v[38:41], v[154:157], v[202:205], v[38:41]
	v_mfma_f32_16x16x32_bf16 v[30:33], v[162:165], v[202:205], v[30:33]
	v_mfma_f32_16x16x32_bf16 v[22:25], v[154:157], v[210:213], v[22:25]
	v_mfma_f32_16x16x32_bf16 v[14:17], v[162:165], v[210:213], v[14:17]
	s_setprio 0
	s_setprio 1
	v_mfma_f32_16x16x32_bf16 v[50:53], v[166:169], v[182:185], v[50:53]
	v_mfma_f32_16x16x32_bf16 v[42:45], v[174:177], v[182:185], v[42:45]
	v_mfma_f32_16x16x32_bf16 v[34:37], v[166:169], v[190:193], v[34:37]
	v_mfma_f32_16x16x32_bf16 v[26:29], v[174:177], v[190:193], v[26:29]
	v_mfma_f32_16x16x32_bf16 v[18:21], v[166:169], v[198:201], v[18:21]
	v_mfma_f32_16x16x32_bf16 v[10:13], v[174:177], v[198:201], v[10:13]
	v_mfma_f32_16x16x32_bf16 v[6:9], v[166:169], v[206:209], v[6:9]
	v_mfma_f32_16x16x32_bf16 v[2:5], v[174:177], v[206:209], v[2:5]
	v_mfma_f32_16x16x32_bf16 v[50:53], v[170:173], v[186:189], v[50:53]
	v_mfma_f32_16x16x32_bf16 v[42:45], v[178:181], v[186:189], v[42:45]
	v_mfma_f32_16x16x32_bf16 v[34:37], v[170:173], v[194:197], v[34:37]
	v_mfma_f32_16x16x32_bf16 v[26:29], v[178:181], v[194:197], v[26:29]
	v_mfma_f32_16x16x32_bf16 v[18:21], v[170:173], v[202:205], v[18:21]
	v_mfma_f32_16x16x32_bf16 v[10:13], v[178:181], v[202:205], v[10:13]
	v_mfma_f32_16x16x32_bf16 v[6:9], v[170:173], v[210:213], v[6:9]
	v_mfma_f32_16x16x32_bf16 v[2:5], v[178:181], v[210:213], v[2:5]
	s_barrier
	s_setprio 0
	ds_read_b128 v[150:153], v148
	ds_read_b128 v[154:157], v148 offset:1024
	ds_read_b128 v[158:161], v148 offset:2048
	ds_read_b128 v[162:165], v148 offset:3072
	ds_read_b128 v[166:169], v149
	ds_read_b128 v[170:173], v149 offset:1024
	ds_read_b128 v[174:177], v149 offset:2048
	ds_read_b128 v[178:181], v149 offset:3072
	s_add_u32 s22, s22, 0x20000
	s_addc_u32 s23, s23, 0
	s_mov_b32 m0, s37
	v_lshl_add_u64 v[222:223], s[22:23], 0, v[130:131]
	ds_read_b128 v[182:185], v147 offset:32768
	ds_read_b128 v[186:189], v147 offset:33792
	ds_read_b128 v[190:193], v147 offset:34816
	ds_read_b128 v[194:197], v147 offset:35840
	ds_read_b128 v[198:201], v147 offset:36864
	ds_read_b128 v[202:205], v147 offset:37888
	ds_read_b128 v[206:209], v147 offset:38912
	ds_read_b128 v[210:213], v147 offset:39936
	global_load_lds_dwordx4 v[222:223], off
	v_lshl_add_u64 v[222:223], s[22:23], 0, v[134:135]
	s_mov_b32 m0, s38
	s_nop 0
	global_load_lds_dwordx4 v[222:223], off
	s_waitcnt vmcnt(8)
	s_waitcnt lgkmcnt(0)
	s_barrier
	s_setprio 1
	v_mfma_f32_16x16x32_bf16 v[126:129], v[150:153], v[182:185], v[126:129]
	v_mfma_f32_16x16x32_bf16 v[122:125], v[158:161], v[182:185], v[122:125]
	v_mfma_f32_16x16x32_bf16 v[118:121], v[150:153], v[190:193], v[118:121]
	v_mfma_f32_16x16x32_bf16 v[110:113], v[158:161], v[190:193], v[110:113]
	v_mfma_f32_16x16x32_bf16 v[102:105], v[150:153], v[198:201], v[102:105]
	v_mfma_f32_16x16x32_bf16 v[94:97], v[158:161], v[198:201], v[94:97]
	v_mfma_f32_16x16x32_bf16 v[86:89], v[150:153], v[206:209], v[86:89]
	v_mfma_f32_16x16x32_bf16 v[78:81], v[158:161], v[206:209], v[78:81]
	v_mfma_f32_16x16x32_bf16 v[126:129], v[154:157], v[186:189], v[126:129]
	v_mfma_f32_16x16x32_bf16 v[122:125], v[162:165], v[186:189], v[122:125]
	v_mfma_f32_16x16x32_bf16 v[118:121], v[154:157], v[194:197], v[118:121]
	v_mfma_f32_16x16x32_bf16 v[110:113], v[162:165], v[194:197], v[110:113]
	v_mfma_f32_16x16x32_bf16 v[102:105], v[154:157], v[202:205], v[102:105]
	v_mfma_f32_16x16x32_bf16 v[94:97], v[162:165], v[202:205], v[94:97]
	v_mfma_f32_16x16x32_bf16 v[86:89], v[154:157], v[210:213], v[86:89]
	v_mfma_f32_16x16x32_bf16 v[78:81], v[162:165], v[210:213], v[78:81]
	s_setprio 0
	s_setprio 1
	v_mfma_f32_16x16x32_bf16 v[114:117], v[166:169], v[182:185], v[114:117]
	v_mfma_f32_16x16x32_bf16 v[106:109], v[174:177], v[182:185], v[106:109]
	v_mfma_f32_16x16x32_bf16 v[98:101], v[166:169], v[190:193], v[98:101]
	v_mfma_f32_16x16x32_bf16 v[90:93], v[174:177], v[190:193], v[90:93]
	v_mfma_f32_16x16x32_bf16 v[82:85], v[166:169], v[198:201], v[82:85]
	v_mfma_f32_16x16x32_bf16 v[74:77], v[174:177], v[198:201], v[74:77]
	v_mfma_f32_16x16x32_bf16 v[70:73], v[166:169], v[206:209], v[70:73]
	v_mfma_f32_16x16x32_bf16 v[66:69], v[174:177], v[206:209], v[66:69]
	v_mfma_f32_16x16x32_bf16 v[114:117], v[170:173], v[186:189], v[114:117]
	v_mfma_f32_16x16x32_bf16 v[106:109], v[178:181], v[186:189], v[106:109]
	v_mfma_f32_16x16x32_bf16 v[98:101], v[170:173], v[194:197], v[98:101]
	v_mfma_f32_16x16x32_bf16 v[90:93], v[178:181], v[194:197], v[90:93]
	v_mfma_f32_16x16x32_bf16 v[82:85], v[170:173], v[202:205], v[82:85]
	v_mfma_f32_16x16x32_bf16 v[74:77], v[178:181], v[202:205], v[74:77]
	v_mfma_f32_16x16x32_bf16 v[70:73], v[170:173], v[210:213], v[70:73]
	v_mfma_f32_16x16x32_bf16 v[66:69], v[178:181], v[210:213], v[66:69]
	s_barrier
	s_setprio 0
	s_mov_b32 m0, s50
	v_lshl_add_u64 v[214:215], v[214:215], 0, s[12:13]
	s_add_u32 s18, s18, 0x20080
	ds_read_b128 v[182:185], v147 offset:49152
	ds_read_b128 v[186:189], v147 offset:50176
	ds_read_b128 v[190:193], v147 offset:51200
	ds_read_b128 v[194:197], v147 offset:52224
	ds_read_b128 v[198:201], v147 offset:53248
	ds_read_b128 v[202:205], v147 offset:54272
	ds_read_b128 v[206:209], v147 offset:55296
	ds_read_b128 v[210:213], v147 offset:56320
	global_load_lds_dwordx4 v[214:215], off
	v_lshl_add_u64 v[214:215], v[216:217], 0, s[12:13]
	s_mov_b32 m0, s51
	s_addc_u32 s19, s19, 0
	global_load_lds_dwordx4 v[214:215], off
	v_lshl_add_u64 v[214:215], s[18:19], 0, v[132:133]
	s_mov_b32 m0, s53
	s_nop 0
	global_load_lds_dwordx4 v[214:215], off
	v_lshl_add_u64 v[214:215], s[18:19], 0, v[136:137]
	s_mov_b32 m0, s54
	s_nop 0
	global_load_lds_dwordx4 v[214:215], off
	v_lshl_add_u64 v[214:215], v[218:219], 0, s[12:13]
	s_mov_b32 m0, s39
	s_nop 0
	global_load_lds_dwordx4 v[214:215], off
	v_lshl_add_u64 v[214:215], v[220:221], 0, s[12:13]
	s_mov_b32 m0, s40
	s_nop 0
	global_load_lds_dwordx4 v[214:215], off
	s_waitcnt vmcnt(8)
	s_waitcnt lgkmcnt(0)
	s_barrier
	s_setprio 1
	v_mfma_f32_16x16x32_bf16 v[62:65], v[150:153], v[182:185], v[62:65]
	v_mfma_f32_16x16x32_bf16 v[58:61], v[158:161], v[182:185], v[58:61]
	v_mfma_f32_16x16x32_bf16 v[54:57], v[150:153], v[190:193], v[54:57]
	v_mfma_f32_16x16x32_bf16 v[46:49], v[158:161], v[190:193], v[46:49]
	v_mfma_f32_16x16x32_bf16 v[38:41], v[150:153], v[198:201], v[38:41]
	v_mfma_f32_16x16x32_bf16 v[30:33], v[158:161], v[198:201], v[30:33]
	v_mfma_f32_16x16x32_bf16 v[22:25], v[150:153], v[206:209], v[22:25]
	v_mfma_f32_16x16x32_bf16 v[14:17], v[158:161], v[206:209], v[14:17]
	v_mfma_f32_16x16x32_bf16 v[62:65], v[154:157], v[186:189], v[62:65]
	v_mfma_f32_16x16x32_bf16 v[58:61], v[162:165], v[186:189], v[58:61]
	v_mfma_f32_16x16x32_bf16 v[54:57], v[154:157], v[194:197], v[54:57]
	v_mfma_f32_16x16x32_bf16 v[46:49], v[162:165], v[194:197], v[46:49]
	v_mfma_f32_16x16x32_bf16 v[38:41], v[154:157], v[202:205], v[38:41]
	v_mfma_f32_16x16x32_bf16 v[30:33], v[162:165], v[202:205], v[30:33]
	v_mfma_f32_16x16x32_bf16 v[22:25], v[154:157], v[210:213], v[22:25]
	v_mfma_f32_16x16x32_bf16 v[14:17], v[162:165], v[210:213], v[14:17]
	s_setprio 0
	s_setprio 1
	v_mfma_f32_16x16x32_bf16 v[50:53], v[166:169], v[182:185], v[50:53]
	v_mfma_f32_16x16x32_bf16 v[42:45], v[174:177], v[182:185], v[42:45]
	v_mfma_f32_16x16x32_bf16 v[34:37], v[166:169], v[190:193], v[34:37]
	v_mfma_f32_16x16x32_bf16 v[26:29], v[174:177], v[190:193], v[26:29]
	v_mfma_f32_16x16x32_bf16 v[18:21], v[166:169], v[198:201], v[18:21]
	v_mfma_f32_16x16x32_bf16 v[10:13], v[174:177], v[198:201], v[10:13]
	v_mfma_f32_16x16x32_bf16 v[6:9], v[166:169], v[206:209], v[6:9]
	v_mfma_f32_16x16x32_bf16 v[2:5], v[174:177], v[206:209], v[2:5]
	v_mfma_f32_16x16x32_bf16 v[50:53], v[170:173], v[186:189], v[50:53]
	v_mfma_f32_16x16x32_bf16 v[42:45], v[178:181], v[186:189], v[42:45]
	v_mfma_f32_16x16x32_bf16 v[34:37], v[170:173], v[194:197], v[34:37]
	v_mfma_f32_16x16x32_bf16 v[26:29], v[178:181], v[194:197], v[26:29]
	v_mfma_f32_16x16x32_bf16 v[18:21], v[170:173], v[202:205], v[18:21]
	v_mfma_f32_16x16x32_bf16 v[10:13], v[178:181], v[202:205], v[10:13]
	v_mfma_f32_16x16x32_bf16 v[6:9], v[170:173], v[210:213], v[6:9]
	v_mfma_f32_16x16x32_bf16 v[2:5], v[178:181], v[210:213], v[2:5]
	s_barrier
	s_setprio 0
	s_add_i32 s43, s43, 2
	s_add_u32 s16, s16, 0x100
	s_addc_u32 s17, s17, 0
	s_cmp_gt_u32 s43, 5
	s_cbranch_scc0 .LBB0_268
	s_cmpk_lt_u32 s33, 0x100
	s_cbranch_scc0 .LBB0_271
	s_barrier

.LBB0_274:
	ds_read_b128 v[150:153], v144
	ds_read_b128 v[154:157], v144 offset:1024
	ds_read_b128 v[158:161], v144 offset:2048
	ds_read_b128 v[162:165], v144 offset:3072
	ds_read_b128 v[166:169], v145
	ds_read_b128 v[170:173], v145 offset:1024
	ds_read_b128 v[174:177], v145 offset:2048
	ds_read_b128 v[178:181], v145 offset:3072
	s_add_u32 s18, s14, s16
	s_addc_u32 s19, s15, s17
	s_add_u32 s18, s18, 0xf900100
	s_addc_u32 s19, s19, 0
	s_add_u32 s49, s40, s16
	s_addc_u32 s50, s41, s17
	s_cmpk_eq_i32 s16, 0x300
	s_cselect_b32 s23, s11, s19
	s_cselect_b32 s22, s10, s18
	s_cselect_b32 s19, s9, s50
	s_cselect_b32 s18, s8, s49
	s_mov_b32 m0, s43
	v_lshl_add_u64 v[214:215], v[140:141], 0, s[16:17]
	ds_read_b128 v[182:185], v146
	ds_read_b128 v[186:189], v146 offset:1024
	ds_read_b128 v[190:193], v146 offset:2048
	ds_read_b128 v[194:197], v146 offset:3072
	ds_read_b128 v[198:201], v146 offset:4096
	ds_read_b128 v[202:205], v146 offset:5120
	ds_read_b128 v[206:209], v146 offset:6144
	ds_read_b128 v[210:213], v146 offset:7168
	global_load_lds_dwordx4 v[214:215], off
	v_lshl_add_u64 v[214:215], v[138:139], 0, s[16:17]
	s_mov_b32 m0, s44
	s_nop 0
	global_load_lds_dwordx4 v[214:215], off
	s_waitcnt vmcnt(8)
	s_waitcnt lgkmcnt(0)
	s_barrier
	s_setprio 1
	v_mfma_f32_16x16x32_bf16 v[126:129], v[150:153], v[182:185], v[126:129]
	v_mfma_f32_16x16x32_bf16 v[122:125], v[158:161], v[182:185], v[122:125]
	v_mfma_f32_16x16x32_bf16 v[118:121], v[150:153], v[190:193], v[118:121]
	v_mfma_f32_16x16x32_bf16 v[110:113], v[158:161], v[190:193], v[110:113]
	v_mfma_f32_16x16x32_bf16 v[102:105], v[150:153], v[198:201], v[102:105]
	v_mfma_f32_16x16x32_bf16 v[94:97], v[158:161], v[198:201], v[94:97]
	v_mfma_f32_16x16x32_bf16 v[86:89], v[150:153], v[206:209], v[86:89]
	v_mfma_f32_16x16x32_bf16 v[78:81], v[158:161], v[206:209], v[78:81]
	v_mfma_f32_16x16x32_bf16 v[126:129], v[154:157], v[186:189], v[126:129]
	v_mfma_f32_16x16x32_bf16 v[122:125], v[162:165], v[186:189], v[122:125]
	v_mfma_f32_16x16x32_bf16 v[118:121], v[154:157], v[194:197], v[118:121]
	v_mfma_f32_16x16x32_bf16 v[110:113], v[162:165], v[194:197], v[110:113]
	v_mfma_f32_16x16x32_bf16 v[102:105], v[154:157], v[202:205], v[102:105]
	v_mfma_f32_16x16x32_bf16 v[94:97], v[162:165], v[202:205], v[94:97]
	v_mfma_f32_16x16x32_bf16 v[86:89], v[154:157], v[210:213], v[86:89]
	v_mfma_f32_16x16x32_bf16 v[78:81], v[162:165], v[210:213], v[78:81]
	s_setprio 0
	s_setprio 1
	v_mfma_f32_16x16x32_bf16 v[114:117], v[166:169], v[182:185], v[114:117]
	v_mfma_f32_16x16x32_bf16 v[106:109], v[174:177], v[182:185], v[106:109]
	v_mfma_f32_16x16x32_bf16 v[98:101], v[166:169], v[190:193], v[98:101]
	v_mfma_f32_16x16x32_bf16 v[90:93], v[174:177], v[190:193], v[90:93]
	v_mfma_f32_16x16x32_bf16 v[82:85], v[166:169], v[198:201], v[82:85]
	v_mfma_f32_16x16x32_bf16 v[74:77], v[174:177], v[198:201], v[74:77]
	v_mfma_f32_16x16x32_bf16 v[70:73], v[166:169], v[206:209], v[70:73]
	v_mfma_f32_16x16x32_bf16 v[66:69], v[174:177], v[206:209], v[66:69]
	v_mfma_f32_16x16x32_bf16 v[114:117], v[170:173], v[186:189], v[114:117]
	v_mfma_f32_16x16x32_bf16 v[106:109], v[178:181], v[186:189], v[106:109]
	v_mfma_f32_16x16x32_bf16 v[98:101], v[170:173], v[194:197], v[98:101]
	v_mfma_f32_16x16x32_bf16 v[90:93], v[178:181], v[194:197], v[90:93]
	v_mfma_f32_16x16x32_bf16 v[82:85], v[170:173], v[202:205], v[82:85]
	v_mfma_f32_16x16x32_bf16 v[74:77], v[178:181], v[202:205], v[74:77]
	v_mfma_f32_16x16x32_bf16 v[70:73], v[170:173], v[210:213], v[70:73]
	v_mfma_f32_16x16x32_bf16 v[66:69], v[178:181], v[210:213], v[66:69]
	s_barrier
	s_setprio 0
	s_mov_b32 m0, s25
	v_lshl_add_u64 v[214:215], s[18:19], 0, v[130:131]
	s_add_u32 s50, s18, 0x20000
	ds_read_b128 v[182:185], v146 offset:16384
	ds_read_b128 v[186:189], v146 offset:17408
	ds_read_b128 v[190:193], v146 offset:18432
	ds_read_b128 v[194:197], v146 offset:19456
	ds_read_b128 v[198:201], v146 offset:20480
	ds_read_b128 v[202:205], v146 offset:21504
	ds_read_b128 v[206:209], v146 offset:22528
	ds_read_b128 v[210:213], v146 offset:23552
	global_load_lds_dwordx4 v[214:215], off
	v_lshl_add_u64 v[216:217], s[18:19], 0, v[136:137]
	s_mov_b32 m0, s45
	s_addc_u32 s51, s19, 0
	global_load_lds_dwordx4 v[216:217], off
	v_lshl_add_u64 v[218:219], s[50:51], 0, v[130:131]
	s_mov_b32 m0, s26
	v_lshl_add_u64 v[220:221], s[22:23], 0, v[134:135]
	global_load_lds_dwordx4 v[218:219], off
	v_lshl_add_u64 v[218:219], s[50:51], 0, v[136:137]
	s_mov_b32 m0, s46
	s_nop 0
	global_load_lds_dwordx4 v[218:219], off
	v_lshl_add_u64 v[218:219], s[22:23], 0, v[132:133]
	s_mov_b32 m0, s7
	s_nop 0
	global_load_lds_dwordx4 v[218:219], off
	s_mov_b32 m0, s34
	s_nop 0
	global_load_lds_dwordx4 v[220:221], off
	s_waitcnt vmcnt(8)
	s_waitcnt lgkmcnt(0)
	s_barrier
	s_setprio 1
	v_mfma_f32_16x16x32_bf16 v[62:65], v[150:153], v[182:185], v[62:65]
	v_mfma_f32_16x16x32_bf16 v[58:61], v[158:161], v[182:185], v[58:61]
	v_mfma_f32_16x16x32_bf16 v[54:57], v[150:153], v[190:193], v[54:57]
	v_mfma_f32_16x16x32_bf16 v[46:49], v[158:161], v[190:193], v[46:49]
	v_mfma_f32_16x16x32_bf16 v[38:41], v[150:153], v[198:201], v[38:41]
	v_mfma_f32_16x16x32_bf16 v[30:33], v[158:161], v[198:201], v[30:33]
	v_mfma_f32_16x16x32_bf16 v[22:25], v[150:153], v[206:209], v[22:25]
	v_mfma_f32_16x16x32_bf16 v[14:17], v[158:161], v[206:209], v[14:17]
	v_mfma_f32_16x16x32_bf16 v[62:65], v[154:157], v[186:189], v[62:65]
	v_mfma_f32_16x16x32_bf16 v[58:61], v[162:165], v[186:189], v[58:61]
	v_mfma_f32_16x16x32_bf16 v[54:57], v[154:157], v[194:197], v[54:57]
	v_mfma_f32_16x16x32_bf16 v[46:49], v[162:165], v[194:197], v[46:49]
	v_mfma_f32_16x16x32_bf16 v[38:41], v[154:157], v[202:205], v[38:41]
	v_mfma_f32_16x16x32_bf16 v[30:33], v[162:165], v[202:205], v[30:33]
	v_mfma_f32_16x16x32_bf16 v[22:25], v[154:157], v[210:213], v[22:25]
	v_mfma_f32_16x16x32_bf16 v[14:17], v[162:165], v[210:213], v[14:17]
	s_setprio 0
	s_setprio 1
	v_mfma_f32_16x16x32_bf16 v[50:53], v[166:169], v[182:185], v[50:53]
	v_mfma_f32_16x16x32_bf16 v[42:45], v[174:177], v[182:185], v[42:45]
	v_mfma_f32_16x16x32_bf16 v[34:37], v[166:169], v[190:193], v[34:37]
	v_mfma_f32_16x16x32_bf16 v[26:29], v[174:177], v[190:193], v[26:29]
	v_mfma_f32_16x16x32_bf16 v[18:21], v[166:169], v[198:201], v[18:21]
	v_mfma_f32_16x16x32_bf16 v[10:13], v[174:177], v[198:201], v[10:13]
	v_mfma_f32_16x16x32_bf16 v[6:9], v[166:169], v[206:209], v[6:9]
	v_mfma_f32_16x16x32_bf16 v[2:5], v[174:177], v[206:209], v[2:5]
	v_mfma_f32_16x16x32_bf16 v[50:53], v[170:173], v[186:189], v[50:53]
	v_mfma_f32_16x16x32_bf16 v[42:45], v[178:181], v[186:189], v[42:45]
	v_mfma_f32_16x16x32_bf16 v[34:37], v[170:173], v[194:197], v[34:37]
	v_mfma_f32_16x16x32_bf16 v[26:29], v[178:181], v[194:197], v[26:29]
	v_mfma_f32_16x16x32_bf16 v[18:21], v[170:173], v[202:205], v[18:21]
	v_mfma_f32_16x16x32_bf16 v[10:13], v[178:181], v[202:205], v[10:13]
	v_mfma_f32_16x16x32_bf16 v[6:9], v[170:173], v[210:213], v[6:9]
	v_mfma_f32_16x16x32_bf16 v[2:5], v[178:181], v[210:213], v[2:5]
	s_barrier
	s_setprio 0
	ds_read_b128 v[150:153], v147
	ds_read_b128 v[154:157], v147 offset:1024
	ds_read_b128 v[158:161], v147 offset:2048
	ds_read_b128 v[162:165], v147 offset:3072
	ds_read_b128 v[166:169], v148
	ds_read_b128 v[170:173], v148 offset:1024
	ds_read_b128 v[174:177], v148 offset:2048
	ds_read_b128 v[178:181], v148 offset:3072
	s_add_u32 s22, s22, 0x20000
	s_addc_u32 s23, s23, 0
	s_mov_b32 m0, s35
	v_lshl_add_u64 v[222:223], s[22:23], 0, v[132:133]
	ds_read_b128 v[182:185], v146 offset:32768
	ds_read_b128 v[186:189], v146 offset:33792
	ds_read_b128 v[190:193], v146 offset:34816
	ds_read_b128 v[194:197], v146 offset:35840
	ds_read_b128 v[198:201], v146 offset:36864
	ds_read_b128 v[202:205], v146 offset:37888
	ds_read_b128 v[206:209], v146 offset:38912
	ds_read_b128 v[210:213], v146 offset:39936
	global_load_lds_dwordx4 v[222:223], off
	v_lshl_add_u64 v[222:223], s[22:23], 0, v[134:135]
	s_mov_b32 m0, s36
	s_nop 0
	global_load_lds_dwordx4 v[222:223], off
	s_waitcnt vmcnt(8)
	s_waitcnt lgkmcnt(0)
	s_barrier
	s_setprio 1
	v_mfma_f32_16x16x32_bf16 v[126:129], v[150:153], v[182:185], v[126:129]
	v_mfma_f32_16x16x32_bf16 v[122:125], v[158:161], v[182:185], v[122:125]
	v_mfma_f32_16x16x32_bf16 v[118:121], v[150:153], v[190:193], v[118:121]
	v_mfma_f32_16x16x32_bf16 v[110:113], v[158:161], v[190:193], v[110:113]
	v_mfma_f32_16x16x32_bf16 v[102:105], v[150:153], v[198:201], v[102:105]
	v_mfma_f32_16x16x32_bf16 v[94:97], v[158:161], v[198:201], v[94:97]
	v_mfma_f32_16x16x32_bf16 v[86:89], v[150:153], v[206:209], v[86:89]
	v_mfma_f32_16x16x32_bf16 v[78:81], v[158:161], v[206:209], v[78:81]
	v_mfma_f32_16x16x32_bf16 v[126:129], v[154:157], v[186:189], v[126:129]
	v_mfma_f32_16x16x32_bf16 v[122:125], v[162:165], v[186:189], v[122:125]
	v_mfma_f32_16x16x32_bf16 v[118:121], v[154:157], v[194:197], v[118:121]
	v_mfma_f32_16x16x32_bf16 v[110:113], v[162:165], v[194:197], v[110:113]
	v_mfma_f32_16x16x32_bf16 v[102:105], v[154:157], v[202:205], v[102:105]
	v_mfma_f32_16x16x32_bf16 v[94:97], v[162:165], v[202:205], v[94:97]
	v_mfma_f32_16x16x32_bf16 v[86:89], v[154:157], v[210:213], v[86:89]
	v_mfma_f32_16x16x32_bf16 v[78:81], v[162:165], v[210:213], v[78:81]
	s_setprio 0
	s_setprio 1
	v_mfma_f32_16x16x32_bf16 v[114:117], v[166:169], v[182:185], v[114:117]
	v_mfma_f32_16x16x32_bf16 v[106:109], v[174:177], v[182:185], v[106:109]
	v_mfma_f32_16x16x32_bf16 v[98:101], v[166:169], v[190:193], v[98:101]
	v_mfma_f32_16x16x32_bf16 v[90:93], v[174:177], v[190:193], v[90:93]
	v_mfma_f32_16x16x32_bf16 v[82:85], v[166:169], v[198:201], v[82:85]
	v_mfma_f32_16x16x32_bf16 v[74:77], v[174:177], v[198:201], v[74:77]
	v_mfma_f32_16x16x32_bf16 v[70:73], v[166:169], v[206:209], v[70:73]
	v_mfma_f32_16x16x32_bf16 v[66:69], v[174:177], v[206:209], v[66:69]
	v_mfma_f32_16x16x32_bf16 v[114:117], v[170:173], v[186:189], v[114:117]
	v_mfma_f32_16x16x32_bf16 v[106:109], v[178:181], v[186:189], v[106:109]
	v_mfma_f32_16x16x32_bf16 v[98:101], v[170:173], v[194:197], v[98:101]
	v_mfma_f32_16x16x32_bf16 v[90:93], v[178:181], v[194:197], v[90:93]
	v_mfma_f32_16x16x32_bf16 v[82:85], v[170:173], v[202:205], v[82:85]
	v_mfma_f32_16x16x32_bf16 v[74:77], v[178:181], v[202:205], v[74:77]
	v_mfma_f32_16x16x32_bf16 v[70:73], v[170:173], v[210:213], v[70:73]
	v_mfma_f32_16x16x32_bf16 v[66:69], v[178:181], v[210:213], v[66:69]
	s_barrier
	s_setprio 0
	s_mov_b32 m0, s27
	v_lshl_add_u64 v[214:215], v[214:215], 0, s[12:13]
	s_add_u32 s18, s18, 0x20080
	ds_read_b128 v[182:185], v146 offset:49152
	ds_read_b128 v[186:189], v146 offset:50176
	ds_read_b128 v[190:193], v146 offset:51200
	ds_read_b128 v[194:197], v146 offset:52224
	ds_read_b128 v[198:201], v146 offset:53248
	ds_read_b128 v[202:205], v146 offset:54272
	ds_read_b128 v[206:209], v146 offset:55296
	ds_read_b128 v[210:213], v146 offset:56320
	global_load_lds_dwordx4 v[214:215], off
	v_lshl_add_u64 v[214:215], v[216:217], 0, s[12:13]
	s_mov_b32 m0, s47
	s_addc_u32 s19, s19, 0
	global_load_lds_dwordx4 v[214:215], off
	v_lshl_add_u64 v[214:215], s[18:19], 0, v[130:131]
	s_mov_b32 m0, s30
	s_nop 0
	global_load_lds_dwordx4 v[214:215], off
	v_lshl_add_u64 v[214:215], s[18:19], 0, v[136:137]
	s_mov_b32 m0, s48
	s_nop 0
	global_load_lds_dwordx4 v[214:215], off
	v_lshl_add_u64 v[214:215], v[218:219], 0, s[12:13]
	s_mov_b32 m0, s38
	s_nop 0
	global_load_lds_dwordx4 v[214:215], off
	v_lshl_add_u64 v[214:215], v[220:221], 0, s[12:13]
	s_mov_b32 m0, s39
	s_nop 0
	global_load_lds_dwordx4 v[214:215], off
	s_waitcnt vmcnt(8)
	s_waitcnt lgkmcnt(0)
	s_barrier
	s_setprio 1
	v_mfma_f32_16x16x32_bf16 v[62:65], v[150:153], v[182:185], v[62:65]
	v_mfma_f32_16x16x32_bf16 v[58:61], v[158:161], v[182:185], v[58:61]
	v_mfma_f32_16x16x32_bf16 v[54:57], v[150:153], v[190:193], v[54:57]
	v_mfma_f32_16x16x32_bf16 v[46:49], v[158:161], v[190:193], v[46:49]
	v_mfma_f32_16x16x32_bf16 v[38:41], v[150:153], v[198:201], v[38:41]
	v_mfma_f32_16x16x32_bf16 v[30:33], v[158:161], v[198:201], v[30:33]
	v_mfma_f32_16x16x32_bf16 v[22:25], v[150:153], v[206:209], v[22:25]
	v_mfma_f32_16x16x32_bf16 v[14:17], v[158:161], v[206:209], v[14:17]
	v_mfma_f32_16x16x32_bf16 v[62:65], v[154:157], v[186:189], v[62:65]
	v_mfma_f32_16x16x32_bf16 v[58:61], v[162:165], v[186:189], v[58:61]
	v_mfma_f32_16x16x32_bf16 v[54:57], v[154:157], v[194:197], v[54:57]
	v_mfma_f32_16x16x32_bf16 v[46:49], v[162:165], v[194:197], v[46:49]
	v_mfma_f32_16x16x32_bf16 v[38:41], v[154:157], v[202:205], v[38:41]
	v_mfma_f32_16x16x32_bf16 v[30:33], v[162:165], v[202:205], v[30:33]
	v_mfma_f32_16x16x32_bf16 v[22:25], v[154:157], v[210:213], v[22:25]
	v_mfma_f32_16x16x32_bf16 v[14:17], v[162:165], v[210:213], v[14:17]
	s_setprio 0
	s_setprio 1
	v_mfma_f32_16x16x32_bf16 v[50:53], v[166:169], v[182:185], v[50:53]
	v_mfma_f32_16x16x32_bf16 v[42:45], v[174:177], v[182:185], v[42:45]
	v_mfma_f32_16x16x32_bf16 v[34:37], v[166:169], v[190:193], v[34:37]
	v_mfma_f32_16x16x32_bf16 v[26:29], v[174:177], v[190:193], v[26:29]
	v_mfma_f32_16x16x32_bf16 v[18:21], v[166:169], v[198:201], v[18:21]
	v_mfma_f32_16x16x32_bf16 v[10:13], v[174:177], v[198:201], v[10:13]
	v_mfma_f32_16x16x32_bf16 v[6:9], v[166:169], v[206:209], v[6:9]
	v_mfma_f32_16x16x32_bf16 v[2:5], v[174:177], v[206:209], v[2:5]
	v_mfma_f32_16x16x32_bf16 v[50:53], v[170:173], v[186:189], v[50:53]
	v_mfma_f32_16x16x32_bf16 v[42:45], v[178:181], v[186:189], v[42:45]
	v_mfma_f32_16x16x32_bf16 v[34:37], v[170:173], v[194:197], v[34:37]
	v_mfma_f32_16x16x32_bf16 v[26:29], v[178:181], v[194:197], v[26:29]
	v_mfma_f32_16x16x32_bf16 v[18:21], v[170:173], v[202:205], v[18:21]
	v_mfma_f32_16x16x32_bf16 v[10:13], v[178:181], v[202:205], v[10:13]
	v_mfma_f32_16x16x32_bf16 v[6:9], v[170:173], v[210:213], v[6:9]
	v_mfma_f32_16x16x32_bf16 v[2:5], v[178:181], v[210:213], v[2:5]
	s_barrier
	s_setprio 0
	s_add_i32 s42, s42, 2
	s_add_u32 s16, s16, 0x100
	s_addc_u32 s17, s17, 0
	s_cmp_gt_u32 s42, 5
	s_cbranch_scc0 .LBB0_274
	s_cmpk_lt_u32 s31, 0x100
	s_cbranch_scc0 .LBB0_277
	s_barrier

.Lpj_skip1_p:
	s_waitcnt lgkmcnt(0)
	s_barrier
	s_setprio 1
	v_mfma_f32_16x16x32_bf16 v[128:131], v[154:157], v[196:199], 0
	v_mfma_f32_16x16x32_bf16 v[124:127], v[172:175], v[196:199], 0
	v_mfma_f32_16x16x32_bf16 v[116:119], v[154:157], v[204:207], 0
	v_mfma_f32_16x16x32_bf16 v[108:111], v[172:175], v[204:207], 0
	v_mfma_f32_16x16x32_bf16 v[100:103], v[154:157], v[212:215], 0
	v_mfma_f32_16x16x32_bf16 v[92:95], v[172:175], v[212:215], 0
	v_mfma_f32_16x16x32_bf16 v[84:87], v[154:157], v[220:223], 0
	v_mfma_f32_16x16x32_bf16 v[76:79], v[172:175], v[220:223], 0
	v_mfma_f32_16x16x32_bf16 v[128:131], v[168:171], v[200:203], v[128:131]
	v_mfma_f32_16x16x32_bf16 v[124:127], v[176:179], v[200:203], v[124:127]
	v_mfma_f32_16x16x32_bf16 v[116:119], v[168:171], v[208:211], v[116:119]
	v_mfma_f32_16x16x32_bf16 v[108:111], v[176:179], v[208:211], v[108:111]
	v_mfma_f32_16x16x32_bf16 v[100:103], v[168:171], v[216:219], v[100:103]
	v_mfma_f32_16x16x32_bf16 v[92:95], v[176:179], v[216:219], v[92:95]
	v_mfma_f32_16x16x32_bf16 v[84:87], v[168:171], v[224:227], v[84:87]
	v_mfma_f32_16x16x32_bf16 v[76:79], v[176:179], v[224:227], v[76:79]
	v_mfma_f32_16x16x32_bf16 v[120:123], v[180:183], v[196:199], 0
	v_mfma_f32_16x16x32_bf16 v[112:115], v[188:191], v[196:199], 0
	v_mfma_f32_16x16x32_bf16 v[104:107], v[180:183], v[204:207], 0
	v_mfma_f32_16x16x32_bf16 v[96:99], v[188:191], v[204:207], 0
	v_mfma_f32_16x16x32_bf16 v[88:91], v[180:183], v[212:215], 0
	v_mfma_f32_16x16x32_bf16 v[80:83], v[188:191], v[212:215], 0
	v_mfma_f32_16x16x32_bf16 v[72:75], v[180:183], v[220:223], 0
	v_mfma_f32_16x16x32_bf16 v[68:71], v[188:191], v[220:223], 0
	v_mfma_f32_16x16x32_bf16 v[120:123], v[184:187], v[200:203], v[120:123]
	v_mfma_f32_16x16x32_bf16 v[112:115], v[192:195], v[200:203], v[112:115]
	v_mfma_f32_16x16x32_bf16 v[104:107], v[184:187], v[208:211], v[104:107]
	v_mfma_f32_16x16x32_bf16 v[96:99], v[192:195], v[208:211], v[96:99]
	v_mfma_f32_16x16x32_bf16 v[88:91], v[184:187], v[216:219], v[88:91]
	v_mfma_f32_16x16x32_bf16 v[80:83], v[192:195], v[216:219], v[80:83]
	v_mfma_f32_16x16x32_bf16 v[72:75], v[184:187], v[224:227], v[72:75]
	v_mfma_f32_16x16x32_bf16 v[68:71], v[192:195], v[224:227], v[68:71]
	s_barrier
	s_setprio 0
	s_add_i32 s43, s50, s10
	s_mov_b32 m0, s43
	ds_read_b128 v[196:199], v167 offset:16384
	ds_read_b128 v[200:203], v167 offset:17408
	ds_read_b128 v[204:207], v167 offset:18432
	ds_read_b128 v[208:211], v167 offset:19456
	ds_read_b128 v[212:215], v167 offset:20480
	ds_read_b128 v[216:219], v167 offset:21504
	ds_read_b128 v[220:223], v167 offset:22528
	ds_read_b128 v[224:227], v167 offset:23552
	global_load_lds_dwordx4 v2, s[46:47]
	s_add_i32 m0, s43, 0x2000
	s_add_u32 s50, s46, 0x80000
	s_addc_u32 s51, s47, 0
	s_add_i32 s33, s33, s10
	global_load_lds_dwordx4 v0, s[46:47]
	s_mov_b32 m0, s33
	s_nop 0
	global_load_lds_dwordx4 v2, s[50:51]
	s_add_i32 m0, s33, 0x2000
	s_nop 0
	global_load_lds_dwordx4 v0, s[50:51]
	s_mov_b32 m0, s12
	s_nop 0
	global_load_lds_dwordx4 v134, s[48:49]
	s_mov_b32 m0, s13
	s_nop 0
	global_load_lds_dwordx4 v132, s[48:49]
	s_cmp_lg_u32 s32, 0
	s_cbranch_scc1 .Lpj_skip2_p
	s_waitcnt vmcnt(8)
.Lpj_skip2_p:
	s_mov_b32 s32, 0
	s_waitcnt lgkmcnt(0)
	s_barrier
	s_setprio 1
	v_mfma_f32_16x16x32_bf16 v[64:67], v[154:157], v[196:199], 0
	v_mfma_f32_16x16x32_bf16 v[60:63], v[172:175], v[196:199], 0
	v_mfma_f32_16x16x32_bf16 v[52:55], v[154:157], v[204:207], 0
	v_mfma_f32_16x16x32_bf16 v[44:47], v[172:175], v[204:207], 0
	v_mfma_f32_16x16x32_bf16 v[36:39], v[154:157], v[212:215], 0
	v_mfma_f32_16x16x32_bf16 v[28:31], v[172:175], v[212:215], 0
	v_mfma_f32_16x16x32_bf16 v[20:23], v[154:157], v[220:223], 0
	v_mfma_f32_16x16x32_bf16 v[12:15], v[172:175], v[220:223], 0
	v_mfma_f32_16x16x32_bf16 v[64:67], v[168:171], v[200:203], v[64:67]
	v_mfma_f32_16x16x32_bf16 v[60:63], v[176:179], v[200:203], v[60:63]
	v_mfma_f32_16x16x32_bf16 v[52:55], v[168:171], v[208:211], v[52:55]
	v_mfma_f32_16x16x32_bf16 v[44:47], v[176:179], v[208:211], v[44:47]
	v_mfma_f32_16x16x32_bf16 v[36:39], v[168:171], v[216:219], v[36:39]
	v_mfma_f32_16x16x32_bf16 v[28:31], v[176:179], v[216:219], v[28:31]
	v_mfma_f32_16x16x32_bf16 v[20:23], v[168:171], v[224:227], v[20:23]
	v_mfma_f32_16x16x32_bf16 v[12:15], v[176:179], v[224:227], v[12:15]
	v_mfma_f32_16x16x32_bf16 v[56:59], v[180:183], v[196:199], 0
	v_mfma_f32_16x16x32_bf16 v[48:51], v[188:191], v[196:199], 0
	v_mfma_f32_16x16x32_bf16 v[40:43], v[180:183], v[204:207], 0
	v_mfma_f32_16x16x32_bf16 v[32:35], v[188:191], v[204:207], 0
	v_mfma_f32_16x16x32_bf16 v[24:27], v[180:183], v[212:215], 0
	v_mfma_f32_16x16x32_bf16 v[16:19], v[188:191], v[212:215], 0
	v_mfma_f32_16x16x32_bf16 v[8:11], v[180:183], v[220:223], 0
	v_mfma_f32_16x16x32_bf16 v[4:7], v[188:191], v[220:223], 0
	v_mfma_f32_16x16x32_bf16 v[56:59], v[184:187], v[200:203], v[56:59]
	v_mfma_f32_16x16x32_bf16 v[48:51], v[192:195], v[200:203], v[48:51]
	v_mfma_f32_16x16x32_bf16 v[40:43], v[184:187], v[208:211], v[40:43]
	v_mfma_f32_16x16x32_bf16 v[32:35], v[192:195], v[208:211], v[32:35]
	v_mfma_f32_16x16x32_bf16 v[24:27], v[184:187], v[216:219], v[24:27]
	v_mfma_f32_16x16x32_bf16 v[16:19], v[192:195], v[216:219], v[16:19]
	v_mfma_f32_16x16x32_bf16 v[8:11], v[184:187], v[224:227], v[8:11]
	v_mfma_f32_16x16x32_bf16 v[4:7], v[192:195], v[224:227], v[4:7]
	s_barrier
	s_setprio 0
	s_add_i32 s33, 0, 0x18000
	v_add_u32_e32 v144, s33, v149
	s_add_i32 s43, 0, 0x1c000
	ds_read_b128 v[154:157], v144
	ds_read_b128 v[168:171], v144 offset:1024
	ds_read_b128 v[172:175], v144 offset:2048
	ds_read_b128 v[176:179], v144 offset:3072
	v_add_u32_e32 v144, s43, v149
	ds_read_b128 v[180:183], v144
	ds_read_b128 v[184:187], v144 offset:1024
	ds_read_b128 v[188:191], v144 offset:2048
	ds_read_b128 v[192:195], v144 offset:3072
	s_add_u32 s48, s48, 0x80000
	s_addc_u32 s49, s49, 0
	s_mov_b32 m0, s14
	ds_read_b128 v[196:199], v167 offset:32768
	ds_read_b128 v[200:203], v167 offset:33792
	ds_read_b128 v[204:207], v167 offset:34816
	ds_read_b128 v[208:211], v167 offset:35840
	ds_read_b128 v[212:215], v167 offset:36864
	ds_read_b128 v[216:219], v167 offset:37888
	ds_read_b128 v[220:223], v167 offset:38912
	ds_read_b128 v[224:227], v167 offset:39936
	global_load_lds_dwordx4 v134, s[48:49]
	s_mov_b32 m0, s15
	s_nop 0
	global_load_lds_dwordx4 v132, s[48:49]
	s_waitcnt vmcnt(8)
	s_waitcnt lgkmcnt(0)
	s_barrier
	s_setprio 1
	v_mfma_f32_16x16x32_bf16 v[128:131], v[154:157], v[196:199], v[128:131]
	v_mfma_f32_16x16x32_bf16 v[124:127], v[172:175], v[196:199], v[124:127]
	v_mfma_f32_16x16x32_bf16 v[116:119], v[154:157], v[204:207], v[116:119]
	v_mfma_f32_16x16x32_bf16 v[108:111], v[172:175], v[204:207], v[108:111]
	v_mfma_f32_16x16x32_bf16 v[100:103], v[154:157], v[212:215], v[100:103]
	v_mfma_f32_16x16x32_bf16 v[92:95], v[172:175], v[212:215], v[92:95]
	v_mfma_f32_16x16x32_bf16 v[84:87], v[154:157], v[220:223], v[84:87]
	v_mfma_f32_16x16x32_bf16 v[76:79], v[172:175], v[220:223], v[76:79]
	v_mfma_f32_16x16x32_bf16 v[128:131], v[168:171], v[200:203], v[128:131]
	v_mfma_f32_16x16x32_bf16 v[124:127], v[176:179], v[200:203], v[124:127]
	v_mfma_f32_16x16x32_bf16 v[116:119], v[168:171], v[208:211], v[116:119]
	v_mfma_f32_16x16x32_bf16 v[108:111], v[176:179], v[208:211], v[108:111]
	v_mfma_f32_16x16x32_bf16 v[100:103], v[168:171], v[216:219], v[100:103]
	v_mfma_f32_16x16x32_bf16 v[92:95], v[176:179], v[216:219], v[92:95]
	v_mfma_f32_16x16x32_bf16 v[84:87], v[168:171], v[224:227], v[84:87]
	v_mfma_f32_16x16x32_bf16 v[76:79], v[176:179], v[224:227], v[76:79]
	v_mfma_f32_16x16x32_bf16 v[120:123], v[180:183], v[196:199], v[120:123]
	v_mfma_f32_16x16x32_bf16 v[112:115], v[188:191], v[196:199], v[112:115]
	v_mfma_f32_16x16x32_bf16 v[104:107], v[180:183], v[204:207], v[104:107]
	v_mfma_f32_16x16x32_bf16 v[96:99], v[188:191], v[204:207], v[96:99]
	v_mfma_f32_16x16x32_bf16 v[88:91], v[180:183], v[212:215], v[88:91]
	v_mfma_f32_16x16x32_bf16 v[80:83], v[188:191], v[212:215], v[80:83]
	v_mfma_f32_16x16x32_bf16 v[72:75], v[180:183], v[220:223], v[72:75]
	v_mfma_f32_16x16x32_bf16 v[68:71], v[188:191], v[220:223], v[68:71]
	v_mfma_f32_16x16x32_bf16 v[120:123], v[184:187], v[200:203], v[120:123]
	v_mfma_f32_16x16x32_bf16 v[112:115], v[192:195], v[200:203], v[112:115]
	v_mfma_f32_16x16x32_bf16 v[104:107], v[184:187], v[208:211], v[104:107]
	v_mfma_f32_16x16x32_bf16 v[96:99], v[192:195], v[208:211], v[96:99]
	v_mfma_f32_16x16x32_bf16 v[88:91], v[184:187], v[216:219], v[88:91]
	v_mfma_f32_16x16x32_bf16 v[80:83], v[192:195], v[216:219], v[80:83]
	v_mfma_f32_16x16x32_bf16 v[72:75], v[184:187], v[224:227], v[72:75]
	v_mfma_f32_16x16x32_bf16 v[68:71], v[192:195], v[224:227], v[68:71]
	s_barrier
	s_setprio 0
	s_add_i32 s33, s33, s10
	s_mov_b32 m0, s33
	ds_read_b128 v[196:199], v167 offset:49152
	ds_read_b128 v[200:203], v167 offset:50176
	ds_read_b128 v[204:207], v167 offset:51200
	ds_read_b128 v[208:211], v167 offset:52224
	ds_read_b128 v[212:215], v167 offset:53248
	ds_read_b128 v[216:219], v167 offset:54272
	ds_read_b128 v[220:223], v167 offset:55296
	ds_read_b128 v[224:227], v167 offset:56320
	s_add_u32 s100, s46, 0x80
	s_addc_u32 s101, s47, 0
	global_load_lds_dwordx4 v2, s[100:101]
	s_add_i32 m0, s33, 0x2000
	s_add_u32 s46, s46, 0x80080
	s_addc_u32 s47, s47, 0
	s_add_i32 s33, s43, s10
	s_add_u32 s100, s46, 0xfff80000
	s_addc_u32 s101, s47, -1
	global_load_lds_dwordx4 v0, s[100:101]
	s_mov_b32 m0, s33
	s_nop 0
	global_load_lds_dwordx4 v2, s[46:47]
	s_add_i32 m0, s33, 0x2000
	s_nop 0
	global_load_lds_dwordx4 v0, s[46:47]
	s_mov_b32 m0, s16
	s_nop 0
	s_add_u32 s100, s48, 0xfff80080
	s_addc_u32 s101, s49, -1
	global_load_lds_dwordx4 v134, s[100:101]
	s_mov_b32 m0, s17
	s_nop 0
	s_add_u32 s100, s48, 0xfff80080
	s_addc_u32 s101, s49, -1
	global_load_lds_dwordx4 v132, s[100:101]
	s_waitcnt vmcnt(8)
	s_waitcnt lgkmcnt(0)
	s_barrier
	s_setprio 1
	v_mfma_f32_16x16x32_bf16 v[64:67], v[154:157], v[196:199], v[64:67]
	v_mfma_f32_16x16x32_bf16 v[60:63], v[172:175], v[196:199], v[60:63]
	v_mfma_f32_16x16x32_bf16 v[52:55], v[154:157], v[204:207], v[52:55]
	v_mfma_f32_16x16x32_bf16 v[44:47], v[172:175], v[204:207], v[44:47]
	v_mfma_f32_16x16x32_bf16 v[36:39], v[154:157], v[212:215], v[36:39]
	v_mfma_f32_16x16x32_bf16 v[28:31], v[172:175], v[212:215], v[28:31]
	v_mfma_f32_16x16x32_bf16 v[20:23], v[154:157], v[220:223], v[20:23]
	v_mfma_f32_16x16x32_bf16 v[12:15], v[172:175], v[220:223], v[12:15]
	v_mfma_f32_16x16x32_bf16 v[64:67], v[168:171], v[200:203], v[64:67]
	v_mfma_f32_16x16x32_bf16 v[60:63], v[176:179], v[200:203], v[60:63]
	v_mfma_f32_16x16x32_bf16 v[52:55], v[168:171], v[208:211], v[52:55]
	v_mfma_f32_16x16x32_bf16 v[44:47], v[176:179], v[208:211], v[44:47]
	v_mfma_f32_16x16x32_bf16 v[36:39], v[168:171], v[216:219], v[36:39]
	v_mfma_f32_16x16x32_bf16 v[28:31], v[176:179], v[216:219], v[28:31]
	v_mfma_f32_16x16x32_bf16 v[20:23], v[168:171], v[224:227], v[20:23]
	v_mfma_f32_16x16x32_bf16 v[12:15], v[176:179], v[224:227], v[12:15]
	v_mfma_f32_16x16x32_bf16 v[56:59], v[180:183], v[196:199], v[56:59]
	v_mfma_f32_16x16x32_bf16 v[48:51], v[188:191], v[196:199], v[48:51]
	v_mfma_f32_16x16x32_bf16 v[40:43], v[180:183], v[204:207], v[40:43]
	v_mfma_f32_16x16x32_bf16 v[32:35], v[188:191], v[204:207], v[32:35]
	v_mfma_f32_16x16x32_bf16 v[24:27], v[180:183], v[212:215], v[24:27]
	v_mfma_f32_16x16x32_bf16 v[16:19], v[188:191], v[212:215], v[16:19]
	v_mfma_f32_16x16x32_bf16 v[8:11], v[180:183], v[220:223], v[8:11]
	v_mfma_f32_16x16x32_bf16 v[4:7], v[188:191], v[220:223], v[4:7]
	v_mfma_f32_16x16x32_bf16 v[56:59], v[184:187], v[200:203], v[56:59]
	v_mfma_f32_16x16x32_bf16 v[48:51], v[192:195], v[200:203], v[48:51]
	v_mfma_f32_16x16x32_bf16 v[40:43], v[184:187], v[208:211], v[40:43]
	v_mfma_f32_16x16x32_bf16 v[32:35], v[192:195], v[208:211], v[32:35]
	v_mfma_f32_16x16x32_bf16 v[24:27], v[184:187], v[216:219], v[24:27]
	v_mfma_f32_16x16x32_bf16 v[16:19], v[192:195], v[216:219], v[16:19]
	v_mfma_f32_16x16x32_bf16 v[8:11], v[184:187], v[224:227], v[8:11]
	v_mfma_f32_16x16x32_bf16 v[4:7], v[192:195], v[224:227], v[4:7]
	s_barrier
	s_setprio 0
	s_add_i32 s35, s35, 2
	s_add_u32 s31, s31, 0x100
	s_addc_u32 s34, s34, 0
	s_add_u32 s44, s44, 0x100
	s_addc_u32 s45, s45, 0
	s_cmp_gt_u32 s35, 29
.LBB0_342:
	s_add_u32 s33, s44, 0xfff80080
	s_addc_u32 s43, s45, -1
	s_add_i32 s50, 0, 0x10000
	s_cmp_eq_u32 s35, 28
	s_cselect_b32 s49, s27, s43
	s_cselect_b32 s48, s28, s33
	v_add_u32_e32 v142, s50, v149
	s_cselect_b32 s47, s25, s34
	s_cselect_b32 s46, s29, s31
	s_add_i32 s33, 0, 0x14000
	ds_read_b128 v[154:157], v142
	ds_read_b128 v[168:171], v142 offset:1024
	ds_read_b128 v[172:175], v142 offset:2048
	ds_read_b128 v[176:179], v142 offset:3072
	v_add_u32_e32 v142, s33, v149
	ds_read_b128 v[180:183], v142
	ds_read_b128 v[184:187], v142 offset:1024
	ds_read_b128 v[188:191], v142 offset:2048
	ds_read_b128 v[192:195], v142 offset:3072
	s_add_i32 m0, s12, 0xc000
	ds_read_b128 v[196:199], v167
	ds_read_b128 v[200:203], v167 offset:1024
	ds_read_b128 v[204:207], v167 offset:2048
	ds_read_b128 v[208:211], v167 offset:3072
	ds_read_b128 v[212:215], v167 offset:4096
	ds_read_b128 v[216:219], v167 offset:5120
	ds_read_b128 v[220:223], v167 offset:6144
	ds_read_b128 v[224:227], v167 offset:7168
	global_load_lds_dwordx4 v140, s[44:45]
	s_add_i32 m0, s12, 0xe000
	s_nop 0
	global_load_lds_dwordx4 v138, s[44:45]
	s_waitcnt vmcnt(8)
	s_waitcnt lgkmcnt(0)
	s_barrier
	s_setprio 1
	v_mfma_f32_16x16x32_bf16 v[128:131], v[154:157], v[196:199], v[128:131]
	v_mfma_f32_16x16x32_bf16 v[124:127], v[172:175], v[196:199], v[124:127]
	v_mfma_f32_16x16x32_bf16 v[116:119], v[154:157], v[204:207], v[116:119]
	v_mfma_f32_16x16x32_bf16 v[108:111], v[172:175], v[204:207], v[108:111]
	v_mfma_f32_16x16x32_bf16 v[100:103], v[154:157], v[212:215], v[100:103]
	v_mfma_f32_16x16x32_bf16 v[92:95], v[172:175], v[212:215], v[92:95]
	v_mfma_f32_16x16x32_bf16 v[84:87], v[154:157], v[220:223], v[84:87]
	v_mfma_f32_16x16x32_bf16 v[76:79], v[172:175], v[220:223], v[76:79]
	v_mfma_f32_16x16x32_bf16 v[128:131], v[168:171], v[200:203], v[128:131]
	v_mfma_f32_16x16x32_bf16 v[124:127], v[176:179], v[200:203], v[124:127]
	v_mfma_f32_16x16x32_bf16 v[116:119], v[168:171], v[208:211], v[116:119]
	v_mfma_f32_16x16x32_bf16 v[108:111], v[176:179], v[208:211], v[108:111]
	v_mfma_f32_16x16x32_bf16 v[100:103], v[168:171], v[216:219], v[100:103]
	v_mfma_f32_16x16x32_bf16 v[92:95], v[176:179], v[216:219], v[92:95]
	v_mfma_f32_16x16x32_bf16 v[84:87], v[168:171], v[224:227], v[84:87]
	v_mfma_f32_16x16x32_bf16 v[76:79], v[176:179], v[224:227], v[76:79]
	v_mfma_f32_16x16x32_bf16 v[120:123], v[180:183], v[196:199], v[120:123]
	v_mfma_f32_16x16x32_bf16 v[112:115], v[188:191], v[196:199], v[112:115]
	v_mfma_f32_16x16x32_bf16 v[104:107], v[180:183], v[204:207], v[104:107]
	v_mfma_f32_16x16x32_bf16 v[96:99], v[188:191], v[204:207], v[96:99]
	v_mfma_f32_16x16x32_bf16 v[88:91], v[180:183], v[212:215], v[88:91]
	v_mfma_f32_16x16x32_bf16 v[80:83], v[188:191], v[212:215], v[80:83]
	v_mfma_f32_16x16x32_bf16 v[72:75], v[180:183], v[220:223], v[72:75]
	v_mfma_f32_16x16x32_bf16 v[68:71], v[188:191], v[220:223], v[68:71]
	v_mfma_f32_16x16x32_bf16 v[120:123], v[184:187], v[200:203], v[120:123]
	v_mfma_f32_16x16x32_bf16 v[112:115], v[192:195], v[200:203], v[112:115]
	v_mfma_f32_16x16x32_bf16 v[104:107], v[184:187], v[208:211], v[104:107]
	v_mfma_f32_16x16x32_bf16 v[96:99], v[192:195], v[208:211], v[96:99]
	v_mfma_f32_16x16x32_bf16 v[88:91], v[184:187], v[216:219], v[88:91]
	v_mfma_f32_16x16x32_bf16 v[80:83], v[192:195], v[216:219], v[80:83]
	v_mfma_f32_16x16x32_bf16 v[72:75], v[184:187], v[224:227], v[72:75]
	v_mfma_f32_16x16x32_bf16 v[68:71], v[192:195], v[224:227], v[68:71]
	s_barrier
	s_setprio 0
	s_add_i32 s43, s50, s10
	s_mov_b32 m0, s43
	ds_read_b128 v[196:199], v167 offset:16384
	ds_read_b128 v[200:203], v167 offset:17408
	ds_read_b128 v[204:207], v167 offset:18432
	ds_read_b128 v[208:211], v167 offset:19456
	ds_read_b128 v[212:215], v167 offset:20480
	ds_read_b128 v[216:219], v167 offset:21504
	ds_read_b128 v[220:223], v167 offset:22528
	ds_read_b128 v[224:227], v167 offset:23552
	global_load_lds_dwordx4 v2, s[46:47]
	s_add_i32 m0, s43, 0x2000
	s_add_u32 s50, s46, 0x80000
	s_addc_u32 s51, s47, 0
	s_add_i32 s33, s33, s10
	global_load_lds_dwordx4 v0, s[46:47]
	s_mov_b32 m0, s33
	s_nop 0
	global_load_lds_dwordx4 v2, s[50:51]
	s_add_i32 m0, s33, 0x2000
	s_nop 0
	global_load_lds_dwordx4 v0, s[50:51]
	s_mov_b32 m0, s12
	s_nop 0
	global_load_lds_dwordx4 v134, s[48:49]
	s_mov_b32 m0, s13
	s_nop 0
	global_load_lds_dwordx4 v132, s[48:49]
	s_waitcnt vmcnt(8)
	s_waitcnt lgkmcnt(0)
	s_barrier
	s_setprio 1
	v_mfma_f32_16x16x32_bf16 v[64:67], v[154:157], v[196:199], v[64:67]
	v_mfma_f32_16x16x32_bf16 v[60:63], v[172:175], v[196:199], v[60:63]
	v_mfma_f32_16x16x32_bf16 v[52:55], v[154:157], v[204:207], v[52:55]
	v_mfma_f32_16x16x32_bf16 v[44:47], v[172:175], v[204:207], v[44:47]
	v_mfma_f32_16x16x32_bf16 v[36:39], v[154:157], v[212:215], v[36:39]
	v_mfma_f32_16x16x32_bf16 v[28:31], v[172:175], v[212:215], v[28:31]
	v_mfma_f32_16x16x32_bf16 v[20:23], v[154:157], v[220:223], v[20:23]
	v_mfma_f32_16x16x32_bf16 v[12:15], v[172:175], v[220:223], v[12:15]
	v_mfma_f32_16x16x32_bf16 v[64:67], v[168:171], v[200:203], v[64:67]
	v_mfma_f32_16x16x32_bf16 v[60:63], v[176:179], v[200:203], v[60:63]
	v_mfma_f32_16x16x32_bf16 v[52:55], v[168:171], v[208:211], v[52:55]
	v_mfma_f32_16x16x32_bf16 v[44:47], v[176:179], v[208:211], v[44:47]
	v_mfma_f32_16x16x32_bf16 v[36:39], v[168:171], v[216:219], v[36:39]
	v_mfma_f32_16x16x32_bf16 v[28:31], v[176:179], v[216:219], v[28:31]
	v_mfma_f32_16x16x32_bf16 v[20:23], v[168:171], v[224:227], v[20:23]
	v_mfma_f32_16x16x32_bf16 v[12:15], v[176:179], v[224:227], v[12:15]
	v_mfma_f32_16x16x32_bf16 v[56:59], v[180:183], v[196:199], v[56:59]
	v_mfma_f32_16x16x32_bf16 v[48:51], v[188:191], v[196:199], v[48:51]
	v_mfma_f32_16x16x32_bf16 v[40:43], v[180:183], v[204:207], v[40:43]
	v_mfma_f32_16x16x32_bf16 v[32:35], v[188:191], v[204:207], v[32:35]
	v_mfma_f32_16x16x32_bf16 v[24:27], v[180:183], v[212:215], v[24:27]
	v_mfma_f32_16x16x32_bf16 v[16:19], v[188:191], v[212:215], v[16:19]
	v_mfma_f32_16x16x32_bf16 v[8:11], v[180:183], v[220:223], v[8:11]
	v_mfma_f32_16x16x32_bf16 v[4:7], v[188:191], v[220:223], v[4:7]
	v_mfma_f32_16x16x32_bf16 v[56:59], v[184:187], v[200:203], v[56:59]
	v_mfma_f32_16x16x32_bf16 v[48:51], v[192:195], v[200:203], v[48:51]
	v_mfma_f32_16x16x32_bf16 v[40:43], v[184:187], v[208:211], v[40:43]
	v_mfma_f32_16x16x32_bf16 v[32:35], v[192:195], v[208:211], v[32:35]
	v_mfma_f32_16x16x32_bf16 v[24:27], v[184:187], v[216:219], v[24:27]
	v_mfma_f32_16x16x32_bf16 v[16:19], v[192:195], v[216:219], v[16:19]
	v_mfma_f32_16x16x32_bf16 v[8:11], v[184:187], v[224:227], v[8:11]
	v_mfma_f32_16x16x32_bf16 v[4:7], v[192:195], v[224:227], v[4:7]
	s_barrier
	s_setprio 0
	s_add_i32 s33, 0, 0x18000
	v_add_u32_e32 v144, s33, v149
	s_add_i32 s43, 0, 0x1c000
	ds_read_b128 v[154:157], v144
	ds_read_b128 v[168:171], v144 offset:1024
	ds_read_b128 v[172:175], v144 offset:2048
	ds_read_b128 v[176:179], v144 offset:3072
	v_add_u32_e32 v144, s43, v149
	ds_read_b128 v[180:183], v144
	ds_read_b128 v[184:187], v144 offset:1024
	ds_read_b128 v[188:191], v144 offset:2048
	ds_read_b128 v[192:195], v144 offset:3072
	s_add_u32 s48, s48, 0x80000
	s_addc_u32 s49, s49, 0
	s_mov_b32 m0, s14
	ds_read_b128 v[196:199], v167 offset:32768
	ds_read_b128 v[200:203], v167 offset:33792
	ds_read_b128 v[204:207], v167 offset:34816
	ds_read_b128 v[208:211], v167 offset:35840
	ds_read_b128 v[212:215], v167 offset:36864
	ds_read_b128 v[216:219], v167 offset:37888
	ds_read_b128 v[220:223], v167 offset:38912
	ds_read_b128 v[224:227], v167 offset:39936
	global_load_lds_dwordx4 v134, s[48:49]
	s_mov_b32 m0, s15
	s_nop 0
	global_load_lds_dwordx4 v132, s[48:49]
	s_waitcnt vmcnt(8)
	s_waitcnt lgkmcnt(0)
	s_barrier
	s_setprio 1
	v_mfma_f32_16x16x32_bf16 v[128:131], v[154:157], v[196:199], v[128:131]
	v_mfma_f32_16x16x32_bf16 v[124:127], v[172:175], v[196:199], v[124:127]
	v_mfma_f32_16x16x32_bf16 v[116:119], v[154:157], v[204:207], v[116:119]
	v_mfma_f32_16x16x32_bf16 v[108:111], v[172:175], v[204:207], v[108:111]
	v_mfma_f32_16x16x32_bf16 v[100:103], v[154:157], v[212:215], v[100:103]
	v_mfma_f32_16x16x32_bf16 v[92:95], v[172:175], v[212:215], v[92:95]
	v_mfma_f32_16x16x32_bf16 v[84:87], v[154:157], v[220:223], v[84:87]
	v_mfma_f32_16x16x32_bf16 v[76:79], v[172:175], v[220:223], v[76:79]
	v_mfma_f32_16x16x32_bf16 v[128:131], v[168:171], v[200:203], v[128:131]
	v_mfma_f32_16x16x32_bf16 v[124:127], v[176:179], v[200:203], v[124:127]
	v_mfma_f32_16x16x32_bf16 v[116:119], v[168:171], v[208:211], v[116:119]
	v_mfma_f32_16x16x32_bf16 v[108:111], v[176:179], v[208:211], v[108:111]
	v_mfma_f32_16x16x32_bf16 v[100:103], v[168:171], v[216:219], v[100:103]
	v_mfma_f32_16x16x32_bf16 v[92:95], v[176:179], v[216:219], v[92:95]
	v_mfma_f32_16x16x32_bf16 v[84:87], v[168:171], v[224:227], v[84:87]
	v_mfma_f32_16x16x32_bf16 v[76:79], v[176:179], v[224:227], v[76:79]
	v_mfma_f32_16x16x32_bf16 v[120:123], v[180:183], v[196:199], v[120:123]
	v_mfma_f32_16x16x32_bf16 v[112:115], v[188:191], v[196:199], v[112:115]
	v_mfma_f32_16x16x32_bf16 v[104:107], v[180:183], v[204:207], v[104:107]
	v_mfma_f32_16x16x32_bf16 v[96:99], v[188:191], v[204:207], v[96:99]
	v_mfma_f32_16x16x32_bf16 v[88:91], v[180:183], v[212:215], v[88:91]
	v_mfma_f32_16x16x32_bf16 v[80:83], v[188:191], v[212:215], v[80:83]
	v_mfma_f32_16x16x32_bf16 v[72:75], v[180:183], v[220:223], v[72:75]
	v_mfma_f32_16x16x32_bf16 v[68:71], v[188:191], v[220:223], v[68:71]
	v_mfma_f32_16x16x32_bf16 v[120:123], v[184:187], v[200:203], v[120:123]
	v_mfma_f32_16x16x32_bf16 v[112:115], v[192:195], v[200:203], v[112:115]
	v_mfma_f32_16x16x32_bf16 v[104:107], v[184:187], v[208:211], v[104:107]
	v_mfma_f32_16x16x32_bf16 v[96:99], v[192:195], v[208:211], v[96:99]
	v_mfma_f32_16x16x32_bf16 v[88:91], v[184:187], v[216:219], v[88:91]
	v_mfma_f32_16x16x32_bf16 v[80:83], v[192:195], v[216:219], v[80:83]
	v_mfma_f32_16x16x32_bf16 v[72:75], v[184:187], v[224:227], v[72:75]
	v_mfma_f32_16x16x32_bf16 v[68:71], v[192:195], v[224:227], v[68:71]
	s_barrier
	s_setprio 0
	s_add_i32 s33, s33, s10
	s_mov_b32 m0, s33
	ds_read_b128 v[196:199], v167 offset:49152
	ds_read_b128 v[200:203], v167 offset:50176
	ds_read_b128 v[204:207], v167 offset:51200
	ds_read_b128 v[208:211], v167 offset:52224
	ds_read_b128 v[212:215], v167 offset:53248
	ds_read_b128 v[216:219], v167 offset:54272
	ds_read_b128 v[220:223], v167 offset:55296
	ds_read_b128 v[224:227], v167 offset:56320
	s_add_u32 s100, s46, 0x80
	s_addc_u32 s101, s47, 0
	global_load_lds_dwordx4 v2, s[100:101]
	s_add_i32 m0, s33, 0x2000
	s_add_u32 s46, s46, 0x80080
	s_addc_u32 s47, s47, 0
	s_add_i32 s33, s43, s10
	s_add_u32 s100, s46, 0xfff80000
	s_addc_u32 s101, s47, -1
	global_load_lds_dwordx4 v0, s[100:101]
	s_mov_b32 m0, s33
	s_nop 0
	global_load_lds_dwordx4 v2, s[46:47]
	s_add_i32 m0, s33, 0x2000
	s_nop 0
	global_load_lds_dwordx4 v0, s[46:47]
	s_mov_b32 m0, s16
	s_nop 0
	s_add_u32 s100, s48, 0xfff80080
	s_addc_u32 s101, s49, -1
	global_load_lds_dwordx4 v134, s[100:101]
	s_mov_b32 m0, s17
	s_nop 0
	s_add_u32 s100, s48, 0xfff80080
	s_addc_u32 s101, s49, -1
	global_load_lds_dwordx4 v132, s[100:101]
	s_waitcnt vmcnt(8)
	s_waitcnt lgkmcnt(0)
	s_barrier
	s_setprio 1
	v_mfma_f32_16x16x32_bf16 v[64:67], v[154:157], v[196:199], v[64:67]
	v_mfma_f32_16x16x32_bf16 v[60:63], v[172:175], v[196:199], v[60:63]
	v_mfma_f32_16x16x32_bf16 v[52:55], v[154:157], v[204:207], v[52:55]
	v_mfma_f32_16x16x32_bf16 v[44:47], v[172:175], v[204:207], v[44:47]
	v_mfma_f32_16x16x32_bf16 v[36:39], v[154:157], v[212:215], v[36:39]
	v_mfma_f32_16x16x32_bf16 v[28:31], v[172:175], v[212:215], v[28:31]
	v_mfma_f32_16x16x32_bf16 v[20:23], v[154:157], v[220:223], v[20:23]
	v_mfma_f32_16x16x32_bf16 v[12:15], v[172:175], v[220:223], v[12:15]
	v_mfma_f32_16x16x32_bf16 v[64:67], v[168:171], v[200:203], v[64:67]
	v_mfma_f32_16x16x32_bf16 v[60:63], v[176:179], v[200:203], v[60:63]
	v_mfma_f32_16x16x32_bf16 v[52:55], v[168:171], v[208:211], v[52:55]
	v_mfma_f32_16x16x32_bf16 v[44:47], v[176:179], v[208:211], v[44:47]
	v_mfma_f32_16x16x32_bf16 v[36:39], v[168:171], v[216:219], v[36:39]
	v_mfma_f32_16x16x32_bf16 v[28:31], v[176:179], v[216:219], v[28:31]
	v_mfma_f32_16x16x32_bf16 v[20:23], v[168:171], v[224:227], v[20:23]
	v_mfma_f32_16x16x32_bf16 v[12:15], v[176:179], v[224:227], v[12:15]
	v_mfma_f32_16x16x32_bf16 v[56:59], v[180:183], v[196:199], v[56:59]
	v_mfma_f32_16x16x32_bf16 v[48:51], v[188:191], v[196:199], v[48:51]
	v_mfma_f32_16x16x32_bf16 v[40:43], v[180:183], v[204:207], v[40:43]
	v_mfma_f32_16x16x32_bf16 v[32:35], v[188:191], v[204:207], v[32:35]
	v_mfma_f32_16x16x32_bf16 v[24:27], v[180:183], v[212:215], v[24:27]
	v_mfma_f32_16x16x32_bf16 v[16:19], v[188:191], v[212:215], v[16:19]
	v_mfma_f32_16x16x32_bf16 v[8:11], v[180:183], v[220:223], v[8:11]
	v_mfma_f32_16x16x32_bf16 v[4:7], v[188:191], v[220:223], v[4:7]
	v_mfma_f32_16x16x32_bf16 v[56:59], v[184:187], v[200:203], v[56:59]
	v_mfma_f32_16x16x32_bf16 v[48:51], v[192:195], v[200:203], v[48:51]
	v_mfma_f32_16x16x32_bf16 v[40:43], v[184:187], v[208:211], v[40:43]
	v_mfma_f32_16x16x32_bf16 v[32:35], v[192:195], v[208:211], v[32:35]
	v_mfma_f32_16x16x32_bf16 v[24:27], v[184:187], v[216:219], v[24:27]
	v_mfma_f32_16x16x32_bf16 v[16:19], v[192:195], v[216:219], v[16:19]
	v_mfma_f32_16x16x32_bf16 v[8:11], v[184:187], v[224:227], v[8:11]
	v_mfma_f32_16x16x32_bf16 v[4:7], v[192:195], v[224:227], v[4:7]
	s_barrier
	s_setprio 0
	s_add_i32 s35, s35, 2
	s_add_u32 s31, s31, 0x100
	s_addc_u32 s34, s34, 0
	s_add_u32 s44, s44, 0x100
	s_addc_u32 s45, s45, 0
	s_cmp_gt_u32 s35, 29
	s_cbranch_scc0 .LBB0_342
	s_and_b64 vcc, exec, s[22:23]
	s_cbranch_vccz .LBB0_345
	s_nop 0

.LBB0_740:
	s_mov_b32 s48, s6
	s_ashr_i32 s49, s6, 31
	s_mov_b32 s94, s7
	s_lshl_b64 s[6:7], s[48:49], 20
	s_add_u32 s56, s70, s6
	s_addc_u32 s57, s71, s7
	s_and_b64 s[6:7], exec, s[52:53]
	s_mov_b32 s50, s5
	s_cselect_b32 s5, s57, s39
	s_cselect_b32 s6, s56, s38
	s_add_u32 s60, s80, s60
	s_addc_u32 s61, s81, s61
	s_mov_b32 s67, s8
	s_and_b64 s[8:9], exec, s[52:53]
	s_cselect_b32 s7, s61, s37
	s_cselect_b32 s8, s60, s36
	s_add_u32 s9, s36, 0x100
	s_addc_u32 s10, s37, 0
	s_add_u32 s36, s38, 0x80080
	s_addc_u32 s37, s39, 0
	s_mov_b32 s11, -2
	s_waitcnt lgkmcnt(0)
	s_add_u32 s12, s36, 0xfff80080
	s_addc_u32 s13, s37, -1
	s_add_i32 s14, 0, 0x10000
	s_cmp_eq_u32 s11, 28
	s_cselect_b32 s63, s5, s13
	s_cselect_b32 s62, s6, s12
	s_cselect_b32 s39, s7, s10
	s_cselect_b32 s38, s8, s9
	s_add_i32 s15, 0, 0x14000
	v_add_u32_e32 v144, s14, v230
	v_add_u32_e32 v160, s15, v230
	ds_read_b128 v[124:127], v144
	ds_read_b128 v[128:131], v144 offset:1024
	ds_read_b128 v[136:139], v144 offset:2048
	ds_read_b128 v[144:147], v144 offset:3072
	ds_read_b128 v[148:151], v160
	ds_read_b128 v[152:155], v160 offset:1024
	ds_read_b128 v[156:159], v160 offset:2048
	ds_read_b128 v[160:163], v160 offset:3072
	v_lshl_add_u64 v[196:197], s[36:37], 0, v[222:223]
	s_add_i32 m0, s21, 0xc000
	ds_read_b128 v[164:167], v243
	ds_read_b128 v[168:171], v243 offset:1024
	ds_read_b128 v[172:175], v243 offset:2048
	ds_read_b128 v[176:179], v243 offset:3072
	ds_read_b128 v[180:183], v243 offset:4096
	ds_read_b128 v[184:187], v243 offset:5120
	ds_read_b128 v[188:191], v243 offset:6144
	ds_read_b128 v[192:195], v243 offset:7168
	global_load_lds_dwordx4 v[196:197], off
	v_lshl_add_u64 v[196:197], s[36:37], 0, v[220:221]
	s_add_i32 m0, s21, 0xe000
	s_nop 0
	global_load_lds_dwordx4 v[196:197], off
	s_waitcnt vmcnt(8)
	s_waitcnt lgkmcnt(0)
	s_barrier
	s_setprio 1
	v_mfma_f32_16x16x32_bf16 v[140:143], v[124:127], v[164:167], 0
	v_mfma_f32_16x16x32_bf16 v[132:135], v[136:139], v[164:167], 0
	v_mfma_f32_16x16x32_bf16 v[112:115], v[124:127], v[172:175], 0
	v_mfma_f32_16x16x32_bf16 v[108:111], v[136:139], v[172:175], 0
	v_mfma_f32_16x16x32_bf16 v[96:99], v[124:127], v[180:183], 0
	v_mfma_f32_16x16x32_bf16 v[92:95], v[136:139], v[180:183], 0
	v_mfma_f32_16x16x32_bf16 v[80:83], v[124:127], v[188:191], 0
	v_mfma_f32_16x16x32_bf16 v[76:79], v[136:139], v[188:191], 0
	v_mfma_f32_16x16x32_bf16 v[140:143], v[128:131], v[168:171], v[140:143]
	v_mfma_f32_16x16x32_bf16 v[132:135], v[144:147], v[168:171], v[132:135]
	v_mfma_f32_16x16x32_bf16 v[112:115], v[128:131], v[176:179], v[112:115]
	v_mfma_f32_16x16x32_bf16 v[108:111], v[144:147], v[176:179], v[108:111]
	v_mfma_f32_16x16x32_bf16 v[96:99], v[128:131], v[184:187], v[96:99]
	v_mfma_f32_16x16x32_bf16 v[92:95], v[144:147], v[184:187], v[92:95]
	v_mfma_f32_16x16x32_bf16 v[80:83], v[128:131], v[192:195], v[80:83]
	v_mfma_f32_16x16x32_bf16 v[76:79], v[144:147], v[192:195], v[76:79]
	s_setprio 0
	s_setprio 1
	v_mfma_f32_16x16x32_bf16 v[120:123], v[148:151], v[164:167], 0
	v_mfma_f32_16x16x32_bf16 v[116:119], v[156:159], v[164:167], 0
	v_mfma_f32_16x16x32_bf16 v[104:107], v[148:151], v[172:175], 0
	v_mfma_f32_16x16x32_bf16 v[100:103], v[156:159], v[172:175], 0
	v_mfma_f32_16x16x32_bf16 v[88:91], v[148:151], v[180:183], 0
	v_mfma_f32_16x16x32_bf16 v[84:87], v[156:159], v[180:183], 0
	v_mfma_f32_16x16x32_bf16 v[72:75], v[148:151], v[188:191], 0
	v_mfma_f32_16x16x32_bf16 v[68:71], v[156:159], v[188:191], 0
	v_mfma_f32_16x16x32_bf16 v[120:123], v[152:155], v[168:171], v[120:123]
	v_mfma_f32_16x16x32_bf16 v[116:119], v[160:163], v[168:171], v[116:119]
	v_mfma_f32_16x16x32_bf16 v[104:107], v[152:155], v[176:179], v[104:107]
	v_mfma_f32_16x16x32_bf16 v[100:103], v[160:163], v[176:179], v[100:103]
	v_mfma_f32_16x16x32_bf16 v[88:91], v[152:155], v[184:187], v[88:91]
	v_mfma_f32_16x16x32_bf16 v[84:87], v[160:163], v[184:187], v[84:87]
	v_mfma_f32_16x16x32_bf16 v[72:75], v[152:155], v[192:195], v[72:75]
	v_mfma_f32_16x16x32_bf16 v[68:71], v[160:163], v[192:195], v[68:71]
	s_barrier
	s_setprio 0
	s_add_i32 s12, s14, s82
	v_lshl_add_u64 v[196:197], s[38:39], 0, v[2:3]
	s_mov_b32 m0, s12
	ds_read_b128 v[164:167], v243 offset:16384
	ds_read_b128 v[168:171], v243 offset:17408
	ds_read_b128 v[172:175], v243 offset:18432
	ds_read_b128 v[176:179], v243 offset:19456
	ds_read_b128 v[180:183], v243 offset:20480
	ds_read_b128 v[184:187], v243 offset:21504
	ds_read_b128 v[188:191], v243 offset:22528
	ds_read_b128 v[192:195], v243 offset:23552
	global_load_lds_dwordx4 v[196:197], off
	s_add_i32 m0, s12, 0x2000
	s_add_u32 s12, s38, 0x80000
	v_lshl_add_u64 v[198:199], s[38:39], 0, v[218:219]
	s_addc_u32 s13, s39, 0
	s_add_i32 s14, s15, s82
	global_load_lds_dwordx4 v[198:199], off
	v_lshl_add_u64 v[200:201], s[12:13], 0, v[2:3]
	s_mov_b32 m0, s14
	v_lshl_add_u64 v[202:203], s[62:63], 0, v[216:217]
	global_load_lds_dwordx4 v[200:201], off
	v_lshl_add_u64 v[200:201], s[12:13], 0, v[218:219]
	s_add_i32 m0, s14, 0x2000
	s_nop 0
	global_load_lds_dwordx4 v[200:201], off
	v_lshl_add_u64 v[200:201], s[62:63], 0, v[0:1]
	s_mov_b32 m0, s21
	s_nop 0
	global_load_lds_dwordx4 v[200:201], off
	s_mov_b32 m0, s83
	s_nop 0
	global_load_lds_dwordx4 v[202:203], off
	s_waitcnt vmcnt(8)
	s_waitcnt lgkmcnt(0)
	s_barrier
	s_setprio 1
	v_mfma_f32_16x16x32_bf16 v[64:67], v[124:127], v[164:167], 0
	v_mfma_f32_16x16x32_bf16 v[60:63], v[136:139], v[164:167], 0
	v_mfma_f32_16x16x32_bf16 v[48:51], v[124:127], v[172:175], 0
	v_mfma_f32_16x16x32_bf16 v[44:47], v[136:139], v[172:175], 0
	v_mfma_f32_16x16x32_bf16 v[32:35], v[124:127], v[180:183], 0
	v_mfma_f32_16x16x32_bf16 v[28:31], v[136:139], v[180:183], 0
	v_mfma_f32_16x16x32_bf16 v[16:19], v[124:127], v[188:191], 0
	v_mfma_f32_16x16x32_bf16 v[12:15], v[136:139], v[188:191], 0
	v_mfma_f32_16x16x32_bf16 v[64:67], v[128:131], v[168:171], v[64:67]
	v_mfma_f32_16x16x32_bf16 v[60:63], v[144:147], v[168:171], v[60:63]
	v_mfma_f32_16x16x32_bf16 v[48:51], v[128:131], v[176:179], v[48:51]
	v_mfma_f32_16x16x32_bf16 v[44:47], v[144:147], v[176:179], v[44:47]
	v_mfma_f32_16x16x32_bf16 v[32:35], v[128:131], v[184:187], v[32:35]
	v_mfma_f32_16x16x32_bf16 v[28:31], v[144:147], v[184:187], v[28:31]
	v_mfma_f32_16x16x32_bf16 v[16:19], v[128:131], v[192:195], v[16:19]
	v_mfma_f32_16x16x32_bf16 v[12:15], v[144:147], v[192:195], v[12:15]
	s_setprio 0
	s_setprio 1
	v_mfma_f32_16x16x32_bf16 v[56:59], v[148:151], v[164:167], 0
	v_mfma_f32_16x16x32_bf16 v[52:55], v[156:159], v[164:167], 0
	v_mfma_f32_16x16x32_bf16 v[40:43], v[148:151], v[172:175], 0
	v_mfma_f32_16x16x32_bf16 v[36:39], v[156:159], v[172:175], 0
	v_mfma_f32_16x16x32_bf16 v[24:27], v[148:151], v[180:183], 0
	v_mfma_f32_16x16x32_bf16 v[20:23], v[156:159], v[180:183], 0
	v_mfma_f32_16x16x32_bf16 v[8:11], v[148:151], v[188:191], 0
	v_mfma_f32_16x16x32_bf16 v[4:7], v[156:159], v[188:191], 0
	v_mfma_f32_16x16x32_bf16 v[56:59], v[152:155], v[168:171], v[56:59]
	v_mfma_f32_16x16x32_bf16 v[52:55], v[160:163], v[168:171], v[52:55]
	v_mfma_f32_16x16x32_bf16 v[40:43], v[152:155], v[176:179], v[40:43]
	v_mfma_f32_16x16x32_bf16 v[36:39], v[160:163], v[176:179], v[36:39]
	v_mfma_f32_16x16x32_bf16 v[24:27], v[152:155], v[184:187], v[24:27]
	v_mfma_f32_16x16x32_bf16 v[20:23], v[160:163], v[184:187], v[20:23]
	v_mfma_f32_16x16x32_bf16 v[8:11], v[152:155], v[192:195], v[8:11]
	v_mfma_f32_16x16x32_bf16 v[4:7], v[160:163], v[192:195], v[4:7]
	s_barrier
	s_setprio 0
	s_add_i32 s14, 0, 0x18000
	s_add_i32 s15, 0, 0x1c000
	v_add_u32_e32 v144, s14, v230
	v_add_u32_e32 v160, s15, v230
	ds_read_b128 v[124:127], v144
	ds_read_b128 v[128:131], v144 offset:1024
	ds_read_b128 v[136:139], v144 offset:2048
	ds_read_b128 v[144:147], v144 offset:3072
	ds_read_b128 v[148:151], v160
	ds_read_b128 v[152:155], v160 offset:1024
	ds_read_b128 v[156:159], v160 offset:2048
	ds_read_b128 v[160:163], v160 offset:3072
	s_add_u32 s12, s62, 0x80000
	s_addc_u32 s13, s63, 0
	s_mov_b32 m0, s84
	v_lshl_add_u64 v[204:205], s[12:13], 0, v[0:1]
	ds_read_b128 v[164:167], v243 offset:32768
	ds_read_b128 v[168:171], v243 offset:33792
	ds_read_b128 v[172:175], v243 offset:34816
	ds_read_b128 v[176:179], v243 offset:35840
	ds_read_b128 v[180:183], v243 offset:36864
	ds_read_b128 v[184:187], v243 offset:37888
	ds_read_b128 v[188:191], v243 offset:38912
	ds_read_b128 v[192:195], v243 offset:39936
	global_load_lds_dwordx4 v[204:205], off
	v_lshl_add_u64 v[204:205], s[12:13], 0, v[216:217]
	s_mov_b32 m0, s85
	s_nop 0
	global_load_lds_dwordx4 v[204:205], off
	s_waitcnt vmcnt(8)
	s_waitcnt lgkmcnt(0)
	s_barrier
	s_setprio 1
	v_mfma_f32_16x16x32_bf16 v[140:143], v[124:127], v[164:167], v[140:143]
	v_mfma_f32_16x16x32_bf16 v[132:135], v[136:139], v[164:167], v[132:135]
	v_mfma_f32_16x16x32_bf16 v[112:115], v[124:127], v[172:175], v[112:115]
	v_mfma_f32_16x16x32_bf16 v[108:111], v[136:139], v[172:175], v[108:111]
	v_mfma_f32_16x16x32_bf16 v[96:99], v[124:127], v[180:183], v[96:99]
	v_mfma_f32_16x16x32_bf16 v[92:95], v[136:139], v[180:183], v[92:95]
	v_mfma_f32_16x16x32_bf16 v[80:83], v[124:127], v[188:191], v[80:83]
	v_mfma_f32_16x16x32_bf16 v[76:79], v[136:139], v[188:191], v[76:79]
	v_mfma_f32_16x16x32_bf16 v[140:143], v[128:131], v[168:171], v[140:143]
	v_mfma_f32_16x16x32_bf16 v[132:135], v[144:147], v[168:171], v[132:135]
	v_mfma_f32_16x16x32_bf16 v[112:115], v[128:131], v[176:179], v[112:115]
	v_mfma_f32_16x16x32_bf16 v[108:111], v[144:147], v[176:179], v[108:111]
	v_mfma_f32_16x16x32_bf16 v[96:99], v[128:131], v[184:187], v[96:99]
	v_mfma_f32_16x16x32_bf16 v[92:95], v[144:147], v[184:187], v[92:95]
	v_mfma_f32_16x16x32_bf16 v[80:83], v[128:131], v[192:195], v[80:83]
	v_mfma_f32_16x16x32_bf16 v[76:79], v[144:147], v[192:195], v[76:79]
	s_setprio 0
	s_setprio 1
	v_mfma_f32_16x16x32_bf16 v[120:123], v[148:151], v[164:167], v[120:123]
	v_mfma_f32_16x16x32_bf16 v[116:119], v[156:159], v[164:167], v[116:119]
	v_mfma_f32_16x16x32_bf16 v[104:107], v[148:151], v[172:175], v[104:107]
	v_mfma_f32_16x16x32_bf16 v[100:103], v[156:159], v[172:175], v[100:103]
	v_mfma_f32_16x16x32_bf16 v[88:91], v[148:151], v[180:183], v[88:91]
	v_mfma_f32_16x16x32_bf16 v[84:87], v[156:159], v[180:183], v[84:87]
	v_mfma_f32_16x16x32_bf16 v[72:75], v[148:151], v[188:191], v[72:75]
	v_mfma_f32_16x16x32_bf16 v[68:71], v[156:159], v[188:191], v[68:71]
	v_mfma_f32_16x16x32_bf16 v[120:123], v[152:155], v[168:171], v[120:123]
	v_mfma_f32_16x16x32_bf16 v[116:119], v[160:163], v[168:171], v[116:119]
	v_mfma_f32_16x16x32_bf16 v[104:107], v[152:155], v[176:179], v[104:107]
	v_mfma_f32_16x16x32_bf16 v[100:103], v[160:163], v[176:179], v[100:103]
	v_mfma_f32_16x16x32_bf16 v[88:91], v[152:155], v[184:187], v[88:91]
	v_mfma_f32_16x16x32_bf16 v[84:87], v[160:163], v[184:187], v[84:87]
	v_mfma_f32_16x16x32_bf16 v[72:75], v[152:155], v[192:195], v[72:75]
	v_mfma_f32_16x16x32_bf16 v[68:71], v[160:163], v[192:195], v[68:71]
	s_barrier
	s_setprio 0
	s_add_i32 s12, s14, s82
	v_lshl_add_u64 v[196:197], v[196:197], 0, s[68:69]
	s_mov_b32 m0, s12
	ds_read_b128 v[164:167], v243 offset:49152
	ds_read_b128 v[168:171], v243 offset:50176
	ds_read_b128 v[172:175], v243 offset:51200
	ds_read_b128 v[176:179], v243 offset:52224
	ds_read_b128 v[180:183], v243 offset:53248
	ds_read_b128 v[184:187], v243 offset:54272
	ds_read_b128 v[188:191], v243 offset:55296
	ds_read_b128 v[192:195], v243 offset:56320
	global_load_lds_dwordx4 v[196:197], off
	s_add_i32 m0, s12, 0x2000
	s_add_u32 s12, s38, 0x80080
	v_lshl_add_u64 v[196:197], v[198:199], 0, s[68:69]
	s_addc_u32 s13, s39, 0
	s_add_i32 s14, s15, s82
	global_load_lds_dwordx4 v[196:197], off
	v_lshl_add_u64 v[196:197], s[12:13], 0, v[2:3]
	s_mov_b32 m0, s14
	s_nop 0
	global_load_lds_dwordx4 v[196:197], off
	v_lshl_add_u64 v[196:197], s[12:13], 0, v[218:219]
	s_add_i32 m0, s14, 0x2000
	s_nop 0
	global_load_lds_dwordx4 v[196:197], off
	v_lshl_add_u64 v[196:197], v[200:201], 0, s[68:69]
	s_mov_b32 m0, s89
	s_nop 0
	global_load_lds_dwordx4 v[196:197], off
	v_lshl_add_u64 v[196:197], v[202:203], 0, s[68:69]
	s_mov_b32 m0, s90
	s_nop 0
	global_load_lds_dwordx4 v[196:197], off
	s_waitcnt vmcnt(8)
	s_waitcnt lgkmcnt(0)
	s_barrier
	s_setprio 1
	v_mfma_f32_16x16x32_bf16 v[64:67], v[124:127], v[164:167], v[64:67]
	v_mfma_f32_16x16x32_bf16 v[60:63], v[136:139], v[164:167], v[60:63]
	v_mfma_f32_16x16x32_bf16 v[48:51], v[124:127], v[172:175], v[48:51]
	v_mfma_f32_16x16x32_bf16 v[44:47], v[136:139], v[172:175], v[44:47]
	v_mfma_f32_16x16x32_bf16 v[32:35], v[124:127], v[180:183], v[32:35]
	v_mfma_f32_16x16x32_bf16 v[28:31], v[136:139], v[180:183], v[28:31]
	v_mfma_f32_16x16x32_bf16 v[16:19], v[124:127], v[188:191], v[16:19]
	v_mfma_f32_16x16x32_bf16 v[12:15], v[136:139], v[188:191], v[12:15]
	v_mfma_f32_16x16x32_bf16 v[64:67], v[128:131], v[168:171], v[64:67]
	v_mfma_f32_16x16x32_bf16 v[60:63], v[144:147], v[168:171], v[60:63]
	v_mfma_f32_16x16x32_bf16 v[48:51], v[128:131], v[176:179], v[48:51]
	v_mfma_f32_16x16x32_bf16 v[44:47], v[144:147], v[176:179], v[44:47]
	v_mfma_f32_16x16x32_bf16 v[32:35], v[128:131], v[184:187], v[32:35]
	v_mfma_f32_16x16x32_bf16 v[28:31], v[144:147], v[184:187], v[28:31]
	v_mfma_f32_16x16x32_bf16 v[16:19], v[128:131], v[192:195], v[16:19]
	v_mfma_f32_16x16x32_bf16 v[12:15], v[144:147], v[192:195], v[12:15]
	s_setprio 0
	s_setprio 1
	v_mfma_f32_16x16x32_bf16 v[56:59], v[148:151], v[164:167], v[56:59]
	v_mfma_f32_16x16x32_bf16 v[52:55], v[156:159], v[164:167], v[52:55]
	v_mfma_f32_16x16x32_bf16 v[40:43], v[148:151], v[172:175], v[40:43]
	v_mfma_f32_16x16x32_bf16 v[36:39], v[156:159], v[172:175], v[36:39]
	v_mfma_f32_16x16x32_bf16 v[24:27], v[148:151], v[180:183], v[24:27]
	v_mfma_f32_16x16x32_bf16 v[20:23], v[156:159], v[180:183], v[20:23]
	v_mfma_f32_16x16x32_bf16 v[8:11], v[148:151], v[188:191], v[8:11]
	v_mfma_f32_16x16x32_bf16 v[4:7], v[156:159], v[188:191], v[4:7]
	v_mfma_f32_16x16x32_bf16 v[56:59], v[152:155], v[168:171], v[56:59]
	v_mfma_f32_16x16x32_bf16 v[52:55], v[160:163], v[168:171], v[52:55]
	v_mfma_f32_16x16x32_bf16 v[40:43], v[152:155], v[176:179], v[40:43]
	v_mfma_f32_16x16x32_bf16 v[36:39], v[160:163], v[176:179], v[36:39]
	v_mfma_f32_16x16x32_bf16 v[24:27], v[152:155], v[184:187], v[24:27]
	v_mfma_f32_16x16x32_bf16 v[20:23], v[160:163], v[184:187], v[20:23]
	v_mfma_f32_16x16x32_bf16 v[8:11], v[152:155], v[192:195], v[8:11]
	v_mfma_f32_16x16x32_bf16 v[4:7], v[160:163], v[192:195], v[4:7]
	s_barrier
	s_setprio 0
	s_add_i32 s11, s11, 2
	s_add_u32 s9, s9, 0x100
	s_addc_u32 s10, s10, 0
	s_add_u32 s36, s36, 0x100
	s_addc_u32 s37, s37, 0
	s_cmp_gt_u32 s11, 29
.LBB0_741:
	s_add_u32 s12, s36, 0xfff80080
	s_addc_u32 s13, s37, -1
	s_add_i32 s14, 0, 0x10000
	s_cmp_eq_u32 s11, 28
	s_cselect_b32 s63, s5, s13
	s_cselect_b32 s62, s6, s12
	s_cselect_b32 s39, s7, s10
	s_cselect_b32 s38, s8, s9
	s_add_i32 s15, 0, 0x14000
	v_add_u32_e32 v144, s14, v230
	v_add_u32_e32 v160, s15, v230
	ds_read_b128 v[124:127], v144
	ds_read_b128 v[128:131], v144 offset:1024
	ds_read_b128 v[136:139], v144 offset:2048
	ds_read_b128 v[144:147], v144 offset:3072
	ds_read_b128 v[148:151], v160
	ds_read_b128 v[152:155], v160 offset:1024
	ds_read_b128 v[156:159], v160 offset:2048
	ds_read_b128 v[160:163], v160 offset:3072
	v_lshl_add_u64 v[196:197], s[36:37], 0, v[222:223]
	s_add_i32 m0, s21, 0xc000
	ds_read_b128 v[164:167], v243
	ds_read_b128 v[168:171], v243 offset:1024
	ds_read_b128 v[172:175], v243 offset:2048
	ds_read_b128 v[176:179], v243 offset:3072
	ds_read_b128 v[180:183], v243 offset:4096
	ds_read_b128 v[184:187], v243 offset:5120
	ds_read_b128 v[188:191], v243 offset:6144
	ds_read_b128 v[192:195], v243 offset:7168
	global_load_lds_dwordx4 v[196:197], off
	v_lshl_add_u64 v[196:197], s[36:37], 0, v[220:221]
	s_add_i32 m0, s21, 0xe000
	s_nop 0
	global_load_lds_dwordx4 v[196:197], off
	s_waitcnt vmcnt(8)
	s_waitcnt lgkmcnt(0)
	s_barrier
	s_setprio 1
	v_mfma_f32_16x16x32_bf16 v[140:143], v[124:127], v[164:167], v[140:143]
	v_mfma_f32_16x16x32_bf16 v[132:135], v[136:139], v[164:167], v[132:135]
	v_mfma_f32_16x16x32_bf16 v[112:115], v[124:127], v[172:175], v[112:115]
	v_mfma_f32_16x16x32_bf16 v[108:111], v[136:139], v[172:175], v[108:111]
	v_mfma_f32_16x16x32_bf16 v[96:99], v[124:127], v[180:183], v[96:99]
	v_mfma_f32_16x16x32_bf16 v[92:95], v[136:139], v[180:183], v[92:95]
	v_mfma_f32_16x16x32_bf16 v[80:83], v[124:127], v[188:191], v[80:83]
	v_mfma_f32_16x16x32_bf16 v[76:79], v[136:139], v[188:191], v[76:79]
	v_mfma_f32_16x16x32_bf16 v[140:143], v[128:131], v[168:171], v[140:143]
	v_mfma_f32_16x16x32_bf16 v[132:135], v[144:147], v[168:171], v[132:135]
	v_mfma_f32_16x16x32_bf16 v[112:115], v[128:131], v[176:179], v[112:115]
	v_mfma_f32_16x16x32_bf16 v[108:111], v[144:147], v[176:179], v[108:111]
	v_mfma_f32_16x16x32_bf16 v[96:99], v[128:131], v[184:187], v[96:99]
	v_mfma_f32_16x16x32_bf16 v[92:95], v[144:147], v[184:187], v[92:95]
	v_mfma_f32_16x16x32_bf16 v[80:83], v[128:131], v[192:195], v[80:83]
	v_mfma_f32_16x16x32_bf16 v[76:79], v[144:147], v[192:195], v[76:79]
	s_setprio 0
	s_setprio 1
	v_mfma_f32_16x16x32_bf16 v[120:123], v[148:151], v[164:167], v[120:123]
	v_mfma_f32_16x16x32_bf16 v[116:119], v[156:159], v[164:167], v[116:119]
	v_mfma_f32_16x16x32_bf16 v[104:107], v[148:151], v[172:175], v[104:107]
	v_mfma_f32_16x16x32_bf16 v[100:103], v[156:159], v[172:175], v[100:103]
	v_mfma_f32_16x16x32_bf16 v[88:91], v[148:151], v[180:183], v[88:91]
	v_mfma_f32_16x16x32_bf16 v[84:87], v[156:159], v[180:183], v[84:87]
	v_mfma_f32_16x16x32_bf16 v[72:75], v[148:151], v[188:191], v[72:75]
	v_mfma_f32_16x16x32_bf16 v[68:71], v[156:159], v[188:191], v[68:71]
	v_mfma_f32_16x16x32_bf16 v[120:123], v[152:155], v[168:171], v[120:123]
	v_mfma_f32_16x16x32_bf16 v[116:119], v[160:163], v[168:171], v[116:119]
	v_mfma_f32_16x16x32_bf16 v[104:107], v[152:155], v[176:179], v[104:107]
	v_mfma_f32_16x16x32_bf16 v[100:103], v[160:163], v[176:179], v[100:103]
	v_mfma_f32_16x16x32_bf16 v[88:91], v[152:155], v[184:187], v[88:91]
	v_mfma_f32_16x16x32_bf16 v[84:87], v[160:163], v[184:187], v[84:87]
	v_mfma_f32_16x16x32_bf16 v[72:75], v[152:155], v[192:195], v[72:75]
	v_mfma_f32_16x16x32_bf16 v[68:71], v[160:163], v[192:195], v[68:71]
	s_barrier
	s_setprio 0
	s_add_i32 s12, s14, s82
	v_lshl_add_u64 v[196:197], s[38:39], 0, v[2:3]
	s_mov_b32 m0, s12
	ds_read_b128 v[164:167], v243 offset:16384
	ds_read_b128 v[168:171], v243 offset:17408
	ds_read_b128 v[172:175], v243 offset:18432
	ds_read_b128 v[176:179], v243 offset:19456
	ds_read_b128 v[180:183], v243 offset:20480
	ds_read_b128 v[184:187], v243 offset:21504
	ds_read_b128 v[188:191], v243 offset:22528
	ds_read_b128 v[192:195], v243 offset:23552
	global_load_lds_dwordx4 v[196:197], off
	s_add_i32 m0, s12, 0x2000
	s_add_u32 s12, s38, 0x80000
	v_lshl_add_u64 v[198:199], s[38:39], 0, v[218:219]
	s_addc_u32 s13, s39, 0
	s_add_i32 s14, s15, s82
	global_load_lds_dwordx4 v[198:199], off
	v_lshl_add_u64 v[200:201], s[12:13], 0, v[2:3]
	s_mov_b32 m0, s14
	v_lshl_add_u64 v[202:203], s[62:63], 0, v[216:217]
	global_load_lds_dwordx4 v[200:201], off
	v_lshl_add_u64 v[200:201], s[12:13], 0, v[218:219]
	s_add_i32 m0, s14, 0x2000
	s_nop 0
	global_load_lds_dwordx4 v[200:201], off
	v_lshl_add_u64 v[200:201], s[62:63], 0, v[0:1]
	s_mov_b32 m0, s21
	s_nop 0
	global_load_lds_dwordx4 v[200:201], off
	s_mov_b32 m0, s83
	s_nop 0
	global_load_lds_dwordx4 v[202:203], off
	s_waitcnt vmcnt(8)
	s_waitcnt lgkmcnt(0)
	s_barrier
	s_setprio 1
	v_mfma_f32_16x16x32_bf16 v[64:67], v[124:127], v[164:167], v[64:67]
	v_mfma_f32_16x16x32_bf16 v[60:63], v[136:139], v[164:167], v[60:63]
	v_mfma_f32_16x16x32_bf16 v[48:51], v[124:127], v[172:175], v[48:51]
	v_mfma_f32_16x16x32_bf16 v[44:47], v[136:139], v[172:175], v[44:47]
	v_mfma_f32_16x16x32_bf16 v[32:35], v[124:127], v[180:183], v[32:35]
	v_mfma_f32_16x16x32_bf16 v[28:31], v[136:139], v[180:183], v[28:31]
	v_mfma_f32_16x16x32_bf16 v[16:19], v[124:127], v[188:191], v[16:19]
	v_mfma_f32_16x16x32_bf16 v[12:15], v[136:139], v[188:191], v[12:15]
	v_mfma_f32_16x16x32_bf16 v[64:67], v[128:131], v[168:171], v[64:67]
	v_mfma_f32_16x16x32_bf16 v[60:63], v[144:147], v[168:171], v[60:63]
	v_mfma_f32_16x16x32_bf16 v[48:51], v[128:131], v[176:179], v[48:51]
	v_mfma_f32_16x16x32_bf16 v[44:47], v[144:147], v[176:179], v[44:47]
	v_mfma_f32_16x16x32_bf16 v[32:35], v[128:131], v[184:187], v[32:35]
	v_mfma_f32_16x16x32_bf16 v[28:31], v[144:147], v[184:187], v[28:31]
	v_mfma_f32_16x16x32_bf16 v[16:19], v[128:131], v[192:195], v[16:19]
	v_mfma_f32_16x16x32_bf16 v[12:15], v[144:147], v[192:195], v[12:15]
	s_setprio 0
	s_setprio 1
	v_mfma_f32_16x16x32_bf16 v[56:59], v[148:151], v[164:167], v[56:59]
	v_mfma_f32_16x16x32_bf16 v[52:55], v[156:159], v[164:167], v[52:55]
	v_mfma_f32_16x16x32_bf16 v[40:43], v[148:151], v[172:175], v[40:43]
	v_mfma_f32_16x16x32_bf16 v[36:39], v[156:159], v[172:175], v[36:39]
	v_mfma_f32_16x16x32_bf16 v[24:27], v[148:151], v[180:183], v[24:27]
	v_mfma_f32_16x16x32_bf16 v[20:23], v[156:159], v[180:183], v[20:23]
	v_mfma_f32_16x16x32_bf16 v[8:11], v[148:151], v[188:191], v[8:11]
	v_mfma_f32_16x16x32_bf16 v[4:7], v[156:159], v[188:191], v[4:7]
	v_mfma_f32_16x16x32_bf16 v[56:59], v[152:155], v[168:171], v[56:59]
	v_mfma_f32_16x16x32_bf16 v[52:55], v[160:163], v[168:171], v[52:55]
	v_mfma_f32_16x16x32_bf16 v[40:43], v[152:155], v[176:179], v[40:43]
	v_mfma_f32_16x16x32_bf16 v[36:39], v[160:163], v[176:179], v[36:39]
	v_mfma_f32_16x16x32_bf16 v[24:27], v[152:155], v[184:187], v[24:27]
	v_mfma_f32_16x16x32_bf16 v[20:23], v[160:163], v[184:187], v[20:23]
	v_mfma_f32_16x16x32_bf16 v[8:11], v[152:155], v[192:195], v[8:11]
	v_mfma_f32_16x16x32_bf16 v[4:7], v[160:163], v[192:195], v[4:7]
	s_barrier
	s_setprio 0
	s_add_i32 s14, 0, 0x18000
	s_add_i32 s15, 0, 0x1c000
	v_add_u32_e32 v144, s14, v230
	v_add_u32_e32 v160, s15, v230
	ds_read_b128 v[124:127], v144
	ds_read_b128 v[128:131], v144 offset:1024
	ds_read_b128 v[136:139], v144 offset:2048
	ds_read_b128 v[144:147], v144 offset:3072
	ds_read_b128 v[148:151], v160
	ds_read_b128 v[152:155], v160 offset:1024
	ds_read_b128 v[156:159], v160 offset:2048
	ds_read_b128 v[160:163], v160 offset:3072
	s_add_u32 s12, s62, 0x80000
	s_addc_u32 s13, s63, 0
	s_mov_b32 m0, s84
	v_lshl_add_u64 v[204:205], s[12:13], 0, v[0:1]
	ds_read_b128 v[164:167], v243 offset:32768
	ds_read_b128 v[168:171], v243 offset:33792
	ds_read_b128 v[172:175], v243 offset:34816
	ds_read_b128 v[176:179], v243 offset:35840
	ds_read_b128 v[180:183], v243 offset:36864
	ds_read_b128 v[184:187], v243 offset:37888
	ds_read_b128 v[188:191], v243 offset:38912
	ds_read_b128 v[192:195], v243 offset:39936
	global_load_lds_dwordx4 v[204:205], off
	v_lshl_add_u64 v[204:205], s[12:13], 0, v[216:217]
	s_mov_b32 m0, s85
	s_nop 0
	global_load_lds_dwordx4 v[204:205], off
	s_waitcnt vmcnt(8)
	s_waitcnt lgkmcnt(0)
	s_barrier
	s_setprio 1
	v_mfma_f32_16x16x32_bf16 v[140:143], v[124:127], v[164:167], v[140:143]
	v_mfma_f32_16x16x32_bf16 v[132:135], v[136:139], v[164:167], v[132:135]
	v_mfma_f32_16x16x32_bf16 v[112:115], v[124:127], v[172:175], v[112:115]
	v_mfma_f32_16x16x32_bf16 v[108:111], v[136:139], v[172:175], v[108:111]
	v_mfma_f32_16x16x32_bf16 v[96:99], v[124:127], v[180:183], v[96:99]
	v_mfma_f32_16x16x32_bf16 v[92:95], v[136:139], v[180:183], v[92:95]
	v_mfma_f32_16x16x32_bf16 v[80:83], v[124:127], v[188:191], v[80:83]
	v_mfma_f32_16x16x32_bf16 v[76:79], v[136:139], v[188:191], v[76:79]
	v_mfma_f32_16x16x32_bf16 v[140:143], v[128:131], v[168:171], v[140:143]
	v_mfma_f32_16x16x32_bf16 v[132:135], v[144:147], v[168:171], v[132:135]
	v_mfma_f32_16x16x32_bf16 v[112:115], v[128:131], v[176:179], v[112:115]
	v_mfma_f32_16x16x32_bf16 v[108:111], v[144:147], v[176:179], v[108:111]
	v_mfma_f32_16x16x32_bf16 v[96:99], v[128:131], v[184:187], v[96:99]
	v_mfma_f32_16x16x32_bf16 v[92:95], v[144:147], v[184:187], v[92:95]
	v_mfma_f32_16x16x32_bf16 v[80:83], v[128:131], v[192:195], v[80:83]
	v_mfma_f32_16x16x32_bf16 v[76:79], v[144:147], v[192:195], v[76:79]
	s_setprio 0
	s_setprio 1
	v_mfma_f32_16x16x32_bf16 v[120:123], v[148:151], v[164:167], v[120:123]
	v_mfma_f32_16x16x32_bf16 v[116:119], v[156:159], v[164:167], v[116:119]
	v_mfma_f32_16x16x32_bf16 v[104:107], v[148:151], v[172:175], v[104:107]
	v_mfma_f32_16x16x32_bf16 v[100:103], v[156:159], v[172:175], v[100:103]
	v_mfma_f32_16x16x32_bf16 v[88:91], v[148:151], v[180:183], v[88:91]
	v_mfma_f32_16x16x32_bf16 v[84:87], v[156:159], v[180:183], v[84:87]
	v_mfma_f32_16x16x32_bf16 v[72:75], v[148:151], v[188:191], v[72:75]
	v_mfma_f32_16x16x32_bf16 v[68:71], v[156:159], v[188:191], v[68:71]
	v_mfma_f32_16x16x32_bf16 v[120:123], v[152:155], v[168:171], v[120:123]
	v_mfma_f32_16x16x32_bf16 v[116:119], v[160:163], v[168:171], v[116:119]
	v_mfma_f32_16x16x32_bf16 v[104:107], v[152:155], v[176:179], v[104:107]
	v_mfma_f32_16x16x32_bf16 v[100:103], v[160:163], v[176:179], v[100:103]
	v_mfma_f32_16x16x32_bf16 v[88:91], v[152:155], v[184:187], v[88:91]
	v_mfma_f32_16x16x32_bf16 v[84:87], v[160:163], v[184:187], v[84:87]
	v_mfma_f32_16x16x32_bf16 v[72:75], v[152:155], v[192:195], v[72:75]
	v_mfma_f32_16x16x32_bf16 v[68:71], v[160:163], v[192:195], v[68:71]
	s_barrier
	s_setprio 0
	s_add_i32 s12, s14, s82
	v_lshl_add_u64 v[196:197], v[196:197], 0, s[68:69]
	s_mov_b32 m0, s12
	ds_read_b128 v[164:167], v243 offset:49152
	ds_read_b128 v[168:171], v243 offset:50176
	ds_read_b128 v[172:175], v243 offset:51200
	ds_read_b128 v[176:179], v243 offset:52224
	ds_read_b128 v[180:183], v243 offset:53248
	ds_read_b128 v[184:187], v243 offset:54272
	ds_read_b128 v[188:191], v243 offset:55296
	ds_read_b128 v[192:195], v243 offset:56320
	global_load_lds_dwordx4 v[196:197], off
	s_add_i32 m0, s12, 0x2000
	s_add_u32 s12, s38, 0x80080
	v_lshl_add_u64 v[196:197], v[198:199], 0, s[68:69]
	s_addc_u32 s13, s39, 0
	s_add_i32 s14, s15, s82
	global_load_lds_dwordx4 v[196:197], off
	v_lshl_add_u64 v[196:197], s[12:13], 0, v[2:3]
	s_mov_b32 m0, s14
	s_nop 0
	global_load_lds_dwordx4 v[196:197], off
	v_lshl_add_u64 v[196:197], s[12:13], 0, v[218:219]
	s_add_i32 m0, s14, 0x2000
	s_nop 0
	global_load_lds_dwordx4 v[196:197], off
	v_lshl_add_u64 v[196:197], v[200:201], 0, s[68:69]
	s_mov_b32 m0, s89
	s_nop 0
	global_load_lds_dwordx4 v[196:197], off
	v_lshl_add_u64 v[196:197], v[202:203], 0, s[68:69]
	s_mov_b32 m0, s90
	s_nop 0
	global_load_lds_dwordx4 v[196:197], off
	s_waitcnt vmcnt(8)
	s_waitcnt lgkmcnt(0)
	s_barrier
	s_setprio 1
	v_mfma_f32_16x16x32_bf16 v[64:67], v[124:127], v[164:167], v[64:67]
	v_mfma_f32_16x16x32_bf16 v[60:63], v[136:139], v[164:167], v[60:63]
	v_mfma_f32_16x16x32_bf16 v[48:51], v[124:127], v[172:175], v[48:51]
	v_mfma_f32_16x16x32_bf16 v[44:47], v[136:139], v[172:175], v[44:47]
	v_mfma_f32_16x16x32_bf16 v[32:35], v[124:127], v[180:183], v[32:35]
	v_mfma_f32_16x16x32_bf16 v[28:31], v[136:139], v[180:183], v[28:31]
	v_mfma_f32_16x16x32_bf16 v[16:19], v[124:127], v[188:191], v[16:19]
	v_mfma_f32_16x16x32_bf16 v[12:15], v[136:139], v[188:191], v[12:15]
	v_mfma_f32_16x16x32_bf16 v[64:67], v[128:131], v[168:171], v[64:67]
	v_mfma_f32_16x16x32_bf16 v[60:63], v[144:147], v[168:171], v[60:63]
	v_mfma_f32_16x16x32_bf16 v[48:51], v[128:131], v[176:179], v[48:51]
	v_mfma_f32_16x16x32_bf16 v[44:47], v[144:147], v[176:179], v[44:47]
	v_mfma_f32_16x16x32_bf16 v[32:35], v[128:131], v[184:187], v[32:35]
	v_mfma_f32_16x16x32_bf16 v[28:31], v[144:147], v[184:187], v[28:31]
	v_mfma_f32_16x16x32_bf16 v[16:19], v[128:131], v[192:195], v[16:19]
	v_mfma_f32_16x16x32_bf16 v[12:15], v[144:147], v[192:195], v[12:15]
	s_setprio 0
	s_setprio 1
	v_mfma_f32_16x16x32_bf16 v[56:59], v[148:151], v[164:167], v[56:59]
	v_mfma_f32_16x16x32_bf16 v[52:55], v[156:159], v[164:167], v[52:55]
	v_mfma_f32_16x16x32_bf16 v[40:43], v[148:151], v[172:175], v[40:43]
	v_mfma_f32_16x16x32_bf16 v[36:39], v[156:159], v[172:175], v[36:39]
	v_mfma_f32_16x16x32_bf16 v[24:27], v[148:151], v[180:183], v[24:27]
	v_mfma_f32_16x16x32_bf16 v[20:23], v[156:159], v[180:183], v[20:23]
	v_mfma_f32_16x16x32_bf16 v[8:11], v[148:151], v[188:191], v[8:11]
	v_mfma_f32_16x16x32_bf16 v[4:7], v[156:159], v[188:191], v[4:7]
	v_mfma_f32_16x16x32_bf16 v[56:59], v[152:155], v[168:171], v[56:59]
	v_mfma_f32_16x16x32_bf16 v[52:55], v[160:163], v[168:171], v[52:55]
	v_mfma_f32_16x16x32_bf16 v[40:43], v[152:155], v[176:179], v[40:43]
	v_mfma_f32_16x16x32_bf16 v[36:39], v[160:163], v[176:179], v[36:39]
	v_mfma_f32_16x16x32_bf16 v[24:27], v[152:155], v[184:187], v[24:27]
	v_mfma_f32_16x16x32_bf16 v[20:23], v[160:163], v[184:187], v[20:23]
	v_mfma_f32_16x16x32_bf16 v[8:11], v[152:155], v[192:195], v[8:11]
	v_mfma_f32_16x16x32_bf16 v[4:7], v[160:163], v[192:195], v[4:7]
	s_barrier
	s_setprio 0
	s_add_i32 s11, s11, 2
	s_add_u32 s9, s9, 0x100
	s_addc_u32 s10, s10, 0
	s_add_u32 s36, s36, 0x100
	s_addc_u32 s37, s37, 0
	s_cmp_gt_u32 s11, 29
	s_cbranch_scc0 .LBB0_741
	s_and_b64 vcc, exec, s[46:47]
	s_cbranch_vccz .LBB0_744
	s_barrier

.LBB0_853:
	v_and_b32_e32 v203, 15, v16
	v_bfe_u32 v201, v16, 4, 2
	s_and_b32 s5, s5, 3
	v_lshlrev_b32_e32 v16, 4, v201
	v_lshlrev_b32_e32 v202, 2, v203
	v_lshl_or_b32 v16, v203, 6, v16
	v_and_b32_e32 v19, 32, v202
	s_lshl_b32 s14, s8, 13
	s_lshl_b32 s15, s5, 12
	s_add_i32 m0, s10, 0x18000
	v_lshl_add_u64 v[10:11], v[10:11], 0, s[68:69]
	v_bitop3_b32 v140, v16, s15, v19 bitop3:0xde
	v_bitop3_b32 v16, v16, s14, v19 bitop3:0xde
	s_nop 0
	global_load_lds_dwordx4 v[10:11], off
	v_lshl_add_u64 v[8:9], v[8:9], 0, s[68:69]
	s_add_i32 m0, s10, 0x1a000
	s_add_i32 s14, s10, 0x8000
	s_add_i32 s15, s10, 0xa000
	global_load_lds_dwordx4 v[8:9], off
	v_lshl_add_u64 v[6:7], v[6:7], 0, s[68:69]
	s_mov_b32 m0, s14
	s_add_u32 s16, s20, 0x80080
	global_load_lds_dwordx4 v[6:7], off
	v_lshl_add_u64 v[4:5], v[4:5], 0, s[68:69]
	s_mov_b32 m0, s15
	s_addc_u32 s17, s21, 0
	global_load_lds_dwordx4 v[4:5], off
	s_add_i32 m0, s10, 0x1c000
	v_lshl_add_u64 v[4:5], s[16:17], 0, v[2:3]
	global_load_lds_dwordx4 v[4:5], off
	v_lshl_add_u64 v[4:5], s[16:17], 0, v[134:135]
	s_add_i32 m0, s10, 0x1e000
	v_readlane_b32 s16, v254, 25
	global_load_lds_dwordx4 v[4:5], off
	v_readlane_b32 s17, v254, 26
	s_add_u32 s16, s16, s24
	s_addc_u32 s17, s17, s25
	s_add_u32 s16, s2, s16
	s_addc_u32 s17, s3, s17
	s_and_b32 s18, s18, 7
	s_lshl_b32 s18, s18, 23
	s_lshl_b32 s19, s19, 20
	v_lshlrev_b32_e32 v4, 15, v15
	s_or_b32 s18, s18, s19
	v_and_b32_e32 v4, 0xffff0000, v4
	s_add_u32 s18, s2, s18
	v_lshl_add_u32 v4, v17, 12, v4
	v_and_b32_e32 v5, 1, v15
	s_addc_u32 s19, s3, 0
	v_lshl_or_b32 v4, v5, 6, v4
	s_add_u32 s24, s18, 0x22180080
	v_lshl_add_u32 v4, v18, 1, v4
	v_mov_b32_e32 v5, v3
	s_addc_u32 s25, s19, 0
	v_lshl_add_u64 v[136:137], s[24:25], 0, v[4:5]
	v_lshlrev_b32_e32 v4, 15, v12
	v_and_b32_e32 v4, 0xffff0000, v4
	v_lshl_add_u32 v4, v13, 12, v4
	v_and_b32_e32 v5, 1, v12
	v_lshl_or_b32 v4, v5, 6, v4
	s_waitcnt vmcnt(8)
	s_barrier
	s_waitcnt vmcnt(6)
	v_lshl_add_u32 v4, v14, 1, v4
	v_mov_b32_e32 v5, v3
	v_lshl_add_u64 v[138:139], s[24:25], 0, v[4:5]
	v_lshl_or_b32 v200, s8, 6, v203
	s_mov_b32 s28, -2
	s_mov_b64 s[24:25], 0
	v_add_u32_e32 v141, 0, v16
	s_barrier
	s_add_u32 s26, s18, s24
	s_addc_u32 s27, s19, s25
	s_add_u32 s26, s26, 0x22100100
	s_addc_u32 s27, s27, 0
	s_add_u32 s29, s16, s24
	s_addc_u32 s30, s17, s25
	s_add_i32 s31, 0, 0x10000
	s_cmpk_eq_i32 s24, 0xf00
	s_cselect_b32 s37, s23, s27
	s_cselect_b32 s36, s22, s26
	s_cselect_b32 s27, s21, s30
	s_cselect_b32 s26, s20, s29
	s_add_i32 s29, 0, 0x14000
	v_add_u32_e32 v154, s31, v140
	v_add_u32_e32 v170, s29, v140
	ds_read_b128 v[142:145], v154
	ds_read_b128 v[146:149], v154 offset:1024
	ds_read_b128 v[150:153], v154 offset:2048
	ds_read_b128 v[154:157], v154 offset:3072
	ds_read_b128 v[158:161], v170
	ds_read_b128 v[162:165], v170 offset:1024
	ds_read_b128 v[166:169], v170 offset:2048
	ds_read_b128 v[170:173], v170 offset:3072
	v_lshl_add_u64 v[198:199], v[138:139], 0, s[24:25]
	s_add_i32 m0, s10, 0xc000
	ds_read_b128 v[174:177], v141
	ds_read_b128 v[178:181], v141 offset:1024
	ds_read_b128 v[182:185], v141 offset:2048
	ds_read_b128 v[186:189], v141 offset:3072
	ds_read_b128 v[190:193], v141 offset:4096
	ds_read_b128 v[194:197], v141 offset:5120
	ds_read_b128 v[204:207], v141 offset:6144
	ds_read_b128 v[208:211], v141 offset:7168
	global_load_lds_dwordx4 v[198:199], off
	v_lshl_add_u64 v[198:199], v[136:137], 0, s[24:25]
	s_add_i32 m0, s10, 0xe000
	s_nop 0
	global_load_lds_dwordx4 v[198:199], off
	s_waitcnt vmcnt(8)
	s_waitcnt lgkmcnt(0)
	s_barrier
	s_setprio 1
	v_mfma_f32_16x16x32_bf16 v[128:131], v[142:145], v[174:177], 0
	v_mfma_f32_16x16x32_bf16 v[124:127], v[150:153], v[174:177], 0
	v_mfma_f32_16x16x32_bf16 v[112:115], v[142:145], v[182:185], 0
	v_mfma_f32_16x16x32_bf16 v[108:111], v[150:153], v[182:185], 0
	v_mfma_f32_16x16x32_bf16 v[96:99], v[142:145], v[190:193], 0
	v_mfma_f32_16x16x32_bf16 v[92:95], v[150:153], v[190:193], 0
	v_mfma_f32_16x16x32_bf16 v[80:83], v[142:145], v[204:207], 0
	v_mfma_f32_16x16x32_bf16 v[76:79], v[150:153], v[204:207], 0
	v_mfma_f32_16x16x32_bf16 v[128:131], v[146:149], v[178:181], v[128:131]
	v_mfma_f32_16x16x32_bf16 v[124:127], v[154:157], v[178:181], v[124:127]
	v_mfma_f32_16x16x32_bf16 v[112:115], v[146:149], v[186:189], v[112:115]
	v_mfma_f32_16x16x32_bf16 v[108:111], v[154:157], v[186:189], v[108:111]
	v_mfma_f32_16x16x32_bf16 v[96:99], v[146:149], v[194:197], v[96:99]
	v_mfma_f32_16x16x32_bf16 v[92:95], v[154:157], v[194:197], v[92:95]
	v_mfma_f32_16x16x32_bf16 v[80:83], v[146:149], v[208:211], v[80:83]
	v_mfma_f32_16x16x32_bf16 v[76:79], v[154:157], v[208:211], v[76:79]
	s_setprio 0
	s_setprio 1
	v_mfma_f32_16x16x32_bf16 v[120:123], v[158:161], v[174:177], 0
	v_mfma_f32_16x16x32_bf16 v[116:119], v[166:169], v[174:177], 0
	v_mfma_f32_16x16x32_bf16 v[104:107], v[158:161], v[182:185], 0
	v_mfma_f32_16x16x32_bf16 v[100:103], v[166:169], v[182:185], 0
	v_mfma_f32_16x16x32_bf16 v[88:91], v[158:161], v[190:193], 0
	v_mfma_f32_16x16x32_bf16 v[84:87], v[166:169], v[190:193], 0
	v_mfma_f32_16x16x32_bf16 v[72:75], v[158:161], v[204:207], 0
	v_mfma_f32_16x16x32_bf16 v[68:71], v[166:169], v[204:207], 0
	v_mfma_f32_16x16x32_bf16 v[120:123], v[162:165], v[178:181], v[120:123]
	v_mfma_f32_16x16x32_bf16 v[116:119], v[170:173], v[178:181], v[116:119]
	v_mfma_f32_16x16x32_bf16 v[104:107], v[162:165], v[186:189], v[104:107]
	v_mfma_f32_16x16x32_bf16 v[100:103], v[170:173], v[186:189], v[100:103]
	v_mfma_f32_16x16x32_bf16 v[88:91], v[162:165], v[194:197], v[88:91]
	v_mfma_f32_16x16x32_bf16 v[84:87], v[170:173], v[194:197], v[84:87]
	v_mfma_f32_16x16x32_bf16 v[72:75], v[162:165], v[208:211], v[72:75]
	v_mfma_f32_16x16x32_bf16 v[68:71], v[170:173], v[208:211], v[68:71]
	s_barrier
	s_setprio 0
	s_add_i32 s30, s31, s9
	v_lshl_add_u64 v[198:199], s[26:27], 0, v[2:3]
	s_mov_b32 m0, s30
	ds_read_b128 v[174:177], v141 offset:16384
	ds_read_b128 v[178:181], v141 offset:17408
	ds_read_b128 v[182:185], v141 offset:18432
	ds_read_b128 v[186:189], v141 offset:19456
	ds_read_b128 v[190:193], v141 offset:20480
	ds_read_b128 v[194:197], v141 offset:21504
	ds_read_b128 v[204:207], v141 offset:22528
	ds_read_b128 v[208:211], v141 offset:23552
	global_load_lds_dwordx4 v[198:199], off
	s_add_i32 m0, s30, 0x2000
	s_add_u32 s30, s26, 0x80000
	v_lshl_add_u64 v[212:213], s[26:27], 0, v[134:135]
	s_addc_u32 s31, s27, 0
	s_add_i32 s29, s29, s9
	global_load_lds_dwordx4 v[212:213], off
	v_lshl_add_u64 v[214:215], s[30:31], 0, v[2:3]
	s_mov_b32 m0, s29
	v_lshl_add_u64 v[216:217], s[36:37], 0, v[132:133]
	global_load_lds_dwordx4 v[214:215], off
	v_lshl_add_u64 v[214:215], s[30:31], 0, v[134:135]
	s_add_i32 m0, s29, 0x2000
	s_nop 0
	global_load_lds_dwordx4 v[214:215], off
	v_lshl_add_u64 v[214:215], s[36:37], 0, v[0:1]
	s_mov_b32 m0, s10
	s_nop 0
	global_load_lds_dwordx4 v[214:215], off
	s_mov_b32 m0, s11
	s_nop 0
	global_load_lds_dwordx4 v[216:217], off
	s_waitcnt vmcnt(8)
	s_waitcnt lgkmcnt(0)
	s_barrier
	s_setprio 1
	v_mfma_f32_16x16x32_bf16 v[64:67], v[142:145], v[174:177], 0
	v_mfma_f32_16x16x32_bf16 v[60:63], v[150:153], v[174:177], 0
	v_mfma_f32_16x16x32_bf16 v[48:51], v[142:145], v[182:185], 0
	v_mfma_f32_16x16x32_bf16 v[44:47], v[150:153], v[182:185], 0
	v_mfma_f32_16x16x32_bf16 v[32:35], v[142:145], v[190:193], 0
	v_mfma_f32_16x16x32_bf16 v[28:31], v[150:153], v[190:193], 0
	v_mfma_f32_16x16x32_bf16 v[16:19], v[142:145], v[204:207], 0
	v_mfma_f32_16x16x32_bf16 v[12:15], v[150:153], v[204:207], 0
	v_mfma_f32_16x16x32_bf16 v[64:67], v[146:149], v[178:181], v[64:67]
	v_mfma_f32_16x16x32_bf16 v[60:63], v[154:157], v[178:181], v[60:63]
	v_mfma_f32_16x16x32_bf16 v[48:51], v[146:149], v[186:189], v[48:51]
	v_mfma_f32_16x16x32_bf16 v[44:47], v[154:157], v[186:189], v[44:47]
	v_mfma_f32_16x16x32_bf16 v[32:35], v[146:149], v[194:197], v[32:35]
	v_mfma_f32_16x16x32_bf16 v[28:31], v[154:157], v[194:197], v[28:31]
	v_mfma_f32_16x16x32_bf16 v[16:19], v[146:149], v[208:211], v[16:19]
	v_mfma_f32_16x16x32_bf16 v[12:15], v[154:157], v[208:211], v[12:15]
	s_setprio 0
	s_setprio 1
	v_mfma_f32_16x16x32_bf16 v[56:59], v[158:161], v[174:177], 0
	v_mfma_f32_16x16x32_bf16 v[52:55], v[166:169], v[174:177], 0
	v_mfma_f32_16x16x32_bf16 v[40:43], v[158:161], v[182:185], 0
	v_mfma_f32_16x16x32_bf16 v[36:39], v[166:169], v[182:185], 0
	v_mfma_f32_16x16x32_bf16 v[24:27], v[158:161], v[190:193], 0
	v_mfma_f32_16x16x32_bf16 v[20:23], v[166:169], v[190:193], 0
	v_mfma_f32_16x16x32_bf16 v[8:11], v[158:161], v[204:207], 0
	v_mfma_f32_16x16x32_bf16 v[4:7], v[166:169], v[204:207], 0
	v_mfma_f32_16x16x32_bf16 v[56:59], v[162:165], v[178:181], v[56:59]
	v_mfma_f32_16x16x32_bf16 v[52:55], v[170:173], v[178:181], v[52:55]
	v_mfma_f32_16x16x32_bf16 v[40:43], v[162:165], v[186:189], v[40:43]
	v_mfma_f32_16x16x32_bf16 v[36:39], v[170:173], v[186:189], v[36:39]
	v_mfma_f32_16x16x32_bf16 v[24:27], v[162:165], v[194:197], v[24:27]
	v_mfma_f32_16x16x32_bf16 v[20:23], v[170:173], v[194:197], v[20:23]
	v_mfma_f32_16x16x32_bf16 v[8:11], v[162:165], v[208:211], v[8:11]
	v_mfma_f32_16x16x32_bf16 v[4:7], v[170:173], v[208:211], v[4:7]
	s_barrier
	s_setprio 0
	s_add_i32 s29, 0, 0x18000
	s_add_i32 s33, 0, 0x1c000
	v_add_u32_e32 v154, s29, v140
	v_add_u32_e32 v170, s33, v140
	ds_read_b128 v[142:145], v154
	ds_read_b128 v[146:149], v154 offset:1024
	ds_read_b128 v[150:153], v154 offset:2048
	ds_read_b128 v[154:157], v154 offset:3072
	ds_read_b128 v[158:161], v170
	ds_read_b128 v[162:165], v170 offset:1024
	ds_read_b128 v[166:169], v170 offset:2048
	ds_read_b128 v[170:173], v170 offset:3072
	s_add_u32 s30, s36, 0x80000
	s_addc_u32 s31, s37, 0
	s_mov_b32 m0, s12
	v_lshl_add_u64 v[218:219], s[30:31], 0, v[0:1]
	ds_read_b128 v[174:177], v141 offset:32768
	ds_read_b128 v[178:181], v141 offset:33792
	ds_read_b128 v[182:185], v141 offset:34816
	ds_read_b128 v[186:189], v141 offset:35840
	ds_read_b128 v[190:193], v141 offset:36864
	ds_read_b128 v[194:197], v141 offset:37888
	ds_read_b128 v[204:207], v141 offset:38912
	ds_read_b128 v[208:211], v141 offset:39936
	global_load_lds_dwordx4 v[218:219], off
	v_lshl_add_u64 v[218:219], s[30:31], 0, v[132:133]
	s_mov_b32 m0, s13
	s_nop 0
	global_load_lds_dwordx4 v[218:219], off
	s_waitcnt vmcnt(8)
	s_waitcnt lgkmcnt(0)
	s_barrier
	s_setprio 1
	v_mfma_f32_16x16x32_bf16 v[128:131], v[142:145], v[174:177], v[128:131]
	v_mfma_f32_16x16x32_bf16 v[124:127], v[150:153], v[174:177], v[124:127]
	v_mfma_f32_16x16x32_bf16 v[112:115], v[142:145], v[182:185], v[112:115]
	v_mfma_f32_16x16x32_bf16 v[108:111], v[150:153], v[182:185], v[108:111]
	v_mfma_f32_16x16x32_bf16 v[96:99], v[142:145], v[190:193], v[96:99]
	v_mfma_f32_16x16x32_bf16 v[92:95], v[150:153], v[190:193], v[92:95]
	v_mfma_f32_16x16x32_bf16 v[80:83], v[142:145], v[204:207], v[80:83]
	v_mfma_f32_16x16x32_bf16 v[76:79], v[150:153], v[204:207], v[76:79]
	v_mfma_f32_16x16x32_bf16 v[128:131], v[146:149], v[178:181], v[128:131]
	v_mfma_f32_16x16x32_bf16 v[124:127], v[154:157], v[178:181], v[124:127]
	v_mfma_f32_16x16x32_bf16 v[112:115], v[146:149], v[186:189], v[112:115]
	v_mfma_f32_16x16x32_bf16 v[108:111], v[154:157], v[186:189], v[108:111]
	v_mfma_f32_16x16x32_bf16 v[96:99], v[146:149], v[194:197], v[96:99]
	v_mfma_f32_16x16x32_bf16 v[92:95], v[154:157], v[194:197], v[92:95]
	v_mfma_f32_16x16x32_bf16 v[80:83], v[146:149], v[208:211], v[80:83]
	v_mfma_f32_16x16x32_bf16 v[76:79], v[154:157], v[208:211], v[76:79]
	s_setprio 0
	s_setprio 1
	v_mfma_f32_16x16x32_bf16 v[120:123], v[158:161], v[174:177], v[120:123]
	v_mfma_f32_16x16x32_bf16 v[116:119], v[166:169], v[174:177], v[116:119]
	v_mfma_f32_16x16x32_bf16 v[104:107], v[158:161], v[182:185], v[104:107]
	v_mfma_f32_16x16x32_bf16 v[100:103], v[166:169], v[182:185], v[100:103]
	v_mfma_f32_16x16x32_bf16 v[88:91], v[158:161], v[190:193], v[88:91]
	v_mfma_f32_16x16x32_bf16 v[84:87], v[166:169], v[190:193], v[84:87]
	v_mfma_f32_16x16x32_bf16 v[72:75], v[158:161], v[204:207], v[72:75]
	v_mfma_f32_16x16x32_bf16 v[68:71], v[166:169], v[204:207], v[68:71]
	v_mfma_f32_16x16x32_bf16 v[120:123], v[162:165], v[178:181], v[120:123]
	v_mfma_f32_16x16x32_bf16 v[116:119], v[170:173], v[178:181], v[116:119]
	v_mfma_f32_16x16x32_bf16 v[104:107], v[162:165], v[186:189], v[104:107]
	v_mfma_f32_16x16x32_bf16 v[100:103], v[170:173], v[186:189], v[100:103]
	v_mfma_f32_16x16x32_bf16 v[88:91], v[162:165], v[194:197], v[88:91]
	v_mfma_f32_16x16x32_bf16 v[84:87], v[170:173], v[194:197], v[84:87]
	v_mfma_f32_16x16x32_bf16 v[72:75], v[162:165], v[208:211], v[72:75]
	v_mfma_f32_16x16x32_bf16 v[68:71], v[170:173], v[208:211], v[68:71]
	s_barrier
	s_setprio 0
	s_add_i32 s29, s29, s9
	v_lshl_add_u64 v[198:199], v[198:199], 0, s[68:69]
	s_mov_b32 m0, s29
	ds_read_b128 v[174:177], v141 offset:49152
	ds_read_b128 v[178:181], v141 offset:50176
	ds_read_b128 v[182:185], v141 offset:51200
	ds_read_b128 v[186:189], v141 offset:52224
	ds_read_b128 v[190:193], v141 offset:53248
	ds_read_b128 v[194:197], v141 offset:54272
	ds_read_b128 v[204:207], v141 offset:55296
	ds_read_b128 v[208:211], v141 offset:56320
	global_load_lds_dwordx4 v[198:199], off
	s_add_i32 m0, s29, 0x2000
	s_add_u32 s26, s26, 0x80080
	v_lshl_add_u64 v[198:199], v[212:213], 0, s[68:69]
	s_addc_u32 s27, s27, 0
	s_add_i32 s29, s33, s9
	global_load_lds_dwordx4 v[198:199], off
	v_lshl_add_u64 v[198:199], s[26:27], 0, v[2:3]
	s_mov_b32 m0, s29
	s_nop 0
	global_load_lds_dwordx4 v[198:199], off
	v_lshl_add_u64 v[198:199], s[26:27], 0, v[134:135]
	s_add_i32 m0, s29, 0x2000
	s_nop 0
	global_load_lds_dwordx4 v[198:199], off
	v_lshl_add_u64 v[198:199], v[214:215], 0, s[68:69]
	s_mov_b32 m0, s14
	s_nop 0
	global_load_lds_dwordx4 v[198:199], off
	v_lshl_add_u64 v[198:199], v[216:217], 0, s[68:69]
	s_mov_b32 m0, s15
	s_nop 0
	global_load_lds_dwordx4 v[198:199], off
	s_waitcnt vmcnt(8)
	s_waitcnt lgkmcnt(0)
	s_barrier
	s_setprio 1
	v_mfma_f32_16x16x32_bf16 v[64:67], v[142:145], v[174:177], v[64:67]
	v_mfma_f32_16x16x32_bf16 v[60:63], v[150:153], v[174:177], v[60:63]
	v_mfma_f32_16x16x32_bf16 v[48:51], v[142:145], v[182:185], v[48:51]
	v_mfma_f32_16x16x32_bf16 v[44:47], v[150:153], v[182:185], v[44:47]
	v_mfma_f32_16x16x32_bf16 v[32:35], v[142:145], v[190:193], v[32:35]
	v_mfma_f32_16x16x32_bf16 v[28:31], v[150:153], v[190:193], v[28:31]
	v_mfma_f32_16x16x32_bf16 v[16:19], v[142:145], v[204:207], v[16:19]
	v_mfma_f32_16x16x32_bf16 v[12:15], v[150:153], v[204:207], v[12:15]
	v_mfma_f32_16x16x32_bf16 v[64:67], v[146:149], v[178:181], v[64:67]
	v_mfma_f32_16x16x32_bf16 v[60:63], v[154:157], v[178:181], v[60:63]
	v_mfma_f32_16x16x32_bf16 v[48:51], v[146:149], v[186:189], v[48:51]
	v_mfma_f32_16x16x32_bf16 v[44:47], v[154:157], v[186:189], v[44:47]
	v_mfma_f32_16x16x32_bf16 v[32:35], v[146:149], v[194:197], v[32:35]
	v_mfma_f32_16x16x32_bf16 v[28:31], v[154:157], v[194:197], v[28:31]
	v_mfma_f32_16x16x32_bf16 v[16:19], v[146:149], v[208:211], v[16:19]
	v_mfma_f32_16x16x32_bf16 v[12:15], v[154:157], v[208:211], v[12:15]
	s_setprio 0
	s_setprio 1
	v_mfma_f32_16x16x32_bf16 v[56:59], v[158:161], v[174:177], v[56:59]
	v_mfma_f32_16x16x32_bf16 v[52:55], v[166:169], v[174:177], v[52:55]
	v_mfma_f32_16x16x32_bf16 v[40:43], v[158:161], v[182:185], v[40:43]
	v_mfma_f32_16x16x32_bf16 v[36:39], v[166:169], v[182:185], v[36:39]
	v_mfma_f32_16x16x32_bf16 v[24:27], v[158:161], v[190:193], v[24:27]
	v_mfma_f32_16x16x32_bf16 v[20:23], v[166:169], v[190:193], v[20:23]
	v_mfma_f32_16x16x32_bf16 v[8:11], v[158:161], v[204:207], v[8:11]
	v_mfma_f32_16x16x32_bf16 v[4:7], v[166:169], v[204:207], v[4:7]
	v_mfma_f32_16x16x32_bf16 v[56:59], v[162:165], v[178:181], v[56:59]
	v_mfma_f32_16x16x32_bf16 v[52:55], v[170:173], v[178:181], v[52:55]
	v_mfma_f32_16x16x32_bf16 v[40:43], v[162:165], v[186:189], v[40:43]
	v_mfma_f32_16x16x32_bf16 v[36:39], v[170:173], v[186:189], v[36:39]
	v_mfma_f32_16x16x32_bf16 v[24:27], v[162:165], v[194:197], v[24:27]
	v_mfma_f32_16x16x32_bf16 v[20:23], v[170:173], v[194:197], v[20:23]
	v_mfma_f32_16x16x32_bf16 v[8:11], v[162:165], v[208:211], v[8:11]
	v_mfma_f32_16x16x32_bf16 v[4:7], v[170:173], v[208:211], v[4:7]
	s_barrier
	s_setprio 0
	s_add_i32 s28, s28, 2
	s_add_u32 s24, s24, 0x100
	s_addc_u32 s25, s25, 0
	s_cmp_lt_u32 s28, 30
.LBB0_854:
	s_add_u32 s26, s18, s24
	s_addc_u32 s27, s19, s25
	s_add_u32 s26, s26, 0x22100100
	s_addc_u32 s27, s27, 0
	s_add_u32 s29, s16, s24
	s_addc_u32 s30, s17, s25
	s_add_i32 s31, 0, 0x10000
	s_cmpk_eq_i32 s24, 0xf00
	s_cselect_b32 s37, s23, s27
	s_cselect_b32 s36, s22, s26
	s_cselect_b32 s27, s21, s30
	s_cselect_b32 s26, s20, s29
	s_add_i32 s29, 0, 0x14000
	v_add_u32_e32 v154, s31, v140
	v_add_u32_e32 v170, s29, v140
	ds_read_b128 v[142:145], v154
	ds_read_b128 v[146:149], v154 offset:1024
	ds_read_b128 v[150:153], v154 offset:2048
	ds_read_b128 v[154:157], v154 offset:3072
	ds_read_b128 v[158:161], v170
	ds_read_b128 v[162:165], v170 offset:1024
	ds_read_b128 v[166:169], v170 offset:2048
	ds_read_b128 v[170:173], v170 offset:3072
	v_lshl_add_u64 v[198:199], v[138:139], 0, s[24:25]
	s_add_i32 m0, s10, 0xc000
	ds_read_b128 v[174:177], v141
	ds_read_b128 v[178:181], v141 offset:1024
	ds_read_b128 v[182:185], v141 offset:2048
	ds_read_b128 v[186:189], v141 offset:3072
	ds_read_b128 v[190:193], v141 offset:4096
	ds_read_b128 v[194:197], v141 offset:5120
	ds_read_b128 v[204:207], v141 offset:6144
	ds_read_b128 v[208:211], v141 offset:7168
	global_load_lds_dwordx4 v[198:199], off
	v_lshl_add_u64 v[198:199], v[136:137], 0, s[24:25]
	s_add_i32 m0, s10, 0xe000
	s_nop 0
	global_load_lds_dwordx4 v[198:199], off
	s_waitcnt vmcnt(8)
	s_waitcnt lgkmcnt(0)
	s_barrier
	s_setprio 1
	v_mfma_f32_16x16x32_bf16 v[128:131], v[142:145], v[174:177], v[128:131]
	v_mfma_f32_16x16x32_bf16 v[124:127], v[150:153], v[174:177], v[124:127]
	v_mfma_f32_16x16x32_bf16 v[112:115], v[142:145], v[182:185], v[112:115]
	v_mfma_f32_16x16x32_bf16 v[108:111], v[150:153], v[182:185], v[108:111]
	v_mfma_f32_16x16x32_bf16 v[96:99], v[142:145], v[190:193], v[96:99]
	v_mfma_f32_16x16x32_bf16 v[92:95], v[150:153], v[190:193], v[92:95]
	v_mfma_f32_16x16x32_bf16 v[80:83], v[142:145], v[204:207], v[80:83]
	v_mfma_f32_16x16x32_bf16 v[76:79], v[150:153], v[204:207], v[76:79]
	v_mfma_f32_16x16x32_bf16 v[128:131], v[146:149], v[178:181], v[128:131]
	v_mfma_f32_16x16x32_bf16 v[124:127], v[154:157], v[178:181], v[124:127]
	v_mfma_f32_16x16x32_bf16 v[112:115], v[146:149], v[186:189], v[112:115]
	v_mfma_f32_16x16x32_bf16 v[108:111], v[154:157], v[186:189], v[108:111]
	v_mfma_f32_16x16x32_bf16 v[96:99], v[146:149], v[194:197], v[96:99]
	v_mfma_f32_16x16x32_bf16 v[92:95], v[154:157], v[194:197], v[92:95]
	v_mfma_f32_16x16x32_bf16 v[80:83], v[146:149], v[208:211], v[80:83]
	v_mfma_f32_16x16x32_bf16 v[76:79], v[154:157], v[208:211], v[76:79]
	s_setprio 0
	s_setprio 1
	v_mfma_f32_16x16x32_bf16 v[120:123], v[158:161], v[174:177], v[120:123]
	v_mfma_f32_16x16x32_bf16 v[116:119], v[166:169], v[174:177], v[116:119]
	v_mfma_f32_16x16x32_bf16 v[104:107], v[158:161], v[182:185], v[104:107]
	v_mfma_f32_16x16x32_bf16 v[100:103], v[166:169], v[182:185], v[100:103]
	v_mfma_f32_16x16x32_bf16 v[88:91], v[158:161], v[190:193], v[88:91]
	v_mfma_f32_16x16x32_bf16 v[84:87], v[166:169], v[190:193], v[84:87]
	v_mfma_f32_16x16x32_bf16 v[72:75], v[158:161], v[204:207], v[72:75]
	v_mfma_f32_16x16x32_bf16 v[68:71], v[166:169], v[204:207], v[68:71]
	v_mfma_f32_16x16x32_bf16 v[120:123], v[162:165], v[178:181], v[120:123]
	v_mfma_f32_16x16x32_bf16 v[116:119], v[170:173], v[178:181], v[116:119]
	v_mfma_f32_16x16x32_bf16 v[104:107], v[162:165], v[186:189], v[104:107]
	v_mfma_f32_16x16x32_bf16 v[100:103], v[170:173], v[186:189], v[100:103]
	v_mfma_f32_16x16x32_bf16 v[88:91], v[162:165], v[194:197], v[88:91]
	v_mfma_f32_16x16x32_bf16 v[84:87], v[170:173], v[194:197], v[84:87]
	v_mfma_f32_16x16x32_bf16 v[72:75], v[162:165], v[208:211], v[72:75]
	v_mfma_f32_16x16x32_bf16 v[68:71], v[170:173], v[208:211], v[68:71]
	s_barrier
	s_setprio 0
	s_add_i32 s30, s31, s9
	v_lshl_add_u64 v[198:199], s[26:27], 0, v[2:3]
	s_mov_b32 m0, s30
	ds_read_b128 v[174:177], v141 offset:16384
	ds_read_b128 v[178:181], v141 offset:17408
	ds_read_b128 v[182:185], v141 offset:18432
	ds_read_b128 v[186:189], v141 offset:19456
	ds_read_b128 v[190:193], v141 offset:20480
	ds_read_b128 v[194:197], v141 offset:21504
	ds_read_b128 v[204:207], v141 offset:22528
	ds_read_b128 v[208:211], v141 offset:23552
	global_load_lds_dwordx4 v[198:199], off
	s_add_i32 m0, s30, 0x2000
	s_add_u32 s30, s26, 0x80000
	v_lshl_add_u64 v[212:213], s[26:27], 0, v[134:135]
	s_addc_u32 s31, s27, 0
	s_add_i32 s29, s29, s9
	global_load_lds_dwordx4 v[212:213], off
	v_lshl_add_u64 v[214:215], s[30:31], 0, v[2:3]
	s_mov_b32 m0, s29
	v_lshl_add_u64 v[216:217], s[36:37], 0, v[132:133]
	global_load_lds_dwordx4 v[214:215], off
	v_lshl_add_u64 v[214:215], s[30:31], 0, v[134:135]
	s_add_i32 m0, s29, 0x2000
	s_nop 0
	global_load_lds_dwordx4 v[214:215], off
	v_lshl_add_u64 v[214:215], s[36:37], 0, v[0:1]
	s_mov_b32 m0, s10
	s_nop 0
	global_load_lds_dwordx4 v[214:215], off
	s_mov_b32 m0, s11
	s_nop 0
	global_load_lds_dwordx4 v[216:217], off
	s_waitcnt vmcnt(8)
	s_waitcnt lgkmcnt(0)
	s_barrier
	s_setprio 1
	v_mfma_f32_16x16x32_bf16 v[64:67], v[142:145], v[174:177], v[64:67]
	v_mfma_f32_16x16x32_bf16 v[60:63], v[150:153], v[174:177], v[60:63]
	v_mfma_f32_16x16x32_bf16 v[48:51], v[142:145], v[182:185], v[48:51]
	v_mfma_f32_16x16x32_bf16 v[44:47], v[150:153], v[182:185], v[44:47]
	v_mfma_f32_16x16x32_bf16 v[32:35], v[142:145], v[190:193], v[32:35]
	v_mfma_f32_16x16x32_bf16 v[28:31], v[150:153], v[190:193], v[28:31]
	v_mfma_f32_16x16x32_bf16 v[16:19], v[142:145], v[204:207], v[16:19]
	v_mfma_f32_16x16x32_bf16 v[12:15], v[150:153], v[204:207], v[12:15]
	v_mfma_f32_16x16x32_bf16 v[64:67], v[146:149], v[178:181], v[64:67]
	v_mfma_f32_16x16x32_bf16 v[60:63], v[154:157], v[178:181], v[60:63]
	v_mfma_f32_16x16x32_bf16 v[48:51], v[146:149], v[186:189], v[48:51]
	v_mfma_f32_16x16x32_bf16 v[44:47], v[154:157], v[186:189], v[44:47]
	v_mfma_f32_16x16x32_bf16 v[32:35], v[146:149], v[194:197], v[32:35]
	v_mfma_f32_16x16x32_bf16 v[28:31], v[154:157], v[194:197], v[28:31]
	v_mfma_f32_16x16x32_bf16 v[16:19], v[146:149], v[208:211], v[16:19]
	v_mfma_f32_16x16x32_bf16 v[12:15], v[154:157], v[208:211], v[12:15]
	s_setprio 0
	s_setprio 1
	v_mfma_f32_16x16x32_bf16 v[56:59], v[158:161], v[174:177], v[56:59]
	v_mfma_f32_16x16x32_bf16 v[52:55], v[166:169], v[174:177], v[52:55]
	v_mfma_f32_16x16x32_bf16 v[40:43], v[158:161], v[182:185], v[40:43]
	v_mfma_f32_16x16x32_bf16 v[36:39], v[166:169], v[182:185], v[36:39]
	v_mfma_f32_16x16x32_bf16 v[24:27], v[158:161], v[190:193], v[24:27]
	v_mfma_f32_16x16x32_bf16 v[20:23], v[166:169], v[190:193], v[20:23]
	v_mfma_f32_16x16x32_bf16 v[8:11], v[158:161], v[204:207], v[8:11]
	v_mfma_f32_16x16x32_bf16 v[4:7], v[166:169], v[204:207], v[4:7]
	v_mfma_f32_16x16x32_bf16 v[56:59], v[162:165], v[178:181], v[56:59]
	v_mfma_f32_16x16x32_bf16 v[52:55], v[170:173], v[178:181], v[52:55]
	v_mfma_f32_16x16x32_bf16 v[40:43], v[162:165], v[186:189], v[40:43]
	v_mfma_f32_16x16x32_bf16 v[36:39], v[170:173], v[186:189], v[36:39]
	v_mfma_f32_16x16x32_bf16 v[24:27], v[162:165], v[194:197], v[24:27]
	v_mfma_f32_16x16x32_bf16 v[20:23], v[170:173], v[194:197], v[20:23]
	v_mfma_f32_16x16x32_bf16 v[8:11], v[162:165], v[208:211], v[8:11]
	v_mfma_f32_16x16x32_bf16 v[4:7], v[170:173], v[208:211], v[4:7]
	s_barrier
	s_setprio 0
	s_add_i32 s29, 0, 0x18000
	s_add_i32 s33, 0, 0x1c000
	v_add_u32_e32 v154, s29, v140
	v_add_u32_e32 v170, s33, v140
	ds_read_b128 v[142:145], v154
	ds_read_b128 v[146:149], v154 offset:1024
	ds_read_b128 v[150:153], v154 offset:2048
	ds_read_b128 v[154:157], v154 offset:3072
	ds_read_b128 v[158:161], v170
	ds_read_b128 v[162:165], v170 offset:1024
	ds_read_b128 v[166:169], v170 offset:2048
	ds_read_b128 v[170:173], v170 offset:3072
	s_add_u32 s30, s36, 0x80000
	s_addc_u32 s31, s37, 0
	s_mov_b32 m0, s12
	v_lshl_add_u64 v[218:219], s[30:31], 0, v[0:1]
	ds_read_b128 v[174:177], v141 offset:32768
	ds_read_b128 v[178:181], v141 offset:33792
	ds_read_b128 v[182:185], v141 offset:34816
	ds_read_b128 v[186:189], v141 offset:35840
	ds_read_b128 v[190:193], v141 offset:36864
	ds_read_b128 v[194:197], v141 offset:37888
	ds_read_b128 v[204:207], v141 offset:38912
	ds_read_b128 v[208:211], v141 offset:39936
	global_load_lds_dwordx4 v[218:219], off
	v_lshl_add_u64 v[218:219], s[30:31], 0, v[132:133]
	s_mov_b32 m0, s13
	s_nop 0
	global_load_lds_dwordx4 v[218:219], off
	s_waitcnt vmcnt(8)
	s_waitcnt lgkmcnt(0)
	s_barrier
	s_setprio 1
	v_mfma_f32_16x16x32_bf16 v[128:131], v[142:145], v[174:177], v[128:131]
	v_mfma_f32_16x16x32_bf16 v[124:127], v[150:153], v[174:177], v[124:127]
	v_mfma_f32_16x16x32_bf16 v[112:115], v[142:145], v[182:185], v[112:115]
	v_mfma_f32_16x16x32_bf16 v[108:111], v[150:153], v[182:185], v[108:111]
	v_mfma_f32_16x16x32_bf16 v[96:99], v[142:145], v[190:193], v[96:99]
	v_mfma_f32_16x16x32_bf16 v[92:95], v[150:153], v[190:193], v[92:95]
	v_mfma_f32_16x16x32_bf16 v[80:83], v[142:145], v[204:207], v[80:83]
	v_mfma_f32_16x16x32_bf16 v[76:79], v[150:153], v[204:207], v[76:79]
	v_mfma_f32_16x16x32_bf16 v[128:131], v[146:149], v[178:181], v[128:131]
	v_mfma_f32_16x16x32_bf16 v[124:127], v[154:157], v[178:181], v[124:127]
	v_mfma_f32_16x16x32_bf16 v[112:115], v[146:149], v[186:189], v[112:115]
	v_mfma_f32_16x16x32_bf16 v[108:111], v[154:157], v[186:189], v[108:111]
	v_mfma_f32_16x16x32_bf16 v[96:99], v[146:149], v[194:197], v[96:99]
	v_mfma_f32_16x16x32_bf16 v[92:95], v[154:157], v[194:197], v[92:95]
	v_mfma_f32_16x16x32_bf16 v[80:83], v[146:149], v[208:211], v[80:83]
	v_mfma_f32_16x16x32_bf16 v[76:79], v[154:157], v[208:211], v[76:79]
	s_setprio 0
	s_setprio 1
	v_mfma_f32_16x16x32_bf16 v[120:123], v[158:161], v[174:177], v[120:123]
	v_mfma_f32_16x16x32_bf16 v[116:119], v[166:169], v[174:177], v[116:119]
	v_mfma_f32_16x16x32_bf16 v[104:107], v[158:161], v[182:185], v[104:107]
	v_mfma_f32_16x16x32_bf16 v[100:103], v[166:169], v[182:185], v[100:103]
	v_mfma_f32_16x16x32_bf16 v[88:91], v[158:161], v[190:193], v[88:91]
	v_mfma_f32_16x16x32_bf16 v[84:87], v[166:169], v[190:193], v[84:87]
	v_mfma_f32_16x16x32_bf16 v[72:75], v[158:161], v[204:207], v[72:75]
	v_mfma_f32_16x16x32_bf16 v[68:71], v[166:169], v[204:207], v[68:71]
	v_mfma_f32_16x16x32_bf16 v[120:123], v[162:165], v[178:181], v[120:123]
	v_mfma_f32_16x16x32_bf16 v[116:119], v[170:173], v[178:181], v[116:119]
	v_mfma_f32_16x16x32_bf16 v[104:107], v[162:165], v[186:189], v[104:107]
	v_mfma_f32_16x16x32_bf16 v[100:103], v[170:173], v[186:189], v[100:103]
	v_mfma_f32_16x16x32_bf16 v[88:91], v[162:165], v[194:197], v[88:91]
	v_mfma_f32_16x16x32_bf16 v[84:87], v[170:173], v[194:197], v[84:87]
	v_mfma_f32_16x16x32_bf16 v[72:75], v[162:165], v[208:211], v[72:75]
	v_mfma_f32_16x16x32_bf16 v[68:71], v[170:173], v[208:211], v[68:71]
	s_barrier
	s_setprio 0
	s_add_i32 s29, s29, s9
	v_lshl_add_u64 v[198:199], v[198:199], 0, s[68:69]
	s_mov_b32 m0, s29
	ds_read_b128 v[174:177], v141 offset:49152
	ds_read_b128 v[178:181], v141 offset:50176
	ds_read_b128 v[182:185], v141 offset:51200
	ds_read_b128 v[186:189], v141 offset:52224
	ds_read_b128 v[190:193], v141 offset:53248
	ds_read_b128 v[194:197], v141 offset:54272
	ds_read_b128 v[204:207], v141 offset:55296
	ds_read_b128 v[208:211], v141 offset:56320
	global_load_lds_dwordx4 v[198:199], off
	s_add_i32 m0, s29, 0x2000
	s_add_u32 s26, s26, 0x80080
	v_lshl_add_u64 v[198:199], v[212:213], 0, s[68:69]
	s_addc_u32 s27, s27, 0
	s_add_i32 s29, s33, s9
	global_load_lds_dwordx4 v[198:199], off
	v_lshl_add_u64 v[198:199], s[26:27], 0, v[2:3]
	s_mov_b32 m0, s29
	s_nop 0
	global_load_lds_dwordx4 v[198:199], off
	v_lshl_add_u64 v[198:199], s[26:27], 0, v[134:135]
	s_add_i32 m0, s29, 0x2000
	s_nop 0
	global_load_lds_dwordx4 v[198:199], off
	v_lshl_add_u64 v[198:199], v[214:215], 0, s[68:69]
	s_mov_b32 m0, s14
	s_nop 0
	global_load_lds_dwordx4 v[198:199], off
	v_lshl_add_u64 v[198:199], v[216:217], 0, s[68:69]
	s_mov_b32 m0, s15
	s_nop 0
	global_load_lds_dwordx4 v[198:199], off
	s_waitcnt vmcnt(8)
	s_waitcnt lgkmcnt(0)
	s_barrier
	s_setprio 1
	v_mfma_f32_16x16x32_bf16 v[64:67], v[142:145], v[174:177], v[64:67]
	v_mfma_f32_16x16x32_bf16 v[60:63], v[150:153], v[174:177], v[60:63]
	v_mfma_f32_16x16x32_bf16 v[48:51], v[142:145], v[182:185], v[48:51]
	v_mfma_f32_16x16x32_bf16 v[44:47], v[150:153], v[182:185], v[44:47]
	v_mfma_f32_16x16x32_bf16 v[32:35], v[142:145], v[190:193], v[32:35]
	v_mfma_f32_16x16x32_bf16 v[28:31], v[150:153], v[190:193], v[28:31]
	v_mfma_f32_16x16x32_bf16 v[16:19], v[142:145], v[204:207], v[16:19]
	v_mfma_f32_16x16x32_bf16 v[12:15], v[150:153], v[204:207], v[12:15]
	v_mfma_f32_16x16x32_bf16 v[64:67], v[146:149], v[178:181], v[64:67]
	v_mfma_f32_16x16x32_bf16 v[60:63], v[154:157], v[178:181], v[60:63]
	v_mfma_f32_16x16x32_bf16 v[48:51], v[146:149], v[186:189], v[48:51]
	v_mfma_f32_16x16x32_bf16 v[44:47], v[154:157], v[186:189], v[44:47]
	v_mfma_f32_16x16x32_bf16 v[32:35], v[146:149], v[194:197], v[32:35]
	v_mfma_f32_16x16x32_bf16 v[28:31], v[154:157], v[194:197], v[28:31]
	v_mfma_f32_16x16x32_bf16 v[16:19], v[146:149], v[208:211], v[16:19]
	v_mfma_f32_16x16x32_bf16 v[12:15], v[154:157], v[208:211], v[12:15]
	s_setprio 0
	s_setprio 1
	v_mfma_f32_16x16x32_bf16 v[56:59], v[158:161], v[174:177], v[56:59]
	v_mfma_f32_16x16x32_bf16 v[52:55], v[166:169], v[174:177], v[52:55]
	v_mfma_f32_16x16x32_bf16 v[40:43], v[158:161], v[182:185], v[40:43]
	v_mfma_f32_16x16x32_bf16 v[36:39], v[166:169], v[182:185], v[36:39]
	v_mfma_f32_16x16x32_bf16 v[24:27], v[158:161], v[190:193], v[24:27]
	v_mfma_f32_16x16x32_bf16 v[20:23], v[166:169], v[190:193], v[20:23]
	v_mfma_f32_16x16x32_bf16 v[8:11], v[158:161], v[204:207], v[8:11]
	v_mfma_f32_16x16x32_bf16 v[4:7], v[166:169], v[204:207], v[4:7]
	v_mfma_f32_16x16x32_bf16 v[56:59], v[162:165], v[178:181], v[56:59]
	v_mfma_f32_16x16x32_bf16 v[52:55], v[170:173], v[178:181], v[52:55]
	v_mfma_f32_16x16x32_bf16 v[40:43], v[162:165], v[186:189], v[40:43]
	v_mfma_f32_16x16x32_bf16 v[36:39], v[170:173], v[186:189], v[36:39]
	v_mfma_f32_16x16x32_bf16 v[24:27], v[162:165], v[194:197], v[24:27]
	v_mfma_f32_16x16x32_bf16 v[20:23], v[170:173], v[194:197], v[20:23]
	v_mfma_f32_16x16x32_bf16 v[8:11], v[162:165], v[208:211], v[8:11]
	v_mfma_f32_16x16x32_bf16 v[4:7], v[170:173], v[208:211], v[4:7]
	s_barrier
	s_setprio 0
	s_add_i32 s28, s28, 2
	s_add_u32 s24, s24, 0x100
	s_addc_u32 s25, s25, 0
	s_cmp_lt_u32 s28, 30
	s_cbranch_scc1 .LBB0_854
	s_waitcnt vmcnt(0)
	s_cmpk_gt_u32 s6, 0xff
	s_cbranch_scc1 .LBB0_857
	s_barrier

.LBB0_946:
	s_ashr_i32 s49, s48, 31
	s_andn2_b64 vcc, exec, s[56:57]
	s_lshl_b64 s[6:7], s[48:49], 19
	s_add_u32 s52, s62, s6
	s_addc_u32 s53, s63, s7
	s_and_b64 s[6:7], s[56:57], exec
	s_cselect_b32 s5, s53, s41
	s_cselect_b32 s6, s52, s40
	s_ashr_i32 s51, s50, 31
	s_lshl_b64 s[8:9], s[50:51], 19
	s_add_u32 s54, s64, s8
	s_addc_u32 s55, s65, s9
	s_and_b64 s[8:9], s[56:57], exec
	s_cselect_b32 s7, s55, s39
	s_cselect_b32 s8, s54, s38
	s_add_u32 s9, s38, 0x100
	v_cndmask_b32_e64 v4, 0, 1, s[56:57]
	s_addc_u32 s10, s39, 0
	v_cmp_ne_u32_e64 s[36:37], 1, v4
	s_add_u32 s38, s40, 0x40080
	s_addc_u32 s39, s41, 0
	s_mov_b32 s11, -2
	s_waitcnt lgkmcnt(0)
	s_add_u32 s12, s38, 0xfffc0080
	s_addc_u32 s13, s39, -1
	s_add_i32 s14, 0, 0x10000
	s_cmp_eq_u32 s11, 12
	s_cselect_b32 s57, s5, s13
	s_cselect_b32 s56, s6, s12
	s_cselect_b32 s41, s7, s10
	s_cselect_b32 s40, s8, s9
	s_add_i32 s15, 0, 0x14000
	v_add_u32_e32 v144, s14, v230
	v_add_u32_e32 v160, s15, v230
	ds_read_b128 v[124:127], v144
	ds_read_b128 v[128:131], v144 offset:1024
	ds_read_b128 v[136:139], v144 offset:2048
	ds_read_b128 v[144:147], v144 offset:3072
	ds_read_b128 v[148:151], v160
	ds_read_b128 v[152:155], v160 offset:1024
	ds_read_b128 v[156:159], v160 offset:2048
	ds_read_b128 v[160:163], v160 offset:3072
	v_lshl_add_u64 v[196:197], s[38:39], 0, v[222:223]
	s_add_i32 m0, s71, 0xc000
	ds_read_b128 v[164:167], v243
	ds_read_b128 v[168:171], v243 offset:1024
	ds_read_b128 v[172:175], v243 offset:2048
	ds_read_b128 v[176:179], v243 offset:3072
	ds_read_b128 v[180:183], v243 offset:4096
	ds_read_b128 v[184:187], v243 offset:5120
	ds_read_b128 v[188:191], v243 offset:6144
	ds_read_b128 v[192:195], v243 offset:7168
	global_load_lds_dwordx4 v[196:197], off
	v_lshl_add_u64 v[196:197], s[38:39], 0, v[220:221]
	s_add_i32 m0, s71, 0xe000
	s_nop 0
	global_load_lds_dwordx4 v[196:197], off
	s_waitcnt vmcnt(8)
	s_waitcnt lgkmcnt(0)
	s_barrier
	s_setprio 1
	v_mfma_f32_16x16x32_bf16 v[140:143], v[124:127], v[164:167], 0
	v_mfma_f32_16x16x32_bf16 v[132:135], v[136:139], v[164:167], 0
	v_mfma_f32_16x16x32_bf16 v[112:115], v[124:127], v[172:175], 0
	v_mfma_f32_16x16x32_bf16 v[108:111], v[136:139], v[172:175], 0
	v_mfma_f32_16x16x32_bf16 v[96:99], v[124:127], v[180:183], 0
	v_mfma_f32_16x16x32_bf16 v[92:95], v[136:139], v[180:183], 0
	v_mfma_f32_16x16x32_bf16 v[80:83], v[124:127], v[188:191], 0
	v_mfma_f32_16x16x32_bf16 v[76:79], v[136:139], v[188:191], 0
	v_mfma_f32_16x16x32_bf16 v[140:143], v[128:131], v[168:171], v[140:143]
	v_mfma_f32_16x16x32_bf16 v[132:135], v[144:147], v[168:171], v[132:135]
	v_mfma_f32_16x16x32_bf16 v[112:115], v[128:131], v[176:179], v[112:115]
	v_mfma_f32_16x16x32_bf16 v[108:111], v[144:147], v[176:179], v[108:111]
	v_mfma_f32_16x16x32_bf16 v[96:99], v[128:131], v[184:187], v[96:99]
	v_mfma_f32_16x16x32_bf16 v[92:95], v[144:147], v[184:187], v[92:95]
	v_mfma_f32_16x16x32_bf16 v[80:83], v[128:131], v[192:195], v[80:83]
	v_mfma_f32_16x16x32_bf16 v[76:79], v[144:147], v[192:195], v[76:79]
	s_setprio 0
	s_setprio 1
	v_mfma_f32_16x16x32_bf16 v[120:123], v[148:151], v[164:167], 0
	v_mfma_f32_16x16x32_bf16 v[116:119], v[156:159], v[164:167], 0
	v_mfma_f32_16x16x32_bf16 v[104:107], v[148:151], v[172:175], 0
	v_mfma_f32_16x16x32_bf16 v[100:103], v[156:159], v[172:175], 0
	v_mfma_f32_16x16x32_bf16 v[88:91], v[148:151], v[180:183], 0
	v_mfma_f32_16x16x32_bf16 v[84:87], v[156:159], v[180:183], 0
	v_mfma_f32_16x16x32_bf16 v[72:75], v[148:151], v[188:191], 0
	v_mfma_f32_16x16x32_bf16 v[68:71], v[156:159], v[188:191], 0
	v_mfma_f32_16x16x32_bf16 v[120:123], v[152:155], v[168:171], v[120:123]
	v_mfma_f32_16x16x32_bf16 v[116:119], v[160:163], v[168:171], v[116:119]
	v_mfma_f32_16x16x32_bf16 v[104:107], v[152:155], v[176:179], v[104:107]
	v_mfma_f32_16x16x32_bf16 v[100:103], v[160:163], v[176:179], v[100:103]
	v_mfma_f32_16x16x32_bf16 v[88:91], v[152:155], v[184:187], v[88:91]
	v_mfma_f32_16x16x32_bf16 v[84:87], v[160:163], v[184:187], v[84:87]
	v_mfma_f32_16x16x32_bf16 v[72:75], v[152:155], v[192:195], v[72:75]
	v_mfma_f32_16x16x32_bf16 v[68:71], v[160:163], v[192:195], v[68:71]
	s_barrier
	s_setprio 0
	s_add_i32 s12, s14, s70
	v_lshl_add_u64 v[196:197], s[40:41], 0, v[2:3]
	s_mov_b32 m0, s12
	ds_read_b128 v[164:167], v243 offset:16384
	ds_read_b128 v[168:171], v243 offset:17408
	ds_read_b128 v[172:175], v243 offset:18432
	ds_read_b128 v[176:179], v243 offset:19456
	ds_read_b128 v[180:183], v243 offset:20480
	ds_read_b128 v[184:187], v243 offset:21504
	ds_read_b128 v[188:191], v243 offset:22528
	ds_read_b128 v[192:195], v243 offset:23552
	global_load_lds_dwordx4 v[196:197], off
	s_add_i32 m0, s12, 0x2000
	s_add_u32 s12, s40, 0x40000
	v_lshl_add_u64 v[198:199], s[40:41], 0, v[218:219]
	s_addc_u32 s13, s41, 0
	s_add_i32 s14, s15, s70
	global_load_lds_dwordx4 v[198:199], off
	v_lshl_add_u64 v[200:201], s[12:13], 0, v[2:3]
	s_mov_b32 m0, s14
	v_lshl_add_u64 v[202:203], s[56:57], 0, v[216:217]
	global_load_lds_dwordx4 v[200:201], off
	v_lshl_add_u64 v[200:201], s[12:13], 0, v[218:219]
	s_add_i32 m0, s14, 0x2000
	s_nop 0
	global_load_lds_dwordx4 v[200:201], off
	v_lshl_add_u64 v[200:201], s[56:57], 0, v[0:1]
	s_mov_b32 m0, s71
	s_nop 0
	global_load_lds_dwordx4 v[200:201], off
	s_mov_b32 m0, s80
	s_nop 0
	global_load_lds_dwordx4 v[202:203], off
	s_waitcnt vmcnt(8)
	s_waitcnt lgkmcnt(0)
	s_barrier
	s_setprio 1
	v_mfma_f32_16x16x32_bf16 v[64:67], v[124:127], v[164:167], 0
	v_mfma_f32_16x16x32_bf16 v[60:63], v[136:139], v[164:167], 0
	v_mfma_f32_16x16x32_bf16 v[48:51], v[124:127], v[172:175], 0
	v_mfma_f32_16x16x32_bf16 v[44:47], v[136:139], v[172:175], 0
	v_mfma_f32_16x16x32_bf16 v[32:35], v[124:127], v[180:183], 0
	v_mfma_f32_16x16x32_bf16 v[28:31], v[136:139], v[180:183], 0
	v_mfma_f32_16x16x32_bf16 v[16:19], v[124:127], v[188:191], 0
	v_mfma_f32_16x16x32_bf16 v[12:15], v[136:139], v[188:191], 0
	v_mfma_f32_16x16x32_bf16 v[64:67], v[128:131], v[168:171], v[64:67]
	v_mfma_f32_16x16x32_bf16 v[60:63], v[144:147], v[168:171], v[60:63]
	v_mfma_f32_16x16x32_bf16 v[48:51], v[128:131], v[176:179], v[48:51]
	v_mfma_f32_16x16x32_bf16 v[44:47], v[144:147], v[176:179], v[44:47]
	v_mfma_f32_16x16x32_bf16 v[32:35], v[128:131], v[184:187], v[32:35]
	v_mfma_f32_16x16x32_bf16 v[28:31], v[144:147], v[184:187], v[28:31]
	v_mfma_f32_16x16x32_bf16 v[16:19], v[128:131], v[192:195], v[16:19]
	v_mfma_f32_16x16x32_bf16 v[12:15], v[144:147], v[192:195], v[12:15]
	s_setprio 0
	s_setprio 1
	v_mfma_f32_16x16x32_bf16 v[56:59], v[148:151], v[164:167], 0
	v_mfma_f32_16x16x32_bf16 v[52:55], v[156:159], v[164:167], 0
	v_mfma_f32_16x16x32_bf16 v[40:43], v[148:151], v[172:175], 0
	v_mfma_f32_16x16x32_bf16 v[36:39], v[156:159], v[172:175], 0
	v_mfma_f32_16x16x32_bf16 v[24:27], v[148:151], v[180:183], 0
	v_mfma_f32_16x16x32_bf16 v[20:23], v[156:159], v[180:183], 0
	v_mfma_f32_16x16x32_bf16 v[8:11], v[148:151], v[188:191], 0
	v_mfma_f32_16x16x32_bf16 v[4:7], v[156:159], v[188:191], 0
	v_mfma_f32_16x16x32_bf16 v[56:59], v[152:155], v[168:171], v[56:59]
	v_mfma_f32_16x16x32_bf16 v[52:55], v[160:163], v[168:171], v[52:55]
	v_mfma_f32_16x16x32_bf16 v[40:43], v[152:155], v[176:179], v[40:43]
	v_mfma_f32_16x16x32_bf16 v[36:39], v[160:163], v[176:179], v[36:39]
	v_mfma_f32_16x16x32_bf16 v[24:27], v[152:155], v[184:187], v[24:27]
	v_mfma_f32_16x16x32_bf16 v[20:23], v[160:163], v[184:187], v[20:23]
	v_mfma_f32_16x16x32_bf16 v[8:11], v[152:155], v[192:195], v[8:11]
	v_mfma_f32_16x16x32_bf16 v[4:7], v[160:163], v[192:195], v[4:7]
	s_barrier
	s_setprio 0
	s_add_i32 s14, 0, 0x18000
	s_add_i32 s15, 0, 0x1c000
	v_add_u32_e32 v144, s14, v230
	v_add_u32_e32 v160, s15, v230
	ds_read_b128 v[124:127], v144
	ds_read_b128 v[128:131], v144 offset:1024
	ds_read_b128 v[136:139], v144 offset:2048
	ds_read_b128 v[144:147], v144 offset:3072
	ds_read_b128 v[148:151], v160
	ds_read_b128 v[152:155], v160 offset:1024
	ds_read_b128 v[156:159], v160 offset:2048
	ds_read_b128 v[160:163], v160 offset:3072
	s_add_u32 s12, s56, 0x40000
	s_addc_u32 s13, s57, 0
	s_mov_b32 m0, s81
	v_lshl_add_u64 v[204:205], s[12:13], 0, v[0:1]
	ds_read_b128 v[164:167], v243 offset:32768
	ds_read_b128 v[168:171], v243 offset:33792
	ds_read_b128 v[172:175], v243 offset:34816
	ds_read_b128 v[176:179], v243 offset:35840
	ds_read_b128 v[180:183], v243 offset:36864
	ds_read_b128 v[184:187], v243 offset:37888
	ds_read_b128 v[188:191], v243 offset:38912
	ds_read_b128 v[192:195], v243 offset:39936
	global_load_lds_dwordx4 v[204:205], off
	v_lshl_add_u64 v[204:205], s[12:13], 0, v[216:217]
	s_mov_b32 m0, s82
	s_nop 0
	global_load_lds_dwordx4 v[204:205], off
	s_waitcnt vmcnt(8)
	s_waitcnt lgkmcnt(0)
	s_barrier
	s_setprio 1
	v_mfma_f32_16x16x32_bf16 v[140:143], v[124:127], v[164:167], v[140:143]
	v_mfma_f32_16x16x32_bf16 v[132:135], v[136:139], v[164:167], v[132:135]
	v_mfma_f32_16x16x32_bf16 v[112:115], v[124:127], v[172:175], v[112:115]
	v_mfma_f32_16x16x32_bf16 v[108:111], v[136:139], v[172:175], v[108:111]
	v_mfma_f32_16x16x32_bf16 v[96:99], v[124:127], v[180:183], v[96:99]
	v_mfma_f32_16x16x32_bf16 v[92:95], v[136:139], v[180:183], v[92:95]
	v_mfma_f32_16x16x32_bf16 v[80:83], v[124:127], v[188:191], v[80:83]
	v_mfma_f32_16x16x32_bf16 v[76:79], v[136:139], v[188:191], v[76:79]
	v_mfma_f32_16x16x32_bf16 v[140:143], v[128:131], v[168:171], v[140:143]
	v_mfma_f32_16x16x32_bf16 v[132:135], v[144:147], v[168:171], v[132:135]
	v_mfma_f32_16x16x32_bf16 v[112:115], v[128:131], v[176:179], v[112:115]
	v_mfma_f32_16x16x32_bf16 v[108:111], v[144:147], v[176:179], v[108:111]
	v_mfma_f32_16x16x32_bf16 v[96:99], v[128:131], v[184:187], v[96:99]
	v_mfma_f32_16x16x32_bf16 v[92:95], v[144:147], v[184:187], v[92:95]
	v_mfma_f32_16x16x32_bf16 v[80:83], v[128:131], v[192:195], v[80:83]
	v_mfma_f32_16x16x32_bf16 v[76:79], v[144:147], v[192:195], v[76:79]
	s_setprio 0
	s_setprio 1
	v_mfma_f32_16x16x32_bf16 v[120:123], v[148:151], v[164:167], v[120:123]
	v_mfma_f32_16x16x32_bf16 v[116:119], v[156:159], v[164:167], v[116:119]
	v_mfma_f32_16x16x32_bf16 v[104:107], v[148:151], v[172:175], v[104:107]
	v_mfma_f32_16x16x32_bf16 v[100:103], v[156:159], v[172:175], v[100:103]
	v_mfma_f32_16x16x32_bf16 v[88:91], v[148:151], v[180:183], v[88:91]
	v_mfma_f32_16x16x32_bf16 v[84:87], v[156:159], v[180:183], v[84:87]
	v_mfma_f32_16x16x32_bf16 v[72:75], v[148:151], v[188:191], v[72:75]
	v_mfma_f32_16x16x32_bf16 v[68:71], v[156:159], v[188:191], v[68:71]
	v_mfma_f32_16x16x32_bf16 v[120:123], v[152:155], v[168:171], v[120:123]
	v_mfma_f32_16x16x32_bf16 v[116:119], v[160:163], v[168:171], v[116:119]
	v_mfma_f32_16x16x32_bf16 v[104:107], v[152:155], v[176:179], v[104:107]
	v_mfma_f32_16x16x32_bf16 v[100:103], v[160:163], v[176:179], v[100:103]
	v_mfma_f32_16x16x32_bf16 v[88:91], v[152:155], v[184:187], v[88:91]
	v_mfma_f32_16x16x32_bf16 v[84:87], v[160:163], v[184:187], v[84:87]
	v_mfma_f32_16x16x32_bf16 v[72:75], v[152:155], v[192:195], v[72:75]
	v_mfma_f32_16x16x32_bf16 v[68:71], v[160:163], v[192:195], v[68:71]
	s_barrier
	s_setprio 0
	s_add_i32 s12, s14, s70
	v_lshl_add_u64 v[196:197], v[196:197], 0, s[68:69]
	s_mov_b32 m0, s12
	ds_read_b128 v[164:167], v243 offset:49152
	ds_read_b128 v[168:171], v243 offset:50176
	ds_read_b128 v[172:175], v243 offset:51200
	ds_read_b128 v[176:179], v243 offset:52224
	ds_read_b128 v[180:183], v243 offset:53248
	ds_read_b128 v[184:187], v243 offset:54272
	ds_read_b128 v[188:191], v243 offset:55296
	ds_read_b128 v[192:195], v243 offset:56320
	global_load_lds_dwordx4 v[196:197], off
	s_add_i32 m0, s12, 0x2000
	s_add_u32 s12, s40, 0x40080
	v_lshl_add_u64 v[196:197], v[198:199], 0, s[68:69]
	s_addc_u32 s13, s41, 0
	s_add_i32 s14, s15, s70
	global_load_lds_dwordx4 v[196:197], off
	v_lshl_add_u64 v[196:197], s[12:13], 0, v[2:3]
	s_mov_b32 m0, s14
	s_nop 0
	global_load_lds_dwordx4 v[196:197], off
	v_lshl_add_u64 v[196:197], s[12:13], 0, v[218:219]
	s_add_i32 m0, s14, 0x2000
	s_nop 0
	global_load_lds_dwordx4 v[196:197], off
	v_lshl_add_u64 v[196:197], v[200:201], 0, s[68:69]
	s_mov_b32 m0, s85
	s_nop 0
	global_load_lds_dwordx4 v[196:197], off
	v_lshl_add_u64 v[196:197], v[202:203], 0, s[68:69]
	s_mov_b32 m0, s87
	s_nop 0
	global_load_lds_dwordx4 v[196:197], off
	s_waitcnt vmcnt(8)
	s_waitcnt lgkmcnt(0)
	s_barrier
	s_setprio 1
	v_mfma_f32_16x16x32_bf16 v[64:67], v[124:127], v[164:167], v[64:67]
	v_mfma_f32_16x16x32_bf16 v[60:63], v[136:139], v[164:167], v[60:63]
	v_mfma_f32_16x16x32_bf16 v[48:51], v[124:127], v[172:175], v[48:51]
	v_mfma_f32_16x16x32_bf16 v[44:47], v[136:139], v[172:175], v[44:47]
	v_mfma_f32_16x16x32_bf16 v[32:35], v[124:127], v[180:183], v[32:35]
	v_mfma_f32_16x16x32_bf16 v[28:31], v[136:139], v[180:183], v[28:31]
	v_mfma_f32_16x16x32_bf16 v[16:19], v[124:127], v[188:191], v[16:19]
	v_mfma_f32_16x16x32_bf16 v[12:15], v[136:139], v[188:191], v[12:15]
	v_mfma_f32_16x16x32_bf16 v[64:67], v[128:131], v[168:171], v[64:67]
	v_mfma_f32_16x16x32_bf16 v[60:63], v[144:147], v[168:171], v[60:63]
	v_mfma_f32_16x16x32_bf16 v[48:51], v[128:131], v[176:179], v[48:51]
	v_mfma_f32_16x16x32_bf16 v[44:47], v[144:147], v[176:179], v[44:47]
	v_mfma_f32_16x16x32_bf16 v[32:35], v[128:131], v[184:187], v[32:35]
	v_mfma_f32_16x16x32_bf16 v[28:31], v[144:147], v[184:187], v[28:31]
	v_mfma_f32_16x16x32_bf16 v[16:19], v[128:131], v[192:195], v[16:19]
	v_mfma_f32_16x16x32_bf16 v[12:15], v[144:147], v[192:195], v[12:15]
	s_setprio 0
	s_setprio 1
	v_mfma_f32_16x16x32_bf16 v[56:59], v[148:151], v[164:167], v[56:59]
	v_mfma_f32_16x16x32_bf16 v[52:55], v[156:159], v[164:167], v[52:55]
	v_mfma_f32_16x16x32_bf16 v[40:43], v[148:151], v[172:175], v[40:43]
	v_mfma_f32_16x16x32_bf16 v[36:39], v[156:159], v[172:175], v[36:39]
	v_mfma_f32_16x16x32_bf16 v[24:27], v[148:151], v[180:183], v[24:27]
	v_mfma_f32_16x16x32_bf16 v[20:23], v[156:159], v[180:183], v[20:23]
	v_mfma_f32_16x16x32_bf16 v[8:11], v[148:151], v[188:191], v[8:11]
	v_mfma_f32_16x16x32_bf16 v[4:7], v[156:159], v[188:191], v[4:7]
	v_mfma_f32_16x16x32_bf16 v[56:59], v[152:155], v[168:171], v[56:59]
	v_mfma_f32_16x16x32_bf16 v[52:55], v[160:163], v[168:171], v[52:55]
	v_mfma_f32_16x16x32_bf16 v[40:43], v[152:155], v[176:179], v[40:43]
	v_mfma_f32_16x16x32_bf16 v[36:39], v[160:163], v[176:179], v[36:39]
	v_mfma_f32_16x16x32_bf16 v[24:27], v[152:155], v[184:187], v[24:27]
	v_mfma_f32_16x16x32_bf16 v[20:23], v[160:163], v[184:187], v[20:23]
	v_mfma_f32_16x16x32_bf16 v[8:11], v[152:155], v[192:195], v[8:11]
	v_mfma_f32_16x16x32_bf16 v[4:7], v[160:163], v[192:195], v[4:7]
	s_barrier
	s_setprio 0
	s_add_i32 s11, s11, 2
	s_add_u32 s9, s9, 0x100
	s_addc_u32 s10, s10, 0
	s_add_u32 s38, s38, 0x100
	s_addc_u32 s39, s39, 0
	s_cmp_gt_u32 s11, 13
.LBB0_947:
	s_add_u32 s12, s38, 0xfffc0080
	s_addc_u32 s13, s39, -1
	s_add_i32 s14, 0, 0x10000
	s_cmp_eq_u32 s11, 12
	s_cselect_b32 s57, s5, s13
	s_cselect_b32 s56, s6, s12
	s_cselect_b32 s41, s7, s10
	s_cselect_b32 s40, s8, s9
	s_add_i32 s15, 0, 0x14000
	v_add_u32_e32 v144, s14, v230
	v_add_u32_e32 v160, s15, v230
	ds_read_b128 v[124:127], v144
	ds_read_b128 v[128:131], v144 offset:1024
	ds_read_b128 v[136:139], v144 offset:2048
	ds_read_b128 v[144:147], v144 offset:3072
	ds_read_b128 v[148:151], v160
	ds_read_b128 v[152:155], v160 offset:1024
	ds_read_b128 v[156:159], v160 offset:2048
	ds_read_b128 v[160:163], v160 offset:3072
	v_lshl_add_u64 v[196:197], s[38:39], 0, v[222:223]
	s_add_i32 m0, s71, 0xc000
	ds_read_b128 v[164:167], v243
	ds_read_b128 v[168:171], v243 offset:1024
	ds_read_b128 v[172:175], v243 offset:2048
	ds_read_b128 v[176:179], v243 offset:3072
	ds_read_b128 v[180:183], v243 offset:4096
	ds_read_b128 v[184:187], v243 offset:5120
	ds_read_b128 v[188:191], v243 offset:6144
	ds_read_b128 v[192:195], v243 offset:7168
	global_load_lds_dwordx4 v[196:197], off
	v_lshl_add_u64 v[196:197], s[38:39], 0, v[220:221]
	s_add_i32 m0, s71, 0xe000
	s_nop 0
	global_load_lds_dwordx4 v[196:197], off
	s_waitcnt vmcnt(8)
	s_waitcnt lgkmcnt(0)
	s_barrier
	s_setprio 1
	v_mfma_f32_16x16x32_bf16 v[140:143], v[124:127], v[164:167], v[140:143]
	v_mfma_f32_16x16x32_bf16 v[132:135], v[136:139], v[164:167], v[132:135]
	v_mfma_f32_16x16x32_bf16 v[112:115], v[124:127], v[172:175], v[112:115]
	v_mfma_f32_16x16x32_bf16 v[108:111], v[136:139], v[172:175], v[108:111]
	v_mfma_f32_16x16x32_bf16 v[96:99], v[124:127], v[180:183], v[96:99]
	v_mfma_f32_16x16x32_bf16 v[92:95], v[136:139], v[180:183], v[92:95]
	v_mfma_f32_16x16x32_bf16 v[80:83], v[124:127], v[188:191], v[80:83]
	v_mfma_f32_16x16x32_bf16 v[76:79], v[136:139], v[188:191], v[76:79]
	v_mfma_f32_16x16x32_bf16 v[140:143], v[128:131], v[168:171], v[140:143]
	v_mfma_f32_16x16x32_bf16 v[132:135], v[144:147], v[168:171], v[132:135]
	v_mfma_f32_16x16x32_bf16 v[112:115], v[128:131], v[176:179], v[112:115]
	v_mfma_f32_16x16x32_bf16 v[108:111], v[144:147], v[176:179], v[108:111]
	v_mfma_f32_16x16x32_bf16 v[96:99], v[128:131], v[184:187], v[96:99]
	v_mfma_f32_16x16x32_bf16 v[92:95], v[144:147], v[184:187], v[92:95]
	v_mfma_f32_16x16x32_bf16 v[80:83], v[128:131], v[192:195], v[80:83]
	v_mfma_f32_16x16x32_bf16 v[76:79], v[144:147], v[192:195], v[76:79]
	s_setprio 0
	s_setprio 1
	v_mfma_f32_16x16x32_bf16 v[120:123], v[148:151], v[164:167], v[120:123]
	v_mfma_f32_16x16x32_bf16 v[116:119], v[156:159], v[164:167], v[116:119]
	v_mfma_f32_16x16x32_bf16 v[104:107], v[148:151], v[172:175], v[104:107]
	v_mfma_f32_16x16x32_bf16 v[100:103], v[156:159], v[172:175], v[100:103]
	v_mfma_f32_16x16x32_bf16 v[88:91], v[148:151], v[180:183], v[88:91]
	v_mfma_f32_16x16x32_bf16 v[84:87], v[156:159], v[180:183], v[84:87]
	v_mfma_f32_16x16x32_bf16 v[72:75], v[148:151], v[188:191], v[72:75]
	v_mfma_f32_16x16x32_bf16 v[68:71], v[156:159], v[188:191], v[68:71]
	v_mfma_f32_16x16x32_bf16 v[120:123], v[152:155], v[168:171], v[120:123]
	v_mfma_f32_16x16x32_bf16 v[116:119], v[160:163], v[168:171], v[116:119]
	v_mfma_f32_16x16x32_bf16 v[104:107], v[152:155], v[176:179], v[104:107]
	v_mfma_f32_16x16x32_bf16 v[100:103], v[160:163], v[176:179], v[100:103]
	v_mfma_f32_16x16x32_bf16 v[88:91], v[152:155], v[184:187], v[88:91]
	v_mfma_f32_16x16x32_bf16 v[84:87], v[160:163], v[184:187], v[84:87]
	v_mfma_f32_16x16x32_bf16 v[72:75], v[152:155], v[192:195], v[72:75]
	v_mfma_f32_16x16x32_bf16 v[68:71], v[160:163], v[192:195], v[68:71]
	s_barrier
	s_setprio 0
	s_add_i32 s12, s14, s70
	v_lshl_add_u64 v[196:197], s[40:41], 0, v[2:3]
	s_mov_b32 m0, s12
	ds_read_b128 v[164:167], v243 offset:16384
	ds_read_b128 v[168:171], v243 offset:17408
	ds_read_b128 v[172:175], v243 offset:18432
	ds_read_b128 v[176:179], v243 offset:19456
	ds_read_b128 v[180:183], v243 offset:20480
	ds_read_b128 v[184:187], v243 offset:21504
	ds_read_b128 v[188:191], v243 offset:22528
	ds_read_b128 v[192:195], v243 offset:23552
	global_load_lds_dwordx4 v[196:197], off
	s_add_i32 m0, s12, 0x2000
	s_add_u32 s12, s40, 0x40000
	v_lshl_add_u64 v[198:199], s[40:41], 0, v[218:219]
	s_addc_u32 s13, s41, 0
	s_add_i32 s14, s15, s70
	global_load_lds_dwordx4 v[198:199], off
	v_lshl_add_u64 v[200:201], s[12:13], 0, v[2:3]
	s_mov_b32 m0, s14
	v_lshl_add_u64 v[202:203], s[56:57], 0, v[216:217]
	global_load_lds_dwordx4 v[200:201], off
	v_lshl_add_u64 v[200:201], s[12:13], 0, v[218:219]
	s_add_i32 m0, s14, 0x2000
	s_nop 0
	global_load_lds_dwordx4 v[200:201], off
	v_lshl_add_u64 v[200:201], s[56:57], 0, v[0:1]
	s_mov_b32 m0, s71
	s_nop 0
	global_load_lds_dwordx4 v[200:201], off
	s_mov_b32 m0, s80
	s_nop 0
	global_load_lds_dwordx4 v[202:203], off
	s_waitcnt vmcnt(8)
	s_waitcnt lgkmcnt(0)
	s_barrier
	s_setprio 1
	v_mfma_f32_16x16x32_bf16 v[64:67], v[124:127], v[164:167], v[64:67]
	v_mfma_f32_16x16x32_bf16 v[60:63], v[136:139], v[164:167], v[60:63]
	v_mfma_f32_16x16x32_bf16 v[48:51], v[124:127], v[172:175], v[48:51]
	v_mfma_f32_16x16x32_bf16 v[44:47], v[136:139], v[172:175], v[44:47]
	v_mfma_f32_16x16x32_bf16 v[32:35], v[124:127], v[180:183], v[32:35]
	v_mfma_f32_16x16x32_bf16 v[28:31], v[136:139], v[180:183], v[28:31]
	v_mfma_f32_16x16x32_bf16 v[16:19], v[124:127], v[188:191], v[16:19]
	v_mfma_f32_16x16x32_bf16 v[12:15], v[136:139], v[188:191], v[12:15]
	v_mfma_f32_16x16x32_bf16 v[64:67], v[128:131], v[168:171], v[64:67]
	v_mfma_f32_16x16x32_bf16 v[60:63], v[144:147], v[168:171], v[60:63]
	v_mfma_f32_16x16x32_bf16 v[48:51], v[128:131], v[176:179], v[48:51]
	v_mfma_f32_16x16x32_bf16 v[44:47], v[144:147], v[176:179], v[44:47]
	v_mfma_f32_16x16x32_bf16 v[32:35], v[128:131], v[184:187], v[32:35]
	v_mfma_f32_16x16x32_bf16 v[28:31], v[144:147], v[184:187], v[28:31]
	v_mfma_f32_16x16x32_bf16 v[16:19], v[128:131], v[192:195], v[16:19]
	v_mfma_f32_16x16x32_bf16 v[12:15], v[144:147], v[192:195], v[12:15]
	s_setprio 0
	s_setprio 1
	v_mfma_f32_16x16x32_bf16 v[56:59], v[148:151], v[164:167], v[56:59]
	v_mfma_f32_16x16x32_bf16 v[52:55], v[156:159], v[164:167], v[52:55]
	v_mfma_f32_16x16x32_bf16 v[40:43], v[148:151], v[172:175], v[40:43]
	v_mfma_f32_16x16x32_bf16 v[36:39], v[156:159], v[172:175], v[36:39]
	v_mfma_f32_16x16x32_bf16 v[24:27], v[148:151], v[180:183], v[24:27]
	v_mfma_f32_16x16x32_bf16 v[20:23], v[156:159], v[180:183], v[20:23]
	v_mfma_f32_16x16x32_bf16 v[8:11], v[148:151], v[188:191], v[8:11]
	v_mfma_f32_16x16x32_bf16 v[4:7], v[156:159], v[188:191], v[4:7]
	v_mfma_f32_16x16x32_bf16 v[56:59], v[152:155], v[168:171], v[56:59]
	v_mfma_f32_16x16x32_bf16 v[52:55], v[160:163], v[168:171], v[52:55]
	v_mfma_f32_16x16x32_bf16 v[40:43], v[152:155], v[176:179], v[40:43]
	v_mfma_f32_16x16x32_bf16 v[36:39], v[160:163], v[176:179], v[36:39]
	v_mfma_f32_16x16x32_bf16 v[24:27], v[152:155], v[184:187], v[24:27]
	v_mfma_f32_16x16x32_bf16 v[20:23], v[160:163], v[184:187], v[20:23]
	v_mfma_f32_16x16x32_bf16 v[8:11], v[152:155], v[192:195], v[8:11]
	v_mfma_f32_16x16x32_bf16 v[4:7], v[160:163], v[192:195], v[4:7]
	s_barrier
	s_setprio 0
	s_add_i32 s14, 0, 0x18000
	s_add_i32 s15, 0, 0x1c000
	v_add_u32_e32 v144, s14, v230
	v_add_u32_e32 v160, s15, v230
	ds_read_b128 v[124:127], v144
	ds_read_b128 v[128:131], v144 offset:1024
	ds_read_b128 v[136:139], v144 offset:2048
	ds_read_b128 v[144:147], v144 offset:3072
	ds_read_b128 v[148:151], v160
	ds_read_b128 v[152:155], v160 offset:1024
	ds_read_b128 v[156:159], v160 offset:2048
	ds_read_b128 v[160:163], v160 offset:3072
	s_add_u32 s12, s56, 0x40000
	s_addc_u32 s13, s57, 0
	s_mov_b32 m0, s81
	v_lshl_add_u64 v[204:205], s[12:13], 0, v[0:1]
	ds_read_b128 v[164:167], v243 offset:32768
	ds_read_b128 v[168:171], v243 offset:33792
	ds_read_b128 v[172:175], v243 offset:34816
	ds_read_b128 v[176:179], v243 offset:35840
	ds_read_b128 v[180:183], v243 offset:36864
	ds_read_b128 v[184:187], v243 offset:37888
	ds_read_b128 v[188:191], v243 offset:38912
	ds_read_b128 v[192:195], v243 offset:39936
	global_load_lds_dwordx4 v[204:205], off
	v_lshl_add_u64 v[204:205], s[12:13], 0, v[216:217]
	s_mov_b32 m0, s82
	s_nop 0
	global_load_lds_dwordx4 v[204:205], off
	s_waitcnt vmcnt(8)
	s_waitcnt lgkmcnt(0)
	s_barrier
	s_setprio 1
	v_mfma_f32_16x16x32_bf16 v[140:143], v[124:127], v[164:167], v[140:143]
	v_mfma_f32_16x16x32_bf16 v[132:135], v[136:139], v[164:167], v[132:135]
	v_mfma_f32_16x16x32_bf16 v[112:115], v[124:127], v[172:175], v[112:115]
	v_mfma_f32_16x16x32_bf16 v[108:111], v[136:139], v[172:175], v[108:111]
	v_mfma_f32_16x16x32_bf16 v[96:99], v[124:127], v[180:183], v[96:99]
	v_mfma_f32_16x16x32_bf16 v[92:95], v[136:139], v[180:183], v[92:95]
	v_mfma_f32_16x16x32_bf16 v[80:83], v[124:127], v[188:191], v[80:83]
	v_mfma_f32_16x16x32_bf16 v[76:79], v[136:139], v[188:191], v[76:79]
	v_mfma_f32_16x16x32_bf16 v[140:143], v[128:131], v[168:171], v[140:143]
	v_mfma_f32_16x16x32_bf16 v[132:135], v[144:147], v[168:171], v[132:135]
	v_mfma_f32_16x16x32_bf16 v[112:115], v[128:131], v[176:179], v[112:115]
	v_mfma_f32_16x16x32_bf16 v[108:111], v[144:147], v[176:179], v[108:111]
	v_mfma_f32_16x16x32_bf16 v[96:99], v[128:131], v[184:187], v[96:99]
	v_mfma_f32_16x16x32_bf16 v[92:95], v[144:147], v[184:187], v[92:95]
	v_mfma_f32_16x16x32_bf16 v[80:83], v[128:131], v[192:195], v[80:83]
	v_mfma_f32_16x16x32_bf16 v[76:79], v[144:147], v[192:195], v[76:79]
	s_setprio 0
	s_setprio 1
	v_mfma_f32_16x16x32_bf16 v[120:123], v[148:151], v[164:167], v[120:123]
	v_mfma_f32_16x16x32_bf16 v[116:119], v[156:159], v[164:167], v[116:119]
	v_mfma_f32_16x16x32_bf16 v[104:107], v[148:151], v[172:175], v[104:107]
	v_mfma_f32_16x16x32_bf16 v[100:103], v[156:159], v[172:175], v[100:103]
	v_mfma_f32_16x16x32_bf16 v[88:91], v[148:151], v[180:183], v[88:91]
	v_mfma_f32_16x16x32_bf16 v[84:87], v[156:159], v[180:183], v[84:87]
	v_mfma_f32_16x16x32_bf16 v[72:75], v[148:151], v[188:191], v[72:75]
	v_mfma_f32_16x16x32_bf16 v[68:71], v[156:159], v[188:191], v[68:71]
	v_mfma_f32_16x16x32_bf16 v[120:123], v[152:155], v[168:171], v[120:123]
	v_mfma_f32_16x16x32_bf16 v[116:119], v[160:163], v[168:171], v[116:119]
	v_mfma_f32_16x16x32_bf16 v[104:107], v[152:155], v[176:179], v[104:107]
	v_mfma_f32_16x16x32_bf16 v[100:103], v[160:163], v[176:179], v[100:103]
	v_mfma_f32_16x16x32_bf16 v[88:91], v[152:155], v[184:187], v[88:91]
	v_mfma_f32_16x16x32_bf16 v[84:87], v[160:163], v[184:187], v[84:87]
	v_mfma_f32_16x16x32_bf16 v[72:75], v[152:155], v[192:195], v[72:75]
	v_mfma_f32_16x16x32_bf16 v[68:71], v[160:163], v[192:195], v[68:71]
	s_barrier
	s_setprio 0
	s_add_i32 s12, s14, s70
	v_lshl_add_u64 v[196:197], v[196:197], 0, s[68:69]
	s_mov_b32 m0, s12
	ds_read_b128 v[164:167], v243 offset:49152
	ds_read_b128 v[168:171], v243 offset:50176
	ds_read_b128 v[172:175], v243 offset:51200
	ds_read_b128 v[176:179], v243 offset:52224
	ds_read_b128 v[180:183], v243 offset:53248
	ds_read_b128 v[184:187], v243 offset:54272
	ds_read_b128 v[188:191], v243 offset:55296
	ds_read_b128 v[192:195], v243 offset:56320
	global_load_lds_dwordx4 v[196:197], off
	s_add_i32 m0, s12, 0x2000
	s_add_u32 s12, s40, 0x40080
	v_lshl_add_u64 v[196:197], v[198:199], 0, s[68:69]
	s_addc_u32 s13, s41, 0
	s_add_i32 s14, s15, s70
	global_load_lds_dwordx4 v[196:197], off
	v_lshl_add_u64 v[196:197], s[12:13], 0, v[2:3]
	s_mov_b32 m0, s14
	s_nop 0
	global_load_lds_dwordx4 v[196:197], off
	v_lshl_add_u64 v[196:197], s[12:13], 0, v[218:219]
	s_add_i32 m0, s14, 0x2000
	s_nop 0
	global_load_lds_dwordx4 v[196:197], off
	v_lshl_add_u64 v[196:197], v[200:201], 0, s[68:69]
	s_mov_b32 m0, s85
	s_nop 0
	global_load_lds_dwordx4 v[196:197], off
	v_lshl_add_u64 v[196:197], v[202:203], 0, s[68:69]
	s_mov_b32 m0, s87
	s_nop 0
	global_load_lds_dwordx4 v[196:197], off
	s_waitcnt vmcnt(8)
	s_waitcnt lgkmcnt(0)
	s_barrier
	s_setprio 1
	v_mfma_f32_16x16x32_bf16 v[64:67], v[124:127], v[164:167], v[64:67]
	v_mfma_f32_16x16x32_bf16 v[60:63], v[136:139], v[164:167], v[60:63]
	v_mfma_f32_16x16x32_bf16 v[48:51], v[124:127], v[172:175], v[48:51]
	v_mfma_f32_16x16x32_bf16 v[44:47], v[136:139], v[172:175], v[44:47]
	v_mfma_f32_16x16x32_bf16 v[32:35], v[124:127], v[180:183], v[32:35]
	v_mfma_f32_16x16x32_bf16 v[28:31], v[136:139], v[180:183], v[28:31]
	v_mfma_f32_16x16x32_bf16 v[16:19], v[124:127], v[188:191], v[16:19]
	v_mfma_f32_16x16x32_bf16 v[12:15], v[136:139], v[188:191], v[12:15]
	v_mfma_f32_16x16x32_bf16 v[64:67], v[128:131], v[168:171], v[64:67]
	v_mfma_f32_16x16x32_bf16 v[60:63], v[144:147], v[168:171], v[60:63]
	v_mfma_f32_16x16x32_bf16 v[48:51], v[128:131], v[176:179], v[48:51]
	v_mfma_f32_16x16x32_bf16 v[44:47], v[144:147], v[176:179], v[44:47]
	v_mfma_f32_16x16x32_bf16 v[32:35], v[128:131], v[184:187], v[32:35]
	v_mfma_f32_16x16x32_bf16 v[28:31], v[144:147], v[184:187], v[28:31]
	v_mfma_f32_16x16x32_bf16 v[16:19], v[128:131], v[192:195], v[16:19]
	v_mfma_f32_16x16x32_bf16 v[12:15], v[144:147], v[192:195], v[12:15]
	s_setprio 0
	s_setprio 1
	v_mfma_f32_16x16x32_bf16 v[56:59], v[148:151], v[164:167], v[56:59]
	v_mfma_f32_16x16x32_bf16 v[52:55], v[156:159], v[164:167], v[52:55]
	v_mfma_f32_16x16x32_bf16 v[40:43], v[148:151], v[172:175], v[40:43]
	v_mfma_f32_16x16x32_bf16 v[36:39], v[156:159], v[172:175], v[36:39]
	v_mfma_f32_16x16x32_bf16 v[24:27], v[148:151], v[180:183], v[24:27]
	v_mfma_f32_16x16x32_bf16 v[20:23], v[156:159], v[180:183], v[20:23]
	v_mfma_f32_16x16x32_bf16 v[8:11], v[148:151], v[188:191], v[8:11]
	v_mfma_f32_16x16x32_bf16 v[4:7], v[156:159], v[188:191], v[4:7]
	v_mfma_f32_16x16x32_bf16 v[56:59], v[152:155], v[168:171], v[56:59]
	v_mfma_f32_16x16x32_bf16 v[52:55], v[160:163], v[168:171], v[52:55]
	v_mfma_f32_16x16x32_bf16 v[40:43], v[152:155], v[176:179], v[40:43]
	v_mfma_f32_16x16x32_bf16 v[36:39], v[160:163], v[176:179], v[36:39]
	v_mfma_f32_16x16x32_bf16 v[24:27], v[152:155], v[184:187], v[24:27]
	v_mfma_f32_16x16x32_bf16 v[20:23], v[160:163], v[184:187], v[20:23]
	v_mfma_f32_16x16x32_bf16 v[8:11], v[152:155], v[192:195], v[8:11]
	v_mfma_f32_16x16x32_bf16 v[4:7], v[160:163], v[192:195], v[4:7]
	s_barrier
	s_setprio 0
	s_add_i32 s11, s11, 2
	s_add_u32 s9, s9, 0x100
	s_addc_u32 s10, s10, 0
	s_add_u32 s38, s38, 0x100
	s_addc_u32 s39, s39, 0
	s_cmp_gt_u32 s11, 13
	s_cbranch_scc0 .LBB0_947
	s_and_b64 vcc, exec, s[46:47]
	s_cbranch_vccz .LBB0_950
	s_barrier

.Lgu_skip1_p:
	s_waitcnt lgkmcnt(0)
	s_barrier
	s_setprio 1
	v_mfma_f32_16x16x32_bf16 v[124:127], v[142:145], v[184:187], 0
	v_mfma_f32_16x16x32_bf16 v[120:123], v[150:153], v[184:187], 0
	v_mfma_f32_16x16x32_bf16 v[112:115], v[142:145], v[192:195], 0
	v_mfma_f32_16x16x32_bf16 v[104:107], v[150:153], v[192:195], 0
	v_mfma_f32_16x16x32_bf16 v[96:99], v[142:145], v[200:203], 0
	v_mfma_f32_16x16x32_bf16 v[88:91], v[150:153], v[200:203], 0
	v_mfma_f32_16x16x32_bf16 v[80:83], v[142:145], v[208:211], 0
	v_mfma_f32_16x16x32_bf16 v[72:75], v[150:153], v[208:211], 0
	v_mfma_f32_16x16x32_bf16 v[124:127], v[146:149], v[188:191], v[124:127]
	v_mfma_f32_16x16x32_bf16 v[120:123], v[154:157], v[188:191], v[120:123]
	v_mfma_f32_16x16x32_bf16 v[112:115], v[146:149], v[196:199], v[112:115]
	v_mfma_f32_16x16x32_bf16 v[104:107], v[154:157], v[196:199], v[104:107]
	v_mfma_f32_16x16x32_bf16 v[96:99], v[146:149], v[204:207], v[96:99]
	v_mfma_f32_16x16x32_bf16 v[88:91], v[154:157], v[204:207], v[88:91]
	v_mfma_f32_16x16x32_bf16 v[80:83], v[146:149], v[212:215], v[80:83]
	v_mfma_f32_16x16x32_bf16 v[72:75], v[154:157], v[212:215], v[72:75]
	v_mfma_f32_16x16x32_bf16 v[128:131], v[168:171], v[184:187], 0
	v_mfma_f32_16x16x32_bf16 v[116:119], v[176:179], v[184:187], 0
	v_mfma_f32_16x16x32_bf16 v[108:111], v[168:171], v[192:195], 0
	v_mfma_f32_16x16x32_bf16 v[100:103], v[176:179], v[192:195], 0
	v_mfma_f32_16x16x32_bf16 v[92:95], v[168:171], v[200:203], 0
	v_mfma_f32_16x16x32_bf16 v[84:87], v[176:179], v[200:203], 0
	v_mfma_f32_16x16x32_bf16 v[76:79], v[168:171], v[208:211], 0
	v_mfma_f32_16x16x32_bf16 v[68:71], v[176:179], v[208:211], 0
	v_mfma_f32_16x16x32_bf16 v[128:131], v[172:175], v[188:191], v[128:131]
	v_mfma_f32_16x16x32_bf16 v[116:119], v[180:183], v[188:191], v[116:119]
	v_mfma_f32_16x16x32_bf16 v[108:111], v[172:175], v[196:199], v[108:111]
	v_mfma_f32_16x16x32_bf16 v[100:103], v[180:183], v[196:199], v[100:103]
	v_mfma_f32_16x16x32_bf16 v[92:95], v[172:175], v[204:207], v[92:95]
	v_mfma_f32_16x16x32_bf16 v[84:87], v[180:183], v[204:207], v[84:87]
	v_mfma_f32_16x16x32_bf16 v[76:79], v[172:175], v[212:215], v[76:79]
	v_mfma_f32_16x16x32_bf16 v[68:71], v[180:183], v[212:215], v[68:71]
	s_barrier
	s_setprio 0
	s_add_i32 s12, s14, s56
	s_mov_b32 m0, s12
	ds_read_b128 v[184:187], v167 offset:16384
	ds_read_b128 v[188:191], v167 offset:17408
	ds_read_b128 v[192:195], v167 offset:18432
	ds_read_b128 v[196:199], v167 offset:19456
	ds_read_b128 v[200:203], v167 offset:20480
	ds_read_b128 v[204:207], v167 offset:21504
	ds_read_b128 v[208:211], v167 offset:22528
	ds_read_b128 v[212:215], v167 offset:23552
	global_load_lds_dwordx4 v2, s[46:47]
	s_add_i32 m0, s12, 0x2000
	s_add_u32 s12, s46, 0x80000
	s_addc_u32 s13, s47, 0
	s_add_i32 s14, s15, s56
	global_load_lds_dwordx4 v0, s[46:47]
	s_mov_b32 m0, s14
	s_nop 0
	global_load_lds_dwordx4 v2, s[12:13]
	s_add_i32 m0, s14, 0x2000
	s_nop 0
	global_load_lds_dwordx4 v0, s[12:13]
	s_mov_b32 m0, s60
	s_nop 0
	global_load_lds_dwordx4 v134, s[48:49]
	s_mov_b32 m0, s61
	s_nop 0
	global_load_lds_dwordx4 v132, s[48:49]
	s_cmp_lg_u32 s32, 0
	s_cbranch_scc1 .Lgu_skip2_p
	s_waitcnt vmcnt(8)
.Lgu_skip2_p:
	s_mov_b32 s32, 0
	s_waitcnt lgkmcnt(0)
	s_barrier
	s_setprio 1
	v_mfma_f32_16x16x32_bf16 v[64:67], v[142:145], v[184:187], 0
	v_mfma_f32_16x16x32_bf16 v[56:59], v[150:153], v[184:187], 0
	v_mfma_f32_16x16x32_bf16 v[48:51], v[142:145], v[192:195], 0
	v_mfma_f32_16x16x32_bf16 v[40:43], v[150:153], v[192:195], 0
	v_mfma_f32_16x16x32_bf16 v[32:35], v[142:145], v[200:203], 0
	v_mfma_f32_16x16x32_bf16 v[24:27], v[150:153], v[200:203], 0
	v_mfma_f32_16x16x32_bf16 v[16:19], v[142:145], v[208:211], 0
	v_mfma_f32_16x16x32_bf16 v[8:11], v[150:153], v[208:211], 0
	v_mfma_f32_16x16x32_bf16 v[64:67], v[146:149], v[188:191], v[64:67]
	v_mfma_f32_16x16x32_bf16 v[56:59], v[154:157], v[188:191], v[56:59]
	v_mfma_f32_16x16x32_bf16 v[48:51], v[146:149], v[196:199], v[48:51]
	v_mfma_f32_16x16x32_bf16 v[40:43], v[154:157], v[196:199], v[40:43]
	v_mfma_f32_16x16x32_bf16 v[32:35], v[146:149], v[204:207], v[32:35]
	v_mfma_f32_16x16x32_bf16 v[24:27], v[154:157], v[204:207], v[24:27]
	v_mfma_f32_16x16x32_bf16 v[16:19], v[146:149], v[212:215], v[16:19]
	v_mfma_f32_16x16x32_bf16 v[8:11], v[154:157], v[212:215], v[8:11]
	v_mfma_f32_16x16x32_bf16 v[60:63], v[168:171], v[184:187], 0
	v_mfma_f32_16x16x32_bf16 v[52:55], v[176:179], v[184:187], 0
	v_mfma_f32_16x16x32_bf16 v[44:47], v[168:171], v[192:195], 0
	v_mfma_f32_16x16x32_bf16 v[36:39], v[176:179], v[192:195], 0
	v_mfma_f32_16x16x32_bf16 v[28:31], v[168:171], v[200:203], 0
	v_mfma_f32_16x16x32_bf16 v[20:23], v[176:179], v[200:203], 0
	v_mfma_f32_16x16x32_bf16 v[12:15], v[168:171], v[208:211], 0
	v_mfma_f32_16x16x32_bf16 v[4:7], v[176:179], v[208:211], 0
	v_mfma_f32_16x16x32_bf16 v[60:63], v[172:175], v[188:191], v[60:63]
	v_mfma_f32_16x16x32_bf16 v[52:55], v[180:183], v[188:191], v[52:55]
	v_mfma_f32_16x16x32_bf16 v[44:47], v[172:175], v[196:199], v[44:47]
	v_mfma_f32_16x16x32_bf16 v[36:39], v[180:183], v[196:199], v[36:39]
	v_mfma_f32_16x16x32_bf16 v[28:31], v[172:175], v[204:207], v[28:31]
	v_mfma_f32_16x16x32_bf16 v[20:23], v[180:183], v[204:207], v[20:23]
	v_mfma_f32_16x16x32_bf16 v[12:15], v[172:175], v[212:215], v[12:15]
	v_mfma_f32_16x16x32_bf16 v[4:7], v[180:183], v[212:215], v[4:7]
	s_barrier
	s_setprio 0
	s_add_i32 s14, 0, 0x18000
	s_add_i32 s15, 0, 0x1c000
	v_add_u32_e32 v154, s14, v163
	v_add_u32_e32 v160, s15, v163
	ds_read_b128 v[142:145], v154
	ds_read_b128 v[146:149], v154 offset:1024
	ds_read_b128 v[150:153], v154 offset:2048
	ds_read_b128 v[154:157], v154 offset:3072
	ds_read_b128 v[168:171], v160
	ds_read_b128 v[172:175], v160 offset:1024
	ds_read_b128 v[176:179], v160 offset:2048
	ds_read_b128 v[180:183], v160 offset:3072
	s_add_u32 s12, s48, 0x80000
	s_addc_u32 s13, s49, 0
	s_mov_b32 m0, s62
	ds_read_b128 v[184:187], v167 offset:32768
	ds_read_b128 v[188:191], v167 offset:33792
	ds_read_b128 v[192:195], v167 offset:34816
	ds_read_b128 v[196:199], v167 offset:35840
	ds_read_b128 v[200:203], v167 offset:36864
	ds_read_b128 v[204:207], v167 offset:37888
	ds_read_b128 v[208:211], v167 offset:38912
	ds_read_b128 v[212:215], v167 offset:39936
	global_load_lds_dwordx4 v134, s[12:13]
	s_mov_b32 m0, s63
	s_nop 0
	global_load_lds_dwordx4 v132, s[12:13]
	s_waitcnt vmcnt(8)
	s_waitcnt lgkmcnt(0)
	s_barrier
	s_setprio 1
	v_mfma_f32_16x16x32_bf16 v[124:127], v[142:145], v[184:187], v[124:127]
	v_mfma_f32_16x16x32_bf16 v[120:123], v[150:153], v[184:187], v[120:123]
	v_mfma_f32_16x16x32_bf16 v[112:115], v[142:145], v[192:195], v[112:115]
	v_mfma_f32_16x16x32_bf16 v[104:107], v[150:153], v[192:195], v[104:107]
	v_mfma_f32_16x16x32_bf16 v[96:99], v[142:145], v[200:203], v[96:99]
	v_mfma_f32_16x16x32_bf16 v[88:91], v[150:153], v[200:203], v[88:91]
	v_mfma_f32_16x16x32_bf16 v[80:83], v[142:145], v[208:211], v[80:83]
	v_mfma_f32_16x16x32_bf16 v[72:75], v[150:153], v[208:211], v[72:75]
	v_mfma_f32_16x16x32_bf16 v[124:127], v[146:149], v[188:191], v[124:127]
	v_mfma_f32_16x16x32_bf16 v[120:123], v[154:157], v[188:191], v[120:123]
	v_mfma_f32_16x16x32_bf16 v[112:115], v[146:149], v[196:199], v[112:115]
	v_mfma_f32_16x16x32_bf16 v[104:107], v[154:157], v[196:199], v[104:107]
	v_mfma_f32_16x16x32_bf16 v[96:99], v[146:149], v[204:207], v[96:99]
	v_mfma_f32_16x16x32_bf16 v[88:91], v[154:157], v[204:207], v[88:91]
	v_mfma_f32_16x16x32_bf16 v[80:83], v[146:149], v[212:215], v[80:83]
	v_mfma_f32_16x16x32_bf16 v[72:75], v[154:157], v[212:215], v[72:75]
	v_mfma_f32_16x16x32_bf16 v[128:131], v[168:171], v[184:187], v[128:131]
	v_mfma_f32_16x16x32_bf16 v[116:119], v[176:179], v[184:187], v[116:119]
	v_mfma_f32_16x16x32_bf16 v[108:111], v[168:171], v[192:195], v[108:111]
	v_mfma_f32_16x16x32_bf16 v[100:103], v[176:179], v[192:195], v[100:103]
	v_mfma_f32_16x16x32_bf16 v[92:95], v[168:171], v[200:203], v[92:95]
	v_mfma_f32_16x16x32_bf16 v[84:87], v[176:179], v[200:203], v[84:87]
	v_mfma_f32_16x16x32_bf16 v[76:79], v[168:171], v[208:211], v[76:79]
	v_mfma_f32_16x16x32_bf16 v[68:71], v[176:179], v[208:211], v[68:71]
	v_mfma_f32_16x16x32_bf16 v[128:131], v[172:175], v[188:191], v[128:131]
	v_mfma_f32_16x16x32_bf16 v[116:119], v[180:183], v[188:191], v[116:119]
	v_mfma_f32_16x16x32_bf16 v[108:111], v[172:175], v[196:199], v[108:111]
	v_mfma_f32_16x16x32_bf16 v[100:103], v[180:183], v[196:199], v[100:103]
	v_mfma_f32_16x16x32_bf16 v[92:95], v[172:175], v[204:207], v[92:95]
	v_mfma_f32_16x16x32_bf16 v[84:87], v[180:183], v[204:207], v[84:87]
	v_mfma_f32_16x16x32_bf16 v[76:79], v[172:175], v[212:215], v[76:79]
	v_mfma_f32_16x16x32_bf16 v[68:71], v[180:183], v[212:215], v[68:71]
	s_barrier
	s_setprio 0
	s_add_i32 s12, s14, s56
	s_mov_b32 m0, s12
	ds_read_b128 v[184:187], v167 offset:49152
	ds_read_b128 v[188:191], v167 offset:50176
	ds_read_b128 v[192:195], v167 offset:51200
	ds_read_b128 v[196:199], v167 offset:52224
	ds_read_b128 v[200:203], v167 offset:53248
	ds_read_b128 v[204:207], v167 offset:54272
	ds_read_b128 v[208:211], v167 offset:55296
	ds_read_b128 v[212:215], v167 offset:56320
	s_add_u32 s100, s46, 0x80
	s_addc_u32 s101, s47, 0
	global_load_lds_dwordx4 v2, s[100:101]
	s_add_i32 m0, s12, 0x2000
	s_add_u32 s12, s46, 0x80080
	s_addc_u32 s13, s47, 0
	s_add_i32 s14, s15, s56
	s_add_u32 s100, s46, 0x80
	s_addc_u32 s101, s47, 0
	global_load_lds_dwordx4 v0, s[100:101]
	s_mov_b32 m0, s14
	s_nop 0
	global_load_lds_dwordx4 v2, s[12:13]
	s_add_i32 m0, s14, 0x2000
	s_nop 0
	global_load_lds_dwordx4 v0, s[12:13]
	s_mov_b32 m0, s64
	s_nop 0
	s_add_u32 s100, s48, 0x80
	s_addc_u32 s101, s49, 0
	global_load_lds_dwordx4 v134, s[100:101]
	s_mov_b32 m0, s65
	s_nop 0
	s_add_u32 s100, s48, 0x80
	s_addc_u32 s101, s49, 0
	global_load_lds_dwordx4 v132, s[100:101]
	s_waitcnt vmcnt(8)
	s_waitcnt lgkmcnt(0)
	s_barrier
	s_setprio 1
	v_mfma_f32_16x16x32_bf16 v[64:67], v[142:145], v[184:187], v[64:67]
	v_mfma_f32_16x16x32_bf16 v[56:59], v[150:153], v[184:187], v[56:59]
	v_mfma_f32_16x16x32_bf16 v[48:51], v[142:145], v[192:195], v[48:51]
	v_mfma_f32_16x16x32_bf16 v[40:43], v[150:153], v[192:195], v[40:43]
	v_mfma_f32_16x16x32_bf16 v[32:35], v[142:145], v[200:203], v[32:35]
	v_mfma_f32_16x16x32_bf16 v[24:27], v[150:153], v[200:203], v[24:27]
	v_mfma_f32_16x16x32_bf16 v[16:19], v[142:145], v[208:211], v[16:19]
	v_mfma_f32_16x16x32_bf16 v[8:11], v[150:153], v[208:211], v[8:11]
	v_mfma_f32_16x16x32_bf16 v[64:67], v[146:149], v[188:191], v[64:67]
	v_mfma_f32_16x16x32_bf16 v[56:59], v[154:157], v[188:191], v[56:59]
	v_mfma_f32_16x16x32_bf16 v[48:51], v[146:149], v[196:199], v[48:51]
	v_mfma_f32_16x16x32_bf16 v[40:43], v[154:157], v[196:199], v[40:43]
	v_mfma_f32_16x16x32_bf16 v[32:35], v[146:149], v[204:207], v[32:35]
	v_mfma_f32_16x16x32_bf16 v[24:27], v[154:157], v[204:207], v[24:27]
	v_mfma_f32_16x16x32_bf16 v[16:19], v[146:149], v[212:215], v[16:19]
	v_mfma_f32_16x16x32_bf16 v[8:11], v[154:157], v[212:215], v[8:11]
	v_mfma_f32_16x16x32_bf16 v[60:63], v[168:171], v[184:187], v[60:63]
	v_mfma_f32_16x16x32_bf16 v[52:55], v[176:179], v[184:187], v[52:55]
	v_mfma_f32_16x16x32_bf16 v[44:47], v[168:171], v[192:195], v[44:47]
	v_mfma_f32_16x16x32_bf16 v[36:39], v[176:179], v[192:195], v[36:39]
	v_mfma_f32_16x16x32_bf16 v[28:31], v[168:171], v[200:203], v[28:31]
	v_mfma_f32_16x16x32_bf16 v[20:23], v[176:179], v[200:203], v[20:23]
	v_mfma_f32_16x16x32_bf16 v[12:15], v[168:171], v[208:211], v[12:15]
	v_mfma_f32_16x16x32_bf16 v[4:7], v[176:179], v[208:211], v[4:7]
	v_mfma_f32_16x16x32_bf16 v[60:63], v[172:175], v[188:191], v[60:63]
	v_mfma_f32_16x16x32_bf16 v[52:55], v[180:183], v[188:191], v[52:55]
	v_mfma_f32_16x16x32_bf16 v[44:47], v[172:175], v[196:199], v[44:47]
	v_mfma_f32_16x16x32_bf16 v[36:39], v[180:183], v[196:199], v[36:39]
	v_mfma_f32_16x16x32_bf16 v[28:31], v[172:175], v[204:207], v[28:31]
	v_mfma_f32_16x16x32_bf16 v[20:23], v[180:183], v[204:207], v[20:23]
	v_mfma_f32_16x16x32_bf16 v[12:15], v[172:175], v[212:215], v[12:15]
	v_mfma_f32_16x16x32_bf16 v[4:7], v[180:183], v[212:215], v[4:7]
	s_barrier
	s_setprio 0
	s_add_i32 s11, s11, 2
	s_add_u32 s9, s9, 0x100
	s_addc_u32 s10, s10, 0
	s_add_u32 s44, s44, 0x100
	s_addc_u32 s45, s45, 0
	s_cmp_gt_u32 s11, 29
.LBB0_1066:
	s_add_u32 s12, s44, 0xfff80080
	s_addc_u32 s13, s45, -1
	s_add_i32 s14, 0, 0x10000
	s_cmp_eq_u32 s11, 28
	s_cselect_b32 s49, s5, s13
	s_cselect_b32 s48, s6, s12
	s_cselect_b32 s47, s7, s10
	s_cselect_b32 s46, s8, s9
	s_add_i32 s15, 0, 0x14000
	v_add_u32_e32 v154, s14, v163
	v_add_u32_e32 v158, s15, v163
	ds_read_b128 v[142:145], v154
	ds_read_b128 v[146:149], v154 offset:1024
	ds_read_b128 v[150:153], v154 offset:2048
	ds_read_b128 v[154:157], v154 offset:3072
	ds_read_b128 v[168:171], v158
	ds_read_b128 v[172:175], v158 offset:1024
	ds_read_b128 v[176:179], v158 offset:2048
	ds_read_b128 v[180:183], v158 offset:3072
	s_add_i32 m0, s60, 0xc000
	ds_read_b128 v[184:187], v167
	ds_read_b128 v[188:191], v167 offset:1024
	ds_read_b128 v[192:195], v167 offset:2048
	ds_read_b128 v[196:199], v167 offset:3072
	ds_read_b128 v[200:203], v167 offset:4096
	ds_read_b128 v[204:207], v167 offset:5120
	ds_read_b128 v[208:211], v167 offset:6144
	ds_read_b128 v[212:215], v167 offset:7168
	global_load_lds_dwordx4 v140, s[44:45]
	s_add_i32 m0, s60, 0xe000
	s_nop 0
	global_load_lds_dwordx4 v138, s[44:45]
	s_waitcnt vmcnt(8)
	s_waitcnt lgkmcnt(0)
	s_barrier
	s_setprio 1
	v_mfma_f32_16x16x32_bf16 v[124:127], v[142:145], v[184:187], v[124:127]
	v_mfma_f32_16x16x32_bf16 v[120:123], v[150:153], v[184:187], v[120:123]
	v_mfma_f32_16x16x32_bf16 v[112:115], v[142:145], v[192:195], v[112:115]
	v_mfma_f32_16x16x32_bf16 v[104:107], v[150:153], v[192:195], v[104:107]
	v_mfma_f32_16x16x32_bf16 v[96:99], v[142:145], v[200:203], v[96:99]
	v_mfma_f32_16x16x32_bf16 v[88:91], v[150:153], v[200:203], v[88:91]
	v_mfma_f32_16x16x32_bf16 v[80:83], v[142:145], v[208:211], v[80:83]
	v_mfma_f32_16x16x32_bf16 v[72:75], v[150:153], v[208:211], v[72:75]
	v_mfma_f32_16x16x32_bf16 v[124:127], v[146:149], v[188:191], v[124:127]
	v_mfma_f32_16x16x32_bf16 v[120:123], v[154:157], v[188:191], v[120:123]
	v_mfma_f32_16x16x32_bf16 v[112:115], v[146:149], v[196:199], v[112:115]
	v_mfma_f32_16x16x32_bf16 v[104:107], v[154:157], v[196:199], v[104:107]
	v_mfma_f32_16x16x32_bf16 v[96:99], v[146:149], v[204:207], v[96:99]
	v_mfma_f32_16x16x32_bf16 v[88:91], v[154:157], v[204:207], v[88:91]
	v_mfma_f32_16x16x32_bf16 v[80:83], v[146:149], v[212:215], v[80:83]
	v_mfma_f32_16x16x32_bf16 v[72:75], v[154:157], v[212:215], v[72:75]
	v_mfma_f32_16x16x32_bf16 v[128:131], v[168:171], v[184:187], v[128:131]
	v_mfma_f32_16x16x32_bf16 v[116:119], v[176:179], v[184:187], v[116:119]
	v_mfma_f32_16x16x32_bf16 v[108:111], v[168:171], v[192:195], v[108:111]
	v_mfma_f32_16x16x32_bf16 v[100:103], v[176:179], v[192:195], v[100:103]
	v_mfma_f32_16x16x32_bf16 v[92:95], v[168:171], v[200:203], v[92:95]
	v_mfma_f32_16x16x32_bf16 v[84:87], v[176:179], v[200:203], v[84:87]
	v_mfma_f32_16x16x32_bf16 v[76:79], v[168:171], v[208:211], v[76:79]
	v_mfma_f32_16x16x32_bf16 v[68:71], v[176:179], v[208:211], v[68:71]
	v_mfma_f32_16x16x32_bf16 v[128:131], v[172:175], v[188:191], v[128:131]
	v_mfma_f32_16x16x32_bf16 v[116:119], v[180:183], v[188:191], v[116:119]
	v_mfma_f32_16x16x32_bf16 v[108:111], v[172:175], v[196:199], v[108:111]
	v_mfma_f32_16x16x32_bf16 v[100:103], v[180:183], v[196:199], v[100:103]
	v_mfma_f32_16x16x32_bf16 v[92:95], v[172:175], v[204:207], v[92:95]
	v_mfma_f32_16x16x32_bf16 v[84:87], v[180:183], v[204:207], v[84:87]
	v_mfma_f32_16x16x32_bf16 v[76:79], v[172:175], v[212:215], v[76:79]
	v_mfma_f32_16x16x32_bf16 v[68:71], v[180:183], v[212:215], v[68:71]
	s_barrier
	s_setprio 0
	s_add_i32 s12, s14, s56
	s_mov_b32 m0, s12
	ds_read_b128 v[184:187], v167 offset:16384
	ds_read_b128 v[188:191], v167 offset:17408
	ds_read_b128 v[192:195], v167 offset:18432
	ds_read_b128 v[196:199], v167 offset:19456
	ds_read_b128 v[200:203], v167 offset:20480
	ds_read_b128 v[204:207], v167 offset:21504
	ds_read_b128 v[208:211], v167 offset:22528
	ds_read_b128 v[212:215], v167 offset:23552
	global_load_lds_dwordx4 v2, s[46:47]
	s_add_i32 m0, s12, 0x2000
	s_add_u32 s12, s46, 0x80000
	s_addc_u32 s13, s47, 0
	s_add_i32 s14, s15, s56
	global_load_lds_dwordx4 v0, s[46:47]
	s_mov_b32 m0, s14
	s_nop 0
	global_load_lds_dwordx4 v2, s[12:13]
	s_add_i32 m0, s14, 0x2000
	s_nop 0
	global_load_lds_dwordx4 v0, s[12:13]
	s_mov_b32 m0, s60
	s_nop 0
	global_load_lds_dwordx4 v134, s[48:49]
	s_mov_b32 m0, s61
	s_nop 0
	global_load_lds_dwordx4 v132, s[48:49]
	s_waitcnt vmcnt(8)
	s_waitcnt lgkmcnt(0)
	s_barrier
	s_setprio 1
	v_mfma_f32_16x16x32_bf16 v[64:67], v[142:145], v[184:187], v[64:67]
	v_mfma_f32_16x16x32_bf16 v[56:59], v[150:153], v[184:187], v[56:59]
	v_mfma_f32_16x16x32_bf16 v[48:51], v[142:145], v[192:195], v[48:51]
	v_mfma_f32_16x16x32_bf16 v[40:43], v[150:153], v[192:195], v[40:43]
	v_mfma_f32_16x16x32_bf16 v[32:35], v[142:145], v[200:203], v[32:35]
	v_mfma_f32_16x16x32_bf16 v[24:27], v[150:153], v[200:203], v[24:27]
	v_mfma_f32_16x16x32_bf16 v[16:19], v[142:145], v[208:211], v[16:19]
	v_mfma_f32_16x16x32_bf16 v[8:11], v[150:153], v[208:211], v[8:11]
	v_mfma_f32_16x16x32_bf16 v[64:67], v[146:149], v[188:191], v[64:67]
	v_mfma_f32_16x16x32_bf16 v[56:59], v[154:157], v[188:191], v[56:59]
	v_mfma_f32_16x16x32_bf16 v[48:51], v[146:149], v[196:199], v[48:51]
	v_mfma_f32_16x16x32_bf16 v[40:43], v[154:157], v[196:199], v[40:43]
	v_mfma_f32_16x16x32_bf16 v[32:35], v[146:149], v[204:207], v[32:35]
	v_mfma_f32_16x16x32_bf16 v[24:27], v[154:157], v[204:207], v[24:27]
	v_mfma_f32_16x16x32_bf16 v[16:19], v[146:149], v[212:215], v[16:19]
	v_mfma_f32_16x16x32_bf16 v[8:11], v[154:157], v[212:215], v[8:11]
	v_mfma_f32_16x16x32_bf16 v[60:63], v[168:171], v[184:187], v[60:63]
	v_mfma_f32_16x16x32_bf16 v[52:55], v[176:179], v[184:187], v[52:55]
	v_mfma_f32_16x16x32_bf16 v[44:47], v[168:171], v[192:195], v[44:47]
	v_mfma_f32_16x16x32_bf16 v[36:39], v[176:179], v[192:195], v[36:39]
	v_mfma_f32_16x16x32_bf16 v[28:31], v[168:171], v[200:203], v[28:31]
	v_mfma_f32_16x16x32_bf16 v[20:23], v[176:179], v[200:203], v[20:23]
	v_mfma_f32_16x16x32_bf16 v[12:15], v[168:171], v[208:211], v[12:15]
	v_mfma_f32_16x16x32_bf16 v[4:7], v[176:179], v[208:211], v[4:7]
	v_mfma_f32_16x16x32_bf16 v[60:63], v[172:175], v[188:191], v[60:63]
	v_mfma_f32_16x16x32_bf16 v[52:55], v[180:183], v[188:191], v[52:55]
	v_mfma_f32_16x16x32_bf16 v[44:47], v[172:175], v[196:199], v[44:47]
	v_mfma_f32_16x16x32_bf16 v[36:39], v[180:183], v[196:199], v[36:39]
	v_mfma_f32_16x16x32_bf16 v[28:31], v[172:175], v[204:207], v[28:31]
	v_mfma_f32_16x16x32_bf16 v[20:23], v[180:183], v[204:207], v[20:23]
	v_mfma_f32_16x16x32_bf16 v[12:15], v[172:175], v[212:215], v[12:15]
	v_mfma_f32_16x16x32_bf16 v[4:7], v[180:183], v[212:215], v[4:7]
	s_barrier
	s_setprio 0
	s_add_i32 s14, 0, 0x18000
	s_add_i32 s15, 0, 0x1c000
	v_add_u32_e32 v154, s14, v163
	v_add_u32_e32 v160, s15, v163
	ds_read_b128 v[142:145], v154
	ds_read_b128 v[146:149], v154 offset:1024
	ds_read_b128 v[150:153], v154 offset:2048
	ds_read_b128 v[154:157], v154 offset:3072
	ds_read_b128 v[168:171], v160
	ds_read_b128 v[172:175], v160 offset:1024
	ds_read_b128 v[176:179], v160 offset:2048
	ds_read_b128 v[180:183], v160 offset:3072
	s_add_u32 s12, s48, 0x80000
	s_addc_u32 s13, s49, 0
	s_mov_b32 m0, s62
	ds_read_b128 v[184:187], v167 offset:32768
	ds_read_b128 v[188:191], v167 offset:33792
	ds_read_b128 v[192:195], v167 offset:34816
	ds_read_b128 v[196:199], v167 offset:35840
	ds_read_b128 v[200:203], v167 offset:36864
	ds_read_b128 v[204:207], v167 offset:37888
	ds_read_b128 v[208:211], v167 offset:38912
	ds_read_b128 v[212:215], v167 offset:39936
	global_load_lds_dwordx4 v134, s[12:13]
	s_mov_b32 m0, s63
	s_nop 0
	global_load_lds_dwordx4 v132, s[12:13]
	s_waitcnt vmcnt(8)
	s_waitcnt lgkmcnt(0)
	s_barrier
	s_setprio 1
	v_mfma_f32_16x16x32_bf16 v[124:127], v[142:145], v[184:187], v[124:127]
	v_mfma_f32_16x16x32_bf16 v[120:123], v[150:153], v[184:187], v[120:123]
	v_mfma_f32_16x16x32_bf16 v[112:115], v[142:145], v[192:195], v[112:115]
	v_mfma_f32_16x16x32_bf16 v[104:107], v[150:153], v[192:195], v[104:107]
	v_mfma_f32_16x16x32_bf16 v[96:99], v[142:145], v[200:203], v[96:99]
	v_mfma_f32_16x16x32_bf16 v[88:91], v[150:153], v[200:203], v[88:91]
	v_mfma_f32_16x16x32_bf16 v[80:83], v[142:145], v[208:211], v[80:83]
	v_mfma_f32_16x16x32_bf16 v[72:75], v[150:153], v[208:211], v[72:75]
	v_mfma_f32_16x16x32_bf16 v[124:127], v[146:149], v[188:191], v[124:127]
	v_mfma_f32_16x16x32_bf16 v[120:123], v[154:157], v[188:191], v[120:123]
	v_mfma_f32_16x16x32_bf16 v[112:115], v[146:149], v[196:199], v[112:115]
	v_mfma_f32_16x16x32_bf16 v[104:107], v[154:157], v[196:199], v[104:107]
	v_mfma_f32_16x16x32_bf16 v[96:99], v[146:149], v[204:207], v[96:99]
	v_mfma_f32_16x16x32_bf16 v[88:91], v[154:157], v[204:207], v[88:91]
	v_mfma_f32_16x16x32_bf16 v[80:83], v[146:149], v[212:215], v[80:83]
	v_mfma_f32_16x16x32_bf16 v[72:75], v[154:157], v[212:215], v[72:75]
	v_mfma_f32_16x16x32_bf16 v[128:131], v[168:171], v[184:187], v[128:131]
	v_mfma_f32_16x16x32_bf16 v[116:119], v[176:179], v[184:187], v[116:119]
	v_mfma_f32_16x16x32_bf16 v[108:111], v[168:171], v[192:195], v[108:111]
	v_mfma_f32_16x16x32_bf16 v[100:103], v[176:179], v[192:195], v[100:103]
	v_mfma_f32_16x16x32_bf16 v[92:95], v[168:171], v[200:203], v[92:95]
	v_mfma_f32_16x16x32_bf16 v[84:87], v[176:179], v[200:203], v[84:87]
	v_mfma_f32_16x16x32_bf16 v[76:79], v[168:171], v[208:211], v[76:79]
	v_mfma_f32_16x16x32_bf16 v[68:71], v[176:179], v[208:211], v[68:71]
	v_mfma_f32_16x16x32_bf16 v[128:131], v[172:175], v[188:191], v[128:131]
	v_mfma_f32_16x16x32_bf16 v[116:119], v[180:183], v[188:191], v[116:119]
	v_mfma_f32_16x16x32_bf16 v[108:111], v[172:175], v[196:199], v[108:111]
	v_mfma_f32_16x16x32_bf16 v[100:103], v[180:183], v[196:199], v[100:103]
	v_mfma_f32_16x16x32_bf16 v[92:95], v[172:175], v[204:207], v[92:95]
	v_mfma_f32_16x16x32_bf16 v[84:87], v[180:183], v[204:207], v[84:87]
	v_mfma_f32_16x16x32_bf16 v[76:79], v[172:175], v[212:215], v[76:79]
	v_mfma_f32_16x16x32_bf16 v[68:71], v[180:183], v[212:215], v[68:71]
	s_barrier
	s_setprio 0
	s_add_i32 s12, s14, s56
	s_mov_b32 m0, s12
	ds_read_b128 v[184:187], v167 offset:49152
	ds_read_b128 v[188:191], v167 offset:50176
	ds_read_b128 v[192:195], v167 offset:51200
	ds_read_b128 v[196:199], v167 offset:52224
	ds_read_b128 v[200:203], v167 offset:53248
	ds_read_b128 v[204:207], v167 offset:54272
	ds_read_b128 v[208:211], v167 offset:55296
	ds_read_b128 v[212:215], v167 offset:56320
	s_add_u32 s100, s46, 0x80
	s_addc_u32 s101, s47, 0
	global_load_lds_dwordx4 v2, s[100:101]
	s_add_i32 m0, s12, 0x2000
	s_add_u32 s12, s46, 0x80080
	s_addc_u32 s13, s47, 0
	s_add_i32 s14, s15, s56
	s_add_u32 s100, s46, 0x80
	s_addc_u32 s101, s47, 0
	global_load_lds_dwordx4 v0, s[100:101]
	s_mov_b32 m0, s14
	s_nop 0
	global_load_lds_dwordx4 v2, s[12:13]
	s_add_i32 m0, s14, 0x2000
	s_nop 0
	global_load_lds_dwordx4 v0, s[12:13]
	s_mov_b32 m0, s64
	s_nop 0
	s_add_u32 s100, s48, 0x80
	s_addc_u32 s101, s49, 0
	global_load_lds_dwordx4 v134, s[100:101]
	s_mov_b32 m0, s65
	s_nop 0
	s_add_u32 s100, s48, 0x80
	s_addc_u32 s101, s49, 0
	global_load_lds_dwordx4 v132, s[100:101]
	s_waitcnt vmcnt(8)
	s_waitcnt lgkmcnt(0)
	s_barrier
	s_setprio 1
	v_mfma_f32_16x16x32_bf16 v[64:67], v[142:145], v[184:187], v[64:67]
	v_mfma_f32_16x16x32_bf16 v[56:59], v[150:153], v[184:187], v[56:59]
	v_mfma_f32_16x16x32_bf16 v[48:51], v[142:145], v[192:195], v[48:51]
	v_mfma_f32_16x16x32_bf16 v[40:43], v[150:153], v[192:195], v[40:43]
	v_mfma_f32_16x16x32_bf16 v[32:35], v[142:145], v[200:203], v[32:35]
	v_mfma_f32_16x16x32_bf16 v[24:27], v[150:153], v[200:203], v[24:27]
	v_mfma_f32_16x16x32_bf16 v[16:19], v[142:145], v[208:211], v[16:19]
	v_mfma_f32_16x16x32_bf16 v[8:11], v[150:153], v[208:211], v[8:11]
	v_mfma_f32_16x16x32_bf16 v[64:67], v[146:149], v[188:191], v[64:67]
	v_mfma_f32_16x16x32_bf16 v[56:59], v[154:157], v[188:191], v[56:59]
	v_mfma_f32_16x16x32_bf16 v[48:51], v[146:149], v[196:199], v[48:51]
	v_mfma_f32_16x16x32_bf16 v[40:43], v[154:157], v[196:199], v[40:43]
	v_mfma_f32_16x16x32_bf16 v[32:35], v[146:149], v[204:207], v[32:35]
	v_mfma_f32_16x16x32_bf16 v[24:27], v[154:157], v[204:207], v[24:27]
	v_mfma_f32_16x16x32_bf16 v[16:19], v[146:149], v[212:215], v[16:19]
	v_mfma_f32_16x16x32_bf16 v[8:11], v[154:157], v[212:215], v[8:11]
	v_mfma_f32_16x16x32_bf16 v[60:63], v[168:171], v[184:187], v[60:63]
	v_mfma_f32_16x16x32_bf16 v[52:55], v[176:179], v[184:187], v[52:55]
	v_mfma_f32_16x16x32_bf16 v[44:47], v[168:171], v[192:195], v[44:47]
	v_mfma_f32_16x16x32_bf16 v[36:39], v[176:179], v[192:195], v[36:39]
	v_mfma_f32_16x16x32_bf16 v[28:31], v[168:171], v[200:203], v[28:31]
	v_mfma_f32_16x16x32_bf16 v[20:23], v[176:179], v[200:203], v[20:23]
	v_mfma_f32_16x16x32_bf16 v[12:15], v[168:171], v[208:211], v[12:15]
	v_mfma_f32_16x16x32_bf16 v[4:7], v[176:179], v[208:211], v[4:7]
	v_mfma_f32_16x16x32_bf16 v[60:63], v[172:175], v[188:191], v[60:63]
	v_mfma_f32_16x16x32_bf16 v[52:55], v[180:183], v[188:191], v[52:55]
	v_mfma_f32_16x16x32_bf16 v[44:47], v[172:175], v[196:199], v[44:47]
	v_mfma_f32_16x16x32_bf16 v[36:39], v[180:183], v[196:199], v[36:39]
	v_mfma_f32_16x16x32_bf16 v[28:31], v[172:175], v[204:207], v[28:31]
	v_mfma_f32_16x16x32_bf16 v[20:23], v[180:183], v[204:207], v[20:23]
	v_mfma_f32_16x16x32_bf16 v[12:15], v[172:175], v[212:215], v[12:15]
	v_mfma_f32_16x16x32_bf16 v[4:7], v[180:183], v[212:215], v[4:7]
	s_barrier
	s_setprio 0
	s_add_i32 s11, s11, 2
	s_add_u32 s9, s9, 0x100
	s_addc_u32 s10, s10, 0
	s_add_u32 s44, s44, 0x100
	s_addc_u32 s45, s45, 0
	s_cmp_gt_u32 s11, 29
	s_cbranch_scc0 .LBB0_1066
	s_and_b64 vcc, exec, s[22:23]
	s_cbranch_vccz .LBB0_1069
	s_nop 0

.LBB0_1133:
	s_add_u32 s5, s40, 0x100
	s_addc_u32 s6, s41, 0
	s_mov_b32 s7, -2
	s_waitcnt lgkmcnt(0)
	s_add_u32 s40, s38, 0x100
	s_addc_u32 s41, s39, 0
	s_add_i32 s8, 0, 0x10000
	s_cmpk_eq_i32 s7, 0x54
	s_cselect_b32 s45, s61, s41
	s_cselect_b32 s44, s60, s40
	s_cselect_b32 s43, s63, s6
	s_cselect_b32 s42, s62, s5
	s_add_i32 s10, 0, 0x14000
	v_add_u32_e32 v112, s8, v242
	v_add_u32_e32 v148, s10, v242
	ds_read_b128 v[92:95], v112
	ds_read_b128 v[100:103], v112 offset:1024
	ds_read_b128 v[108:111], v112 offset:2048
	ds_read_b128 v[112:115], v112 offset:3072
	ds_read_b128 v[116:119], v148
	ds_read_b128 v[128:131], v148 offset:1024
	ds_read_b128 v[140:143], v148 offset:2048
	ds_read_b128 v[148:151], v148 offset:3072
	v_lshl_add_u64 v[196:197], s[38:39], 0, v[222:223]
	s_add_i32 m0, s83, 0xc000
	ds_read_b128 v[160:163], v245
	ds_read_b128 v[168:171], v245 offset:1024
	ds_read_b128 v[172:175], v245 offset:2048
	ds_read_b128 v[176:179], v245 offset:3072
	ds_read_b128 v[180:183], v245 offset:4096
	ds_read_b128 v[184:187], v245 offset:5120
	ds_read_b128 v[188:191], v245 offset:6144
	ds_read_b128 v[192:195], v245 offset:7168
	global_load_lds_dwordx4 v[196:197], off
	v_lshl_add_u64 v[196:197], s[38:39], 0, v[220:221]
	s_add_i32 m0, s83, 0xe000
	s_nop 0
	global_load_lds_dwordx4 v[196:197], off
	s_waitcnt vmcnt(8)
	s_waitcnt lgkmcnt(0)
	s_barrier
	s_setprio 1
	v_mfma_f32_16x16x32_bf16 v[164:167], v[92:95], v[160:163], 0
	v_mfma_f32_16x16x32_bf16 v[156:159], v[108:111], v[160:163], 0
	v_mfma_f32_16x16x32_bf16 v[136:139], v[92:95], v[172:175], 0
	v_mfma_f32_16x16x32_bf16 v[132:135], v[108:111], v[172:175], 0
	v_mfma_f32_16x16x32_bf16 v[104:107], v[92:95], v[180:183], 0
	v_mfma_f32_16x16x32_bf16 v[96:99], v[108:111], v[180:183], 0
	v_mfma_f32_16x16x32_bf16 v[80:83], v[92:95], v[188:191], 0
	v_mfma_f32_16x16x32_bf16 v[76:79], v[108:111], v[188:191], 0
	v_mfma_f32_16x16x32_bf16 v[164:167], v[100:103], v[168:171], v[164:167]
	v_mfma_f32_16x16x32_bf16 v[156:159], v[112:115], v[168:171], v[156:159]
	v_mfma_f32_16x16x32_bf16 v[136:139], v[100:103], v[176:179], v[136:139]
	v_mfma_f32_16x16x32_bf16 v[132:135], v[112:115], v[176:179], v[132:135]
	v_mfma_f32_16x16x32_bf16 v[104:107], v[100:103], v[184:187], v[104:107]
	v_mfma_f32_16x16x32_bf16 v[96:99], v[112:115], v[184:187], v[96:99]
	v_mfma_f32_16x16x32_bf16 v[80:83], v[100:103], v[192:195], v[80:83]
	v_mfma_f32_16x16x32_bf16 v[76:79], v[112:115], v[192:195], v[76:79]
	s_setprio 0
	s_setprio 1
	v_mfma_f32_16x16x32_bf16 v[152:155], v[116:119], v[160:163], 0
	v_mfma_f32_16x16x32_bf16 v[144:147], v[140:143], v[160:163], 0
	v_mfma_f32_16x16x32_bf16 v[124:127], v[116:119], v[172:175], 0
	v_mfma_f32_16x16x32_bf16 v[120:123], v[140:143], v[172:175], 0
	v_mfma_f32_16x16x32_bf16 v[88:91], v[116:119], v[180:183], 0
	v_mfma_f32_16x16x32_bf16 v[84:87], v[140:143], v[180:183], 0
	v_mfma_f32_16x16x32_bf16 v[72:75], v[116:119], v[188:191], 0
	v_mfma_f32_16x16x32_bf16 v[68:71], v[140:143], v[188:191], 0
	v_mfma_f32_16x16x32_bf16 v[152:155], v[128:131], v[168:171], v[152:155]
	v_mfma_f32_16x16x32_bf16 v[144:147], v[148:151], v[168:171], v[144:147]
	v_mfma_f32_16x16x32_bf16 v[124:127], v[128:131], v[176:179], v[124:127]
	v_mfma_f32_16x16x32_bf16 v[120:123], v[148:151], v[176:179], v[120:123]
	v_mfma_f32_16x16x32_bf16 v[88:91], v[128:131], v[184:187], v[88:91]
	v_mfma_f32_16x16x32_bf16 v[84:87], v[148:151], v[184:187], v[84:87]
	v_mfma_f32_16x16x32_bf16 v[72:75], v[128:131], v[192:195], v[72:75]
	v_mfma_f32_16x16x32_bf16 v[68:71], v[148:151], v[192:195], v[68:71]
	s_barrier
	s_setprio 0
	s_add_i32 s8, s8, s82
	v_lshl_add_u64 v[196:197], s[42:43], 0, v[2:3]
	s_mov_b32 m0, s8
	ds_read_b128 v[160:163], v245 offset:16384
	ds_read_b128 v[168:171], v245 offset:17408
	ds_read_b128 v[172:175], v245 offset:18432
	ds_read_b128 v[176:179], v245 offset:19456
	ds_read_b128 v[180:183], v245 offset:20480
	ds_read_b128 v[184:187], v245 offset:21504
	ds_read_b128 v[188:191], v245 offset:22528
	ds_read_b128 v[192:195], v245 offset:23552
	global_load_lds_dwordx4 v[196:197], off
	s_add_i32 m0, s8, 0x2000
	s_add_u32 s8, s42, 0x160000
	v_lshl_add_u64 v[198:199], s[42:43], 0, v[218:219]
	s_addc_u32 s9, s43, 0
	s_add_i32 s10, s10, s82
	global_load_lds_dwordx4 v[198:199], off
	v_lshl_add_u64 v[200:201], s[8:9], 0, v[2:3]
	s_mov_b32 m0, s10
	v_lshl_add_u64 v[202:203], s[44:45], 0, v[216:217]
	global_load_lds_dwordx4 v[200:201], off
	v_lshl_add_u64 v[200:201], s[8:9], 0, v[218:219]
	s_add_i32 m0, s10, 0x2000
	s_nop 0
	global_load_lds_dwordx4 v[200:201], off
	v_lshl_add_u64 v[200:201], s[44:45], 0, v[0:1]
	s_mov_b32 m0, s83
	s_nop 0
	global_load_lds_dwordx4 v[200:201], off
	s_mov_b32 m0, s84
	s_nop 0
	global_load_lds_dwordx4 v[202:203], off
	s_waitcnt vmcnt(8)
	s_waitcnt lgkmcnt(0)
	s_barrier
	s_setprio 1
	v_mfma_f32_16x16x32_bf16 v[64:67], v[92:95], v[160:163], 0
	v_mfma_f32_16x16x32_bf16 v[60:63], v[108:111], v[160:163], 0
	v_mfma_f32_16x16x32_bf16 v[48:51], v[92:95], v[172:175], 0
	v_mfma_f32_16x16x32_bf16 v[44:47], v[108:111], v[172:175], 0
	v_mfma_f32_16x16x32_bf16 v[32:35], v[92:95], v[180:183], 0
	v_mfma_f32_16x16x32_bf16 v[28:31], v[108:111], v[180:183], 0
	v_mfma_f32_16x16x32_bf16 v[16:19], v[92:95], v[188:191], 0
	v_mfma_f32_16x16x32_bf16 v[12:15], v[108:111], v[188:191], 0
	v_mfma_f32_16x16x32_bf16 v[64:67], v[100:103], v[168:171], v[64:67]
	v_mfma_f32_16x16x32_bf16 v[60:63], v[112:115], v[168:171], v[60:63]
	v_mfma_f32_16x16x32_bf16 v[48:51], v[100:103], v[176:179], v[48:51]
	v_mfma_f32_16x16x32_bf16 v[44:47], v[112:115], v[176:179], v[44:47]
	v_mfma_f32_16x16x32_bf16 v[32:35], v[100:103], v[184:187], v[32:35]
	v_mfma_f32_16x16x32_bf16 v[28:31], v[112:115], v[184:187], v[28:31]
	v_mfma_f32_16x16x32_bf16 v[16:19], v[100:103], v[192:195], v[16:19]
	v_mfma_f32_16x16x32_bf16 v[12:15], v[112:115], v[192:195], v[12:15]
	s_setprio 0
	s_setprio 1
	v_mfma_f32_16x16x32_bf16 v[56:59], v[116:119], v[160:163], 0
	v_mfma_f32_16x16x32_bf16 v[52:55], v[140:143], v[160:163], 0
	v_mfma_f32_16x16x32_bf16 v[40:43], v[116:119], v[172:175], 0
	v_mfma_f32_16x16x32_bf16 v[36:39], v[140:143], v[172:175], 0
	v_mfma_f32_16x16x32_bf16 v[24:27], v[116:119], v[180:183], 0
	v_mfma_f32_16x16x32_bf16 v[20:23], v[140:143], v[180:183], 0
	v_mfma_f32_16x16x32_bf16 v[8:11], v[116:119], v[188:191], 0
	v_mfma_f32_16x16x32_bf16 v[4:7], v[140:143], v[188:191], 0
	v_mfma_f32_16x16x32_bf16 v[56:59], v[128:131], v[168:171], v[56:59]
	v_mfma_f32_16x16x32_bf16 v[52:55], v[148:151], v[168:171], v[52:55]
	v_mfma_f32_16x16x32_bf16 v[40:43], v[128:131], v[176:179], v[40:43]
	v_mfma_f32_16x16x32_bf16 v[36:39], v[148:151], v[176:179], v[36:39]
	v_mfma_f32_16x16x32_bf16 v[24:27], v[128:131], v[184:187], v[24:27]
	v_mfma_f32_16x16x32_bf16 v[20:23], v[148:151], v[184:187], v[20:23]
	v_mfma_f32_16x16x32_bf16 v[8:11], v[128:131], v[192:195], v[8:11]
	v_mfma_f32_16x16x32_bf16 v[4:7], v[148:151], v[192:195], v[4:7]
	s_barrier
	s_setprio 0
	s_add_i32 s10, 0, 0x18000
	s_add_i32 s11, 0, 0x1c000
	v_add_u32_e32 v112, s10, v242
	v_add_u32_e32 v148, s11, v242
	ds_read_b128 v[92:95], v112
	ds_read_b128 v[100:103], v112 offset:1024
	ds_read_b128 v[108:111], v112 offset:2048
	ds_read_b128 v[112:115], v112 offset:3072
	ds_read_b128 v[116:119], v148
	ds_read_b128 v[128:131], v148 offset:1024
	ds_read_b128 v[140:143], v148 offset:2048
	ds_read_b128 v[148:151], v148 offset:3072
	s_add_u32 s8, s44, 0x160000
	s_addc_u32 s9, s45, 0
	s_mov_b32 m0, s85
	v_lshl_add_u64 v[204:205], s[8:9], 0, v[0:1]
	ds_read_b128 v[160:163], v245 offset:32768
	ds_read_b128 v[168:171], v245 offset:33792
	ds_read_b128 v[172:175], v245 offset:34816
	ds_read_b128 v[176:179], v245 offset:35840
	ds_read_b128 v[180:183], v245 offset:36864
	ds_read_b128 v[184:187], v245 offset:37888
	ds_read_b128 v[188:191], v245 offset:38912
	ds_read_b128 v[192:195], v245 offset:39936
	global_load_lds_dwordx4 v[204:205], off
	v_lshl_add_u64 v[204:205], s[8:9], 0, v[216:217]
	s_mov_b32 m0, s87
	s_nop 0
	global_load_lds_dwordx4 v[204:205], off
	s_waitcnt vmcnt(8)
	s_waitcnt lgkmcnt(0)
	s_barrier
	s_setprio 1
	v_mfma_f32_16x16x32_bf16 v[164:167], v[92:95], v[160:163], v[164:167]
	v_mfma_f32_16x16x32_bf16 v[156:159], v[108:111], v[160:163], v[156:159]
	v_mfma_f32_16x16x32_bf16 v[136:139], v[92:95], v[172:175], v[136:139]
	v_mfma_f32_16x16x32_bf16 v[132:135], v[108:111], v[172:175], v[132:135]
	v_mfma_f32_16x16x32_bf16 v[104:107], v[92:95], v[180:183], v[104:107]
	v_mfma_f32_16x16x32_bf16 v[96:99], v[108:111], v[180:183], v[96:99]
	v_mfma_f32_16x16x32_bf16 v[80:83], v[92:95], v[188:191], v[80:83]
	v_mfma_f32_16x16x32_bf16 v[76:79], v[108:111], v[188:191], v[76:79]
	v_mfma_f32_16x16x32_bf16 v[164:167], v[100:103], v[168:171], v[164:167]
	v_mfma_f32_16x16x32_bf16 v[156:159], v[112:115], v[168:171], v[156:159]
	v_mfma_f32_16x16x32_bf16 v[136:139], v[100:103], v[176:179], v[136:139]
	v_mfma_f32_16x16x32_bf16 v[132:135], v[112:115], v[176:179], v[132:135]
	v_mfma_f32_16x16x32_bf16 v[104:107], v[100:103], v[184:187], v[104:107]
	v_mfma_f32_16x16x32_bf16 v[96:99], v[112:115], v[184:187], v[96:99]
	v_mfma_f32_16x16x32_bf16 v[80:83], v[100:103], v[192:195], v[80:83]
	v_mfma_f32_16x16x32_bf16 v[76:79], v[112:115], v[192:195], v[76:79]
	s_setprio 0
	s_setprio 1
	v_mfma_f32_16x16x32_bf16 v[152:155], v[116:119], v[160:163], v[152:155]
	v_mfma_f32_16x16x32_bf16 v[144:147], v[140:143], v[160:163], v[144:147]
	v_mfma_f32_16x16x32_bf16 v[124:127], v[116:119], v[172:175], v[124:127]
	v_mfma_f32_16x16x32_bf16 v[120:123], v[140:143], v[172:175], v[120:123]
	v_mfma_f32_16x16x32_bf16 v[88:91], v[116:119], v[180:183], v[88:91]
	v_mfma_f32_16x16x32_bf16 v[84:87], v[140:143], v[180:183], v[84:87]
	v_mfma_f32_16x16x32_bf16 v[72:75], v[116:119], v[188:191], v[72:75]
	v_mfma_f32_16x16x32_bf16 v[68:71], v[140:143], v[188:191], v[68:71]
	v_mfma_f32_16x16x32_bf16 v[152:155], v[128:131], v[168:171], v[152:155]
	v_mfma_f32_16x16x32_bf16 v[144:147], v[148:151], v[168:171], v[144:147]
	v_mfma_f32_16x16x32_bf16 v[124:127], v[128:131], v[176:179], v[124:127]
	v_mfma_f32_16x16x32_bf16 v[120:123], v[148:151], v[176:179], v[120:123]
	v_mfma_f32_16x16x32_bf16 v[88:91], v[128:131], v[184:187], v[88:91]
	v_mfma_f32_16x16x32_bf16 v[84:87], v[148:151], v[184:187], v[84:87]
	v_mfma_f32_16x16x32_bf16 v[72:75], v[128:131], v[192:195], v[72:75]
	v_mfma_f32_16x16x32_bf16 v[68:71], v[148:151], v[192:195], v[68:71]
	s_barrier
	s_setprio 0
	s_add_i32 s8, s10, s82
	v_lshl_add_u64 v[196:197], v[196:197], 0, s[68:69]
	s_mov_b32 m0, s8
	ds_read_b128 v[160:163], v245 offset:49152
	ds_read_b128 v[168:171], v245 offset:50176
	ds_read_b128 v[172:175], v245 offset:51200
	ds_read_b128 v[176:179], v245 offset:52224
	ds_read_b128 v[180:183], v245 offset:53248
	ds_read_b128 v[184:187], v245 offset:54272
	ds_read_b128 v[188:191], v245 offset:55296
	ds_read_b128 v[192:195], v245 offset:56320
	global_load_lds_dwordx4 v[196:197], off
	s_add_i32 m0, s8, 0x2000
	s_add_u32 s8, s42, 0x160080
	v_lshl_add_u64 v[196:197], v[198:199], 0, s[68:69]
	s_addc_u32 s9, s43, 0
	s_add_i32 s10, s11, s82
	global_load_lds_dwordx4 v[196:197], off
	v_lshl_add_u64 v[196:197], s[8:9], 0, v[2:3]
	s_mov_b32 m0, s10
	s_nop 0
	global_load_lds_dwordx4 v[196:197], off
	v_lshl_add_u64 v[196:197], s[8:9], 0, v[218:219]
	s_add_i32 m0, s10, 0x2000
	s_nop 0
	global_load_lds_dwordx4 v[196:197], off
	v_lshl_add_u64 v[196:197], v[200:201], 0, s[68:69]
	s_mov_b32 m0, s72
	s_nop 0
	global_load_lds_dwordx4 v[196:197], off
	v_lshl_add_u64 v[196:197], v[202:203], 0, s[68:69]
	s_mov_b32 m0, s88
	s_nop 0
	global_load_lds_dwordx4 v[196:197], off
	s_waitcnt vmcnt(8)
	s_waitcnt lgkmcnt(0)
	s_barrier
	s_setprio 1
	v_mfma_f32_16x16x32_bf16 v[64:67], v[92:95], v[160:163], v[64:67]
	v_mfma_f32_16x16x32_bf16 v[60:63], v[108:111], v[160:163], v[60:63]
	v_mfma_f32_16x16x32_bf16 v[48:51], v[92:95], v[172:175], v[48:51]
	v_mfma_f32_16x16x32_bf16 v[44:47], v[108:111], v[172:175], v[44:47]
	v_mfma_f32_16x16x32_bf16 v[32:35], v[92:95], v[180:183], v[32:35]
	v_mfma_f32_16x16x32_bf16 v[28:31], v[108:111], v[180:183], v[28:31]
	v_mfma_f32_16x16x32_bf16 v[16:19], v[92:95], v[188:191], v[16:19]
	v_mfma_f32_16x16x32_bf16 v[12:15], v[108:111], v[188:191], v[12:15]
	v_mfma_f32_16x16x32_bf16 v[64:67], v[100:103], v[168:171], v[64:67]
	v_mfma_f32_16x16x32_bf16 v[60:63], v[112:115], v[168:171], v[60:63]
	v_mfma_f32_16x16x32_bf16 v[48:51], v[100:103], v[176:179], v[48:51]
	v_mfma_f32_16x16x32_bf16 v[44:47], v[112:115], v[176:179], v[44:47]
	v_mfma_f32_16x16x32_bf16 v[32:35], v[100:103], v[184:187], v[32:35]
	v_mfma_f32_16x16x32_bf16 v[28:31], v[112:115], v[184:187], v[28:31]
	v_mfma_f32_16x16x32_bf16 v[16:19], v[100:103], v[192:195], v[16:19]
	v_mfma_f32_16x16x32_bf16 v[12:15], v[112:115], v[192:195], v[12:15]
	s_setprio 0
	s_setprio 1
	v_mfma_f32_16x16x32_bf16 v[56:59], v[116:119], v[160:163], v[56:59]
	v_mfma_f32_16x16x32_bf16 v[52:55], v[140:143], v[160:163], v[52:55]
	v_mfma_f32_16x16x32_bf16 v[40:43], v[116:119], v[172:175], v[40:43]
	v_mfma_f32_16x16x32_bf16 v[36:39], v[140:143], v[172:175], v[36:39]
	v_mfma_f32_16x16x32_bf16 v[24:27], v[116:119], v[180:183], v[24:27]
	v_mfma_f32_16x16x32_bf16 v[20:23], v[140:143], v[180:183], v[20:23]
	v_mfma_f32_16x16x32_bf16 v[8:11], v[116:119], v[188:191], v[8:11]
	v_mfma_f32_16x16x32_bf16 v[4:7], v[140:143], v[188:191], v[4:7]
	v_mfma_f32_16x16x32_bf16 v[56:59], v[128:131], v[168:171], v[56:59]
	v_mfma_f32_16x16x32_bf16 v[52:55], v[148:151], v[168:171], v[52:55]
	v_mfma_f32_16x16x32_bf16 v[40:43], v[128:131], v[176:179], v[40:43]
	v_mfma_f32_16x16x32_bf16 v[36:39], v[148:151], v[176:179], v[36:39]
	v_mfma_f32_16x16x32_bf16 v[24:27], v[128:131], v[184:187], v[24:27]
	v_mfma_f32_16x16x32_bf16 v[20:23], v[148:151], v[184:187], v[20:23]
	v_mfma_f32_16x16x32_bf16 v[8:11], v[128:131], v[192:195], v[8:11]
	v_mfma_f32_16x16x32_bf16 v[4:7], v[148:151], v[192:195], v[4:7]
	s_barrier
	s_setprio 0
	s_add_i32 s7, s7, 2
	s_add_u32 s5, s5, 0x100
	s_addc_u32 s6, s6, 0
	s_cmpk_gt_u32 s7, 0x55
	s_mov_b64 s[38:39], s[40:41]
.LBB0_1134:
	s_add_u32 s40, s38, 0x100
	s_addc_u32 s41, s39, 0
	s_add_i32 s8, 0, 0x10000
	s_cmpk_eq_i32 s7, 0x54
	s_cselect_b32 s45, s61, s41
	s_cselect_b32 s44, s60, s40
	s_cselect_b32 s43, s63, s6
	s_cselect_b32 s42, s62, s5
	s_add_i32 s10, 0, 0x14000
	v_add_u32_e32 v112, s8, v242
	v_add_u32_e32 v148, s10, v242
	ds_read_b128 v[92:95], v112
	ds_read_b128 v[100:103], v112 offset:1024
	ds_read_b128 v[108:111], v112 offset:2048
	ds_read_b128 v[112:115], v112 offset:3072
	ds_read_b128 v[116:119], v148
	ds_read_b128 v[128:131], v148 offset:1024
	ds_read_b128 v[140:143], v148 offset:2048
	ds_read_b128 v[148:151], v148 offset:3072
	v_lshl_add_u64 v[196:197], s[38:39], 0, v[222:223]
	s_add_i32 m0, s83, 0xc000
	ds_read_b128 v[160:163], v245
	ds_read_b128 v[168:171], v245 offset:1024
	ds_read_b128 v[172:175], v245 offset:2048
	ds_read_b128 v[176:179], v245 offset:3072
	ds_read_b128 v[180:183], v245 offset:4096
	ds_read_b128 v[184:187], v245 offset:5120
	ds_read_b128 v[188:191], v245 offset:6144
	ds_read_b128 v[192:195], v245 offset:7168
	global_load_lds_dwordx4 v[196:197], off
	v_lshl_add_u64 v[196:197], s[38:39], 0, v[220:221]
	s_add_i32 m0, s83, 0xe000
	s_nop 0
	global_load_lds_dwordx4 v[196:197], off
	s_waitcnt vmcnt(8)
	s_waitcnt lgkmcnt(0)
	s_barrier
	s_setprio 1
	v_mfma_f32_16x16x32_bf16 v[164:167], v[92:95], v[160:163], v[164:167]
	v_mfma_f32_16x16x32_bf16 v[156:159], v[108:111], v[160:163], v[156:159]
	v_mfma_f32_16x16x32_bf16 v[136:139], v[92:95], v[172:175], v[136:139]
	v_mfma_f32_16x16x32_bf16 v[132:135], v[108:111], v[172:175], v[132:135]
	v_mfma_f32_16x16x32_bf16 v[104:107], v[92:95], v[180:183], v[104:107]
	v_mfma_f32_16x16x32_bf16 v[96:99], v[108:111], v[180:183], v[96:99]
	v_mfma_f32_16x16x32_bf16 v[80:83], v[92:95], v[188:191], v[80:83]
	v_mfma_f32_16x16x32_bf16 v[76:79], v[108:111], v[188:191], v[76:79]
	v_mfma_f32_16x16x32_bf16 v[164:167], v[100:103], v[168:171], v[164:167]
	v_mfma_f32_16x16x32_bf16 v[156:159], v[112:115], v[168:171], v[156:159]
	v_mfma_f32_16x16x32_bf16 v[136:139], v[100:103], v[176:179], v[136:139]
	v_mfma_f32_16x16x32_bf16 v[132:135], v[112:115], v[176:179], v[132:135]
	v_mfma_f32_16x16x32_bf16 v[104:107], v[100:103], v[184:187], v[104:107]
	v_mfma_f32_16x16x32_bf16 v[96:99], v[112:115], v[184:187], v[96:99]
	v_mfma_f32_16x16x32_bf16 v[80:83], v[100:103], v[192:195], v[80:83]
	v_mfma_f32_16x16x32_bf16 v[76:79], v[112:115], v[192:195], v[76:79]
	s_setprio 0
	s_setprio 1
	v_mfma_f32_16x16x32_bf16 v[152:155], v[116:119], v[160:163], v[152:155]
	v_mfma_f32_16x16x32_bf16 v[144:147], v[140:143], v[160:163], v[144:147]
	v_mfma_f32_16x16x32_bf16 v[124:127], v[116:119], v[172:175], v[124:127]
	v_mfma_f32_16x16x32_bf16 v[120:123], v[140:143], v[172:175], v[120:123]
	v_mfma_f32_16x16x32_bf16 v[88:91], v[116:119], v[180:183], v[88:91]
	v_mfma_f32_16x16x32_bf16 v[84:87], v[140:143], v[180:183], v[84:87]
	v_mfma_f32_16x16x32_bf16 v[72:75], v[116:119], v[188:191], v[72:75]
	v_mfma_f32_16x16x32_bf16 v[68:71], v[140:143], v[188:191], v[68:71]
	v_mfma_f32_16x16x32_bf16 v[152:155], v[128:131], v[168:171], v[152:155]
	v_mfma_f32_16x16x32_bf16 v[144:147], v[148:151], v[168:171], v[144:147]
	v_mfma_f32_16x16x32_bf16 v[124:127], v[128:131], v[176:179], v[124:127]
	v_mfma_f32_16x16x32_bf16 v[120:123], v[148:151], v[176:179], v[120:123]
	v_mfma_f32_16x16x32_bf16 v[88:91], v[128:131], v[184:187], v[88:91]
	v_mfma_f32_16x16x32_bf16 v[84:87], v[148:151], v[184:187], v[84:87]
	v_mfma_f32_16x16x32_bf16 v[72:75], v[128:131], v[192:195], v[72:75]
	v_mfma_f32_16x16x32_bf16 v[68:71], v[148:151], v[192:195], v[68:71]
	s_barrier
	s_setprio 0
	s_add_i32 s8, s8, s82
	v_lshl_add_u64 v[196:197], s[42:43], 0, v[2:3]
	s_mov_b32 m0, s8
	ds_read_b128 v[160:163], v245 offset:16384
	ds_read_b128 v[168:171], v245 offset:17408
	ds_read_b128 v[172:175], v245 offset:18432
	ds_read_b128 v[176:179], v245 offset:19456
	ds_read_b128 v[180:183], v245 offset:20480
	ds_read_b128 v[184:187], v245 offset:21504
	ds_read_b128 v[188:191], v245 offset:22528
	ds_read_b128 v[192:195], v245 offset:23552
	global_load_lds_dwordx4 v[196:197], off
	s_add_i32 m0, s8, 0x2000
	s_add_u32 s8, s42, 0x160000
	v_lshl_add_u64 v[198:199], s[42:43], 0, v[218:219]
	s_addc_u32 s9, s43, 0
	s_add_i32 s10, s10, s82
	global_load_lds_dwordx4 v[198:199], off
	v_lshl_add_u64 v[200:201], s[8:9], 0, v[2:3]
	s_mov_b32 m0, s10
	v_lshl_add_u64 v[202:203], s[44:45], 0, v[216:217]
	global_load_lds_dwordx4 v[200:201], off
	v_lshl_add_u64 v[200:201], s[8:9], 0, v[218:219]
	s_add_i32 m0, s10, 0x2000
	s_nop 0
	global_load_lds_dwordx4 v[200:201], off
	v_lshl_add_u64 v[200:201], s[44:45], 0, v[0:1]
	s_mov_b32 m0, s83
	s_nop 0
	global_load_lds_dwordx4 v[200:201], off
	s_mov_b32 m0, s84
	s_nop 0
	global_load_lds_dwordx4 v[202:203], off
	s_waitcnt vmcnt(8)
	s_waitcnt lgkmcnt(0)
	s_barrier
	s_setprio 1
	v_mfma_f32_16x16x32_bf16 v[64:67], v[92:95], v[160:163], v[64:67]
	v_mfma_f32_16x16x32_bf16 v[60:63], v[108:111], v[160:163], v[60:63]
	v_mfma_f32_16x16x32_bf16 v[48:51], v[92:95], v[172:175], v[48:51]
	v_mfma_f32_16x16x32_bf16 v[44:47], v[108:111], v[172:175], v[44:47]
	v_mfma_f32_16x16x32_bf16 v[32:35], v[92:95], v[180:183], v[32:35]
	v_mfma_f32_16x16x32_bf16 v[28:31], v[108:111], v[180:183], v[28:31]
	v_mfma_f32_16x16x32_bf16 v[16:19], v[92:95], v[188:191], v[16:19]
	v_mfma_f32_16x16x32_bf16 v[12:15], v[108:111], v[188:191], v[12:15]
	v_mfma_f32_16x16x32_bf16 v[64:67], v[100:103], v[168:171], v[64:67]
	v_mfma_f32_16x16x32_bf16 v[60:63], v[112:115], v[168:171], v[60:63]
	v_mfma_f32_16x16x32_bf16 v[48:51], v[100:103], v[176:179], v[48:51]
	v_mfma_f32_16x16x32_bf16 v[44:47], v[112:115], v[176:179], v[44:47]
	v_mfma_f32_16x16x32_bf16 v[32:35], v[100:103], v[184:187], v[32:35]
	v_mfma_f32_16x16x32_bf16 v[28:31], v[112:115], v[184:187], v[28:31]
	v_mfma_f32_16x16x32_bf16 v[16:19], v[100:103], v[192:195], v[16:19]
	v_mfma_f32_16x16x32_bf16 v[12:15], v[112:115], v[192:195], v[12:15]
	s_setprio 0
	s_setprio 1
	v_mfma_f32_16x16x32_bf16 v[56:59], v[116:119], v[160:163], v[56:59]
	v_mfma_f32_16x16x32_bf16 v[52:55], v[140:143], v[160:163], v[52:55]
	v_mfma_f32_16x16x32_bf16 v[40:43], v[116:119], v[172:175], v[40:43]
	v_mfma_f32_16x16x32_bf16 v[36:39], v[140:143], v[172:175], v[36:39]
	v_mfma_f32_16x16x32_bf16 v[24:27], v[116:119], v[180:183], v[24:27]
	v_mfma_f32_16x16x32_bf16 v[20:23], v[140:143], v[180:183], v[20:23]
	v_mfma_f32_16x16x32_bf16 v[8:11], v[116:119], v[188:191], v[8:11]
	v_mfma_f32_16x16x32_bf16 v[4:7], v[140:143], v[188:191], v[4:7]
	v_mfma_f32_16x16x32_bf16 v[56:59], v[128:131], v[168:171], v[56:59]
	v_mfma_f32_16x16x32_bf16 v[52:55], v[148:151], v[168:171], v[52:55]
	v_mfma_f32_16x16x32_bf16 v[40:43], v[128:131], v[176:179], v[40:43]
	v_mfma_f32_16x16x32_bf16 v[36:39], v[148:151], v[176:179], v[36:39]
	v_mfma_f32_16x16x32_bf16 v[24:27], v[128:131], v[184:187], v[24:27]
	v_mfma_f32_16x16x32_bf16 v[20:23], v[148:151], v[184:187], v[20:23]
	v_mfma_f32_16x16x32_bf16 v[8:11], v[128:131], v[192:195], v[8:11]
	v_mfma_f32_16x16x32_bf16 v[4:7], v[148:151], v[192:195], v[4:7]
	s_barrier
	s_setprio 0
	s_add_i32 s10, 0, 0x18000
	s_add_i32 s11, 0, 0x1c000
	v_add_u32_e32 v112, s10, v242
	v_add_u32_e32 v148, s11, v242
	ds_read_b128 v[92:95], v112
	ds_read_b128 v[100:103], v112 offset:1024
	ds_read_b128 v[108:111], v112 offset:2048
	ds_read_b128 v[112:115], v112 offset:3072
	ds_read_b128 v[116:119], v148
	ds_read_b128 v[128:131], v148 offset:1024
	ds_read_b128 v[140:143], v148 offset:2048
	ds_read_b128 v[148:151], v148 offset:3072
	s_add_u32 s8, s44, 0x160000
	s_addc_u32 s9, s45, 0
	s_mov_b32 m0, s85
	v_lshl_add_u64 v[204:205], s[8:9], 0, v[0:1]
	ds_read_b128 v[160:163], v245 offset:32768
	ds_read_b128 v[168:171], v245 offset:33792
	ds_read_b128 v[172:175], v245 offset:34816
	ds_read_b128 v[176:179], v245 offset:35840
	ds_read_b128 v[180:183], v245 offset:36864
	ds_read_b128 v[184:187], v245 offset:37888
	ds_read_b128 v[188:191], v245 offset:38912
	ds_read_b128 v[192:195], v245 offset:39936
	global_load_lds_dwordx4 v[204:205], off
	v_lshl_add_u64 v[204:205], s[8:9], 0, v[216:217]
	s_mov_b32 m0, s87
	s_nop 0
	global_load_lds_dwordx4 v[204:205], off
	s_waitcnt vmcnt(8)
	s_waitcnt lgkmcnt(0)
	s_barrier
	s_setprio 1
	v_mfma_f32_16x16x32_bf16 v[164:167], v[92:95], v[160:163], v[164:167]
	v_mfma_f32_16x16x32_bf16 v[156:159], v[108:111], v[160:163], v[156:159]
	v_mfma_f32_16x16x32_bf16 v[136:139], v[92:95], v[172:175], v[136:139]
	v_mfma_f32_16x16x32_bf16 v[132:135], v[108:111], v[172:175], v[132:135]
	v_mfma_f32_16x16x32_bf16 v[104:107], v[92:95], v[180:183], v[104:107]
	v_mfma_f32_16x16x32_bf16 v[96:99], v[108:111], v[180:183], v[96:99]
	v_mfma_f32_16x16x32_bf16 v[80:83], v[92:95], v[188:191], v[80:83]
	v_mfma_f32_16x16x32_bf16 v[76:79], v[108:111], v[188:191], v[76:79]
	v_mfma_f32_16x16x32_bf16 v[164:167], v[100:103], v[168:171], v[164:167]
	v_mfma_f32_16x16x32_bf16 v[156:159], v[112:115], v[168:171], v[156:159]
	v_mfma_f32_16x16x32_bf16 v[136:139], v[100:103], v[176:179], v[136:139]
	v_mfma_f32_16x16x32_bf16 v[132:135], v[112:115], v[176:179], v[132:135]
	v_mfma_f32_16x16x32_bf16 v[104:107], v[100:103], v[184:187], v[104:107]
	v_mfma_f32_16x16x32_bf16 v[96:99], v[112:115], v[184:187], v[96:99]
	v_mfma_f32_16x16x32_bf16 v[80:83], v[100:103], v[192:195], v[80:83]
	v_mfma_f32_16x16x32_bf16 v[76:79], v[112:115], v[192:195], v[76:79]
	s_setprio 0
	s_setprio 1
	v_mfma_f32_16x16x32_bf16 v[152:155], v[116:119], v[160:163], v[152:155]
	v_mfma_f32_16x16x32_bf16 v[144:147], v[140:143], v[160:163], v[144:147]
	v_mfma_f32_16x16x32_bf16 v[124:127], v[116:119], v[172:175], v[124:127]
	v_mfma_f32_16x16x32_bf16 v[120:123], v[140:143], v[172:175], v[120:123]
	v_mfma_f32_16x16x32_bf16 v[88:91], v[116:119], v[180:183], v[88:91]
	v_mfma_f32_16x16x32_bf16 v[84:87], v[140:143], v[180:183], v[84:87]
	v_mfma_f32_16x16x32_bf16 v[72:75], v[116:119], v[188:191], v[72:75]
	v_mfma_f32_16x16x32_bf16 v[68:71], v[140:143], v[188:191], v[68:71]
	v_mfma_f32_16x16x32_bf16 v[152:155], v[128:131], v[168:171], v[152:155]
	v_mfma_f32_16x16x32_bf16 v[144:147], v[148:151], v[168:171], v[144:147]
	v_mfma_f32_16x16x32_bf16 v[124:127], v[128:131], v[176:179], v[124:127]
	v_mfma_f32_16x16x32_bf16 v[120:123], v[148:151], v[176:179], v[120:123]
	v_mfma_f32_16x16x32_bf16 v[88:91], v[128:131], v[184:187], v[88:91]
	v_mfma_f32_16x16x32_bf16 v[84:87], v[148:151], v[184:187], v[84:87]
	v_mfma_f32_16x16x32_bf16 v[72:75], v[128:131], v[192:195], v[72:75]
	v_mfma_f32_16x16x32_bf16 v[68:71], v[148:151], v[192:195], v[68:71]
	s_barrier
	s_setprio 0
	s_add_i32 s8, s10, s82
	v_lshl_add_u64 v[196:197], v[196:197], 0, s[68:69]
	s_mov_b32 m0, s8
	ds_read_b128 v[160:163], v245 offset:49152
	ds_read_b128 v[168:171], v245 offset:50176
	ds_read_b128 v[172:175], v245 offset:51200
	ds_read_b128 v[176:179], v245 offset:52224
	ds_read_b128 v[180:183], v245 offset:53248
	ds_read_b128 v[184:187], v245 offset:54272
	ds_read_b128 v[188:191], v245 offset:55296
	ds_read_b128 v[192:195], v245 offset:56320
	global_load_lds_dwordx4 v[196:197], off
	s_add_i32 m0, s8, 0x2000
	s_add_u32 s8, s42, 0x160080
	v_lshl_add_u64 v[196:197], v[198:199], 0, s[68:69]
	s_addc_u32 s9, s43, 0
	s_add_i32 s10, s11, s82
	global_load_lds_dwordx4 v[196:197], off
	v_lshl_add_u64 v[196:197], s[8:9], 0, v[2:3]
	s_mov_b32 m0, s10
	s_nop 0
	global_load_lds_dwordx4 v[196:197], off
	v_lshl_add_u64 v[196:197], s[8:9], 0, v[218:219]
	s_add_i32 m0, s10, 0x2000
	s_nop 0
	global_load_lds_dwordx4 v[196:197], off
	v_lshl_add_u64 v[196:197], v[200:201], 0, s[68:69]
	s_mov_b32 m0, s72
	s_nop 0
	global_load_lds_dwordx4 v[196:197], off
	v_lshl_add_u64 v[196:197], v[202:203], 0, s[68:69]
	s_mov_b32 m0, s88
	s_nop 0
	global_load_lds_dwordx4 v[196:197], off
	s_waitcnt vmcnt(8)
	s_waitcnt lgkmcnt(0)
	s_barrier
	s_setprio 1
	v_mfma_f32_16x16x32_bf16 v[64:67], v[92:95], v[160:163], v[64:67]
	v_mfma_f32_16x16x32_bf16 v[60:63], v[108:111], v[160:163], v[60:63]
	v_mfma_f32_16x16x32_bf16 v[48:51], v[92:95], v[172:175], v[48:51]
	v_mfma_f32_16x16x32_bf16 v[44:47], v[108:111], v[172:175], v[44:47]
	v_mfma_f32_16x16x32_bf16 v[32:35], v[92:95], v[180:183], v[32:35]
	v_mfma_f32_16x16x32_bf16 v[28:31], v[108:111], v[180:183], v[28:31]
	v_mfma_f32_16x16x32_bf16 v[16:19], v[92:95], v[188:191], v[16:19]
	v_mfma_f32_16x16x32_bf16 v[12:15], v[108:111], v[188:191], v[12:15]
	v_mfma_f32_16x16x32_bf16 v[64:67], v[100:103], v[168:171], v[64:67]
	v_mfma_f32_16x16x32_bf16 v[60:63], v[112:115], v[168:171], v[60:63]
	v_mfma_f32_16x16x32_bf16 v[48:51], v[100:103], v[176:179], v[48:51]
	v_mfma_f32_16x16x32_bf16 v[44:47], v[112:115], v[176:179], v[44:47]
	v_mfma_f32_16x16x32_bf16 v[32:35], v[100:103], v[184:187], v[32:35]
	v_mfma_f32_16x16x32_bf16 v[28:31], v[112:115], v[184:187], v[28:31]
	v_mfma_f32_16x16x32_bf16 v[16:19], v[100:103], v[192:195], v[16:19]
	v_mfma_f32_16x16x32_bf16 v[12:15], v[112:115], v[192:195], v[12:15]
	s_setprio 0
	s_setprio 1
	v_mfma_f32_16x16x32_bf16 v[56:59], v[116:119], v[160:163], v[56:59]
	v_mfma_f32_16x16x32_bf16 v[52:55], v[140:143], v[160:163], v[52:55]
	v_mfma_f32_16x16x32_bf16 v[40:43], v[116:119], v[172:175], v[40:43]
	v_mfma_f32_16x16x32_bf16 v[36:39], v[140:143], v[172:175], v[36:39]
	v_mfma_f32_16x16x32_bf16 v[24:27], v[116:119], v[180:183], v[24:27]
	v_mfma_f32_16x16x32_bf16 v[20:23], v[140:143], v[180:183], v[20:23]
	v_mfma_f32_16x16x32_bf16 v[8:11], v[116:119], v[188:191], v[8:11]
	v_mfma_f32_16x16x32_bf16 v[4:7], v[140:143], v[188:191], v[4:7]
	v_mfma_f32_16x16x32_bf16 v[56:59], v[128:131], v[168:171], v[56:59]
	v_mfma_f32_16x16x32_bf16 v[52:55], v[148:151], v[168:171], v[52:55]
	v_mfma_f32_16x16x32_bf16 v[40:43], v[128:131], v[176:179], v[40:43]
	v_mfma_f32_16x16x32_bf16 v[36:39], v[148:151], v[176:179], v[36:39]
	v_mfma_f32_16x16x32_bf16 v[24:27], v[128:131], v[184:187], v[24:27]
	v_mfma_f32_16x16x32_bf16 v[20:23], v[148:151], v[184:187], v[20:23]
	v_mfma_f32_16x16x32_bf16 v[8:11], v[128:131], v[192:195], v[8:11]
	v_mfma_f32_16x16x32_bf16 v[4:7], v[148:151], v[192:195], v[4:7]
	s_barrier
	s_setprio 0
	s_add_i32 s7, s7, 2
	s_add_u32 s5, s5, 0x100
	s_addc_u32 s6, s6, 0
	s_cmpk_gt_u32 s7, 0x55
	s_mov_b64 s[38:39], s[40:41]
	s_cbranch_scc0 .LBB0_1134
	s_and_b64 vcc, exec, s[52:53]
	s_cbranch_vccz .LBB0_1137
	s_barrier
